# v14: v13 + norm1/norm2 coefficient-table build: 11 loads issued ahead of the row loads, one counted wait (was a 5-trip loop with 10 vmcnt(0) round trips)
# speedup vs baseline: 1.0056x; 1.0056x over previous
; #define GAS __attribute__((address_space(1)))
; #define LAS __attribute__((address_space(3)))
; #define NR_LOAD(dst, k_) do { const GAS v2u* xr_ = (const GAS v2u*)(X + (size_t)(nw + 2048 * (k_)) * D) + F.lane; \
;         _Pragma("unroll") for (int j = 0; j < 8; ++j) dst[j] = __builtin_nontemporal_load(xr_ + 64 * j); } while (0)
; __device__ __forceinline__ void norm_mod_phase2(const Args& a, Frame& F, const float* gain, const float* modl, int sh_off, int sc_off, int nrows, const float* slab_gate) {
;     ...
;     v2u r0[8], r1[8], r2[8], r3[8], r4[8], r5[8], r6[8], r7[8];
;     ...
;     NR_LOAD(r0, 0); NR_LOAD(r1, 1); NR_LOAD(r2, 2); NR_LOAD(r3, 3); NR_LOAD(r4, 4); NR_LOAD(r5, 5); NR_LOAD(r6, 6); NR_LOAD(r7, 7);
;     { const GAS f32x4* g4 = (const GAS f32x4*)gain;
;       for (int q = F.tid; q < 5 * D / 4; q += NWAVES * 64) { const int bq = q >> 9, cq = q & 511; const GAS f32x4* mb4 = (const GAS f32x4*)(modl + (size_t)bq * MOD_LD);
;           ((LAS f32x4*)CA)[q] = g4[cq] * (mb4[sc_off / 4 + cq] + 1.0f); ((LAS f32x4*)CB)[q] = mb4[sh_off / 4 + cq]; } }
.LBB0_215:
	s_andn2_b64 vcc, exec, s[4:5]
	s_cbranch_vccnz .LBB0_224
	s_getreg_b32 s4, hwreg(HW_REG_HW_ID, 0, 6)
	s_lshl_b32 s4, s4, 2
	s_add_i32 s4, s4, 0
	s_add_i32 s4, s4, 0x20540
	v_mov_b32_e32 v0, s4
	ds_read_b32 v0, v0
	v_mov_b64_e32 v[2:3], s[0:1]
	v_mbcnt_lo_u32_b32 v4, -1, 0
	v_mbcnt_hi_u32_b32 v4, -1, v4
	s_mov_b64 s[20:21], 0x400000
	v_mov_b32_e32 v7, v1
	s_waitcnt lgkmcnt(0)
	v_readfirstlane_b32 s4, v0
	s_nop 1
	v_lshl_add_u32 v142, s4, 6, v4
	v_mov_b32_e32 v128, s72
	v_mov_b32_e32 v129, s73
	v_readfirstlane_b32 s4, v142
	s_ashr_i32 s4, s4, 6
	s_add_i32 s4, s4, s91
	s_ashr_i32 s5, s4, 31
	s_add_i32 s36, s4, 0x800
	s_add_i32 s30, s4, 0x1000
	s_add_i32 s26, s4, 0x1800
	s_add_i32 s22, s4, 0x2000
	s_add_i32 s18, s4, 0x2800
	v_and_b32_e32 v143, 63, v142
	s_lshl_b64 s[6:7], s[4:5], 12
	s_ashr_i32 s37, s36, 31
	s_ashr_i32 s31, s30, 31
	s_ashr_i32 s27, s26, 31
	s_ashr_i32 s23, s22, 31
	s_ashr_i32 s19, s18, 31
	v_lshlrev_b32_e32 v6, 3, v143
	s_lshl_b64 s[8:9], s[36:37], 12
	s_lshl_b64 s[10:11], s[30:31], 12
	s_lshl_b64 s[12:13], s[26:27], 12
	s_lshl_b64 s[14:15], s[22:23], 12
	s_lshl_b64 s[16:17], s[18:19], 12
	s_waitcnt vmcnt(0) lgkmcnt(0)
	v_lshl_add_u64 v[8:9], v[128:129], 0, s[20:21]
	v_lshl_add_u64 v[2:3], v[8:9], 0, s[6:7]
	v_lshl_add_u64 v[4:5], v[8:9], 0, s[8:9]
	v_lshl_add_u64 v[10:11], v[8:9], 0, s[10:11]
	v_lshl_add_u64 v[12:13], v[8:9], 0, s[12:13]
	v_lshl_add_u64 v[14:15], v[8:9], 0, s[14:15]
	v_lshl_add_u64 v[16:17], v[8:9], 0, s[16:17]
	v_lshl_add_u64 v[2:3], v[2:3], 0, v[6:7]
	v_lshl_add_u64 v[4:5], v[4:5], 0, v[6:7]
	v_lshl_add_u64 v[10:11], v[10:11], 0, v[6:7]
	v_lshl_add_u64 v[12:13], v[12:13], 0, v[6:7]
	v_lshl_add_u64 v[14:15], v[14:15], 0, v[6:7]
	v_lshl_add_u64 v[16:17], v[16:17], 0, v[6:7]
	v_and_b32_e32 v184, 0x1ff, v142
	v_lshlrev_b32_e32 v184, 4, v184
	v_mov_b32_e32 v185, 0
	v_mov_b32_e32 v186, s76
	v_lshlrev_b32_e32 v186, 13, v186
	v_mov_b32_e32 v187, 0
	v_lshl_add_u64 v[188:189], v[74:75], 0, v[186:187]
	v_lshl_add_u64 v[188:189], v[188:189], 0, v[184:185]
	global_load_dwordx4 v[192:195], v[188:189], off
	v_add_u32_e32 v196, 0x2000, v184
	v_mov_b32_e32 v201, v184
	v_add_u32_e32 v197, 0xe000, v184
	v_add_u32_e32 v202, 0xc000, v184
	v_add_u32_e32 v198, 0x1a000, v184
	v_add_u32_e32 v203, 0x18000, v184
	v_add_u32_e32 v199, 0x26000, v184
	v_add_u32_e32 v204, 0x24000, v184
	v_add_u32_e32 v200, 0x32000, v184
	v_add_u32_e32 v205, 0x30000, v184
	global_load_dwordx4 v[208:211], v196, s[86:87]
	global_load_dwordx4 v[228:231], v201, s[86:87]
	global_load_dwordx4 v[212:215], v197, s[86:87]
	global_load_dwordx4 v[232:235], v202, s[86:87]
	global_load_dwordx4 v[216:219], v198, s[86:87]
	global_load_dwordx4 v[236:239], v203, s[86:87]
	global_load_dwordx4 v[220:223], v199, s[86:87]
	global_load_dwordx4 v[240:243], v204, s[86:87]
	global_load_dwordx4 v[224:227], v200, s[86:87]
	global_load_dwordx4 v[244:247], v205, s[86:87]
	global_load_dwordx2 v[140:141], v[2:3], off nt
	global_load_dwordx2 v[138:139], v[2:3], off offset:512 nt
	global_load_dwordx2 v[136:137], v[2:3], off offset:1024 nt
	global_load_dwordx2 v[132:133], v[2:3], off offset:1536 nt
	global_load_dwordx2 v[134:135], v[2:3], off offset:2048 nt
	global_load_dwordx2 v[124:125], v[2:3], off offset:2560 nt
	global_load_dwordx2 v[126:127], v[2:3], off offset:3072 nt
	global_load_dwordx2 v[130:131], v[2:3], off offset:3584 nt
	global_load_dwordx2 v[122:123], v[4:5], off nt
	global_load_dwordx2 v[120:121], v[4:5], off offset:512 nt
	global_load_dwordx2 v[118:119], v[4:5], off offset:1024 nt
	global_load_dwordx2 v[116:117], v[4:5], off offset:1536 nt
	global_load_dwordx2 v[114:115], v[4:5], off offset:2048 nt
	global_load_dwordx2 v[112:113], v[4:5], off offset:2560 nt
	global_load_dwordx2 v[110:111], v[4:5], off offset:3072 nt
	global_load_dwordx2 v[108:109], v[4:5], off offset:3584 nt
	global_load_dwordx2 v[106:107], v[10:11], off nt
	global_load_dwordx2 v[104:105], v[10:11], off offset:512 nt
	global_load_dwordx2 v[102:103], v[10:11], off offset:1024 nt
	global_load_dwordx2 v[100:101], v[10:11], off offset:1536 nt
	global_load_dwordx2 v[98:99], v[10:11], off offset:2048 nt
	global_load_dwordx2 v[96:97], v[10:11], off offset:2560 nt
	global_load_dwordx2 v[94:95], v[10:11], off offset:3072 nt
	global_load_dwordx2 v[92:93], v[10:11], off offset:3584 nt
	global_load_dwordx2 v[90:91], v[12:13], off nt
	global_load_dwordx2 v[88:89], v[12:13], off offset:512 nt
	global_load_dwordx2 v[86:87], v[12:13], off offset:1024 nt
	global_load_dwordx2 v[84:85], v[12:13], off offset:1536 nt
	global_load_dwordx2 v[82:83], v[12:13], off offset:2048 nt
	global_load_dwordx2 v[80:81], v[12:13], off offset:2560 nt
	global_load_dwordx2 v[78:79], v[12:13], off offset:3072 nt
	global_load_dwordx2 v[76:77], v[12:13], off offset:3584 nt
	global_load_dwordx2 v[72:73], v[14:15], off nt
	global_load_dwordx2 v[70:71], v[14:15], off offset:512 nt
	global_load_dwordx2 v[68:69], v[14:15], off offset:1024 nt
	global_load_dwordx2 v[66:67], v[14:15], off offset:1536 nt
	global_load_dwordx2 v[64:65], v[14:15], off offset:2048 nt
	global_load_dwordx2 v[62:63], v[14:15], off offset:2560 nt
	global_load_dwordx2 v[60:61], v[14:15], off offset:3072 nt
	global_load_dwordx2 v[58:59], v[14:15], off offset:3584 nt
	global_load_dwordx2 v[56:57], v[16:17], off nt
	global_load_dwordx2 v[54:55], v[16:17], off offset:512 nt
	global_load_dwordx2 v[52:53], v[16:17], off offset:1024 nt
	global_load_dwordx2 v[50:51], v[16:17], off offset:1536 nt
	global_load_dwordx2 v[48:49], v[16:17], off offset:2048 nt
	global_load_dwordx2 v[46:47], v[16:17], off offset:2560 nt
	global_load_dwordx2 v[44:45], v[16:17], off offset:3072 nt
	global_load_dwordx2 v[42:43], v[16:17], off offset:3584 nt
	s_add_i32 s14, s4, 0x3000
	s_ashr_i32 s15, s14, 31
	s_lshl_b64 s[6:7], s[14:15], 12
	s_add_i32 s10, s4, 0x3800
	v_lshl_add_u64 v[2:3], v[8:9], 0, s[6:7]
	s_ashr_i32 s11, s10, 31
	v_lshl_add_u64 v[2:3], v[2:3], 0, v[6:7]
	s_lshl_b64 s[6:7], s[10:11], 12
	global_load_dwordx2 v[40:41], v[2:3], off nt
	global_load_dwordx2 v[38:39], v[2:3], off offset:512 nt
	global_load_dwordx2 v[36:37], v[2:3], off offset:1024 nt
	global_load_dwordx2 v[34:35], v[2:3], off offset:1536 nt
	global_load_dwordx2 v[32:33], v[2:3], off offset:2048 nt
	global_load_dwordx2 v[30:31], v[2:3], off offset:2560 nt
	global_load_dwordx2 v[28:29], v[2:3], off offset:3072 nt
	global_load_dwordx2 v[26:27], v[2:3], off offset:3584 nt
	v_lshl_add_u64 v[2:3], v[8:9], 0, s[6:7]
	v_lshl_add_u64 v[2:3], v[2:3], 0, v[6:7]
	global_load_dwordx2 v[24:25], v[2:3], off nt
	global_load_dwordx2 v[22:23], v[2:3], off offset:512 nt
	global_load_dwordx2 v[20:21], v[2:3], off offset:1024 nt
	global_load_dwordx2 v[18:19], v[2:3], off offset:1536 nt
	global_load_dwordx2 v[16:17], v[2:3], off offset:2048 nt
	global_load_dwordx2 v[14:15], v[2:3], off offset:2560 nt
	global_load_dwordx2 v[12:13], v[2:3], off offset:3072 nt
	global_load_dwordx2 v[10:11], v[2:3], off offset:3584 nt
	s_waitcnt vmcnt(62)
; #define GAS __attribute__((address_space(1)))
; #define LAS __attribute__((address_space(3)))
; __device__ __forceinline__ void norm_mod_phase2(const Args& a, Frame& F, const float* gain, const float* modl, int sh_off, int sc_off, int nrows, const float* slab_gate) {
;     ...
;     { const GAS f32x4* g4 = (const GAS f32x4*)gain;
;       for (int q = F.tid; q < 5 * D / 4; q += NWAVES * 64) { const int bq = q >> 9, cq = q & 511; const GAS f32x4* mb4 = (const GAS f32x4*)(modl + (size_t)bq * MOD_LD);
;           ((LAS f32x4*)CA)[q] = g4[cq] * (mb4[sc_off / 4 + cq] + 1.0f); ((LAS f32x4*)CB)[q] = mb4[sh_off / 4 + cq]; } }
;     asm volatile("s_waitcnt lgkmcnt(0)" ::: "memory"); __builtin_amdgcn_s_barrier(); asm volatile("" ::: "memory");
	v_lshl_add_u32 v184, v142, 4, 0
	v_add_u32_e32 v185, 0xa000, v184
	v_pk_add_f32 v[210:211], v[210:211], 1.0 op_sel_hi:[1,0]
	v_pk_add_f32 v[208:209], v[208:209], 1.0 op_sel_hi:[1,0]
	v_pk_mul_f32 v[210:211], v[194:195], v[210:211]
	v_pk_mul_f32 v[208:209], v[192:193], v[208:209]
	ds_write_b128 v184, v[208:211]
	ds_write_b128 v185, v[228:231]
	v_pk_add_f32 v[214:215], v[214:215], 1.0 op_sel_hi:[1,0]
	v_pk_add_f32 v[212:213], v[212:213], 1.0 op_sel_hi:[1,0]
	v_pk_mul_f32 v[214:215], v[194:195], v[214:215]
	v_pk_mul_f32 v[212:213], v[192:193], v[212:213]
	ds_write_b128 v184, v[212:215] offset:8192
	ds_write_b128 v185, v[232:235] offset:8192
	v_pk_add_f32 v[218:219], v[218:219], 1.0 op_sel_hi:[1,0]
	v_pk_add_f32 v[216:217], v[216:217], 1.0 op_sel_hi:[1,0]
	v_pk_mul_f32 v[218:219], v[194:195], v[218:219]
	v_pk_mul_f32 v[216:217], v[192:193], v[216:217]
	ds_write_b128 v184, v[216:219] offset:16384
	ds_write_b128 v185, v[236:239] offset:16384
	v_pk_add_f32 v[222:223], v[222:223], 1.0 op_sel_hi:[1,0]
	v_pk_add_f32 v[220:221], v[220:221], 1.0 op_sel_hi:[1,0]
	v_pk_mul_f32 v[222:223], v[194:195], v[222:223]
	v_pk_mul_f32 v[220:221], v[192:193], v[220:221]
	ds_write_b128 v184, v[220:223] offset:24576
	ds_write_b128 v185, v[240:243] offset:24576
	v_pk_add_f32 v[226:227], v[226:227], 1.0 op_sel_hi:[1,0]
	v_pk_add_f32 v[224:225], v[224:225], 1.0 op_sel_hi:[1,0]
	v_pk_mul_f32 v[226:227], v[194:195], v[226:227]
	v_pk_mul_f32 v[224:225], v[192:193], v[224:225]
	ds_write_b128 v184, v[224:227] offset:32768
	ds_write_b128 v185, v[244:247] offset:32768
	s_waitcnt vmcnt(62)
	v_cvt_f32_f16_sdwa v153, v140 dst_sel:DWORD dst_unused:UNUSED_PAD src0_sel:WORD_1
	v_cvt_f32_f16_sdwa v149, v138 dst_sel:DWORD dst_unused:UNUSED_PAD src0_sel:WORD_1
	v_cvt_f32_f16_e32 v152, v140
	v_cvt_f32_f16_sdwa v155, v141 dst_sel:DWORD dst_unused:UNUSED_PAD src0_sel:WORD_1
	v_cvt_f32_f16_e32 v148, v138
	v_cvt_f32_f16_sdwa v151, v139 dst_sel:DWORD dst_unused:UNUSED_PAD src0_sel:WORD_1
	v_cvt_f32_f16_e32 v154, v141
	v_cvt_f32_f16_e32 v150, v139
	s_waitcnt vmcnt(61)
	v_cvt_f32_f16_sdwa v139, v136 dst_sel:DWORD dst_unused:UNUSED_PAD src0_sel:WORD_1
	v_cvt_f32_f16_sdwa v141, v137 dst_sel:DWORD dst_unused:UNUSED_PAD src0_sel:WORD_1
	s_mov_b64 s[6:7], 0x8c00000
	v_mov_b32_e32 v74, v153
	v_mov_b32_e32 v75, v149
	v_cvt_f32_f16_e32 v138, v136
	v_cvt_f32_f16_e32 v140, v137
	v_lshl_add_u64 v[2:3], v[128:129], 0, s[6:7]
	v_mov_b32_e32 v4, v152
	v_mov_b32_e32 v5, v148
	v_pk_mul_f32 v[74:75], v[74:75], v[74:75]
	v_mov_b32_e32 v128, v155
	v_mov_b32_e32 v129, v151
	v_pk_fma_f32 v[4:5], v[4:5], v[4:5], v[74:75]
	v_mov_b32_e32 v74, v154
	v_mov_b32_e32 v75, v150
	v_pk_mul_f32 v[128:129], v[128:129], v[128:129]
	s_waitcnt vmcnt(60)
	v_cvt_f32_f16_sdwa v145, v132 dst_sel:DWORD dst_unused:UNUSED_PAD src0_sel:WORD_1
	v_pk_fma_f32 v[74:75], v[74:75], v[74:75], v[128:129]
	v_mov_b32_e32 v128, v139
	v_mov_b32_e32 v129, v141
	v_pk_add_f32 v[4:5], v[4:5], v[74:75]
	v_mov_b32_e32 v74, v138
	v_mov_b32_e32 v75, v140
	v_pk_mul_f32 v[128:129], v[128:129], v[128:129]
	v_cvt_f32_f16_e32 v144, v132
	v_cvt_f32_f16_sdwa v147, v133 dst_sel:DWORD dst_unused:UNUSED_PAD src0_sel:WORD_1
	v_pk_fma_f32 v[74:75], v[74:75], v[74:75], v[128:129]
	v_cvt_f32_f16_e32 v146, v133
	s_waitcnt vmcnt(59)
	v_cvt_f32_f16_sdwa v129, v134 dst_sel:DWORD dst_unused:UNUSED_PAD src0_sel:WORD_1
	v_cvt_f32_f16_e32 v128, v134
	v_cvt_f32_f16_sdwa v133, v135 dst_sel:DWORD dst_unused:UNUSED_PAD src0_sel:WORD_1
	v_cvt_f32_f16_e32 v132, v135
	v_mul_f32_e32 v0, v145, v145
	v_pk_fma_f32 v[136:137], v[144:145], v[144:145], v[0:1] op_sel_hi:[1,1,0]
	v_mul_f32_e32 v0, v147, v147
	v_pk_add_f32 v[4:5], v[4:5], v[4:5] op_sel:[0,1] op_sel_hi:[1,0]
	v_pk_add_f32 v[74:75], v[74:75], v[74:75] op_sel:[0,1] op_sel_hi:[1,0]
	v_pk_fma_f32 v[156:157], v[146:147], v[146:147], v[0:1] op_sel_hi:[1,1,0]
	v_pk_mul_f32 v[134:135], v[128:129], v[128:129]
	v_pk_mul_f32 v[158:159], v[132:133], v[132:133]
	v_mov_b32_e32 v5, v134
	v_mov_b32_e32 v75, v135
	v_mov_b32_e32 v137, v158
	v_mov_b32_e32 v157, v159
	v_pk_add_f32 v[4:5], v[4:5], v[74:75]
	v_pk_add_f32 v[74:75], v[136:137], v[156:157]
	s_waitcnt vmcnt(58)
	v_cvt_f32_f16_sdwa v135, v124 dst_sel:DWORD dst_unused:UNUSED_PAD src0_sel:WORD_1
	v_cvt_f32_f16_sdwa v137, v125 dst_sel:DWORD dst_unused:UNUSED_PAD src0_sel:WORD_1
	v_cvt_f32_f16_e32 v134, v124
	v_cvt_f32_f16_e32 v136, v125
	v_pk_add_f32 v[4:5], v[4:5], v[74:75]
	v_mov_b32_e32 v74, v135
	v_mov_b32_e32 v75, v137
	v_pk_add_f32 v[156:157], v[4:5], v[4:5] op_sel:[0,1] op_sel_hi:[1,0]
	v_mov_b32_e32 v4, v134
	v_mov_b32_e32 v5, v136
	v_pk_mul_f32 v[74:75], v[74:75], v[74:75]
	s_waitcnt vmcnt(57)
	v_cvt_f32_f16_sdwa v125, v127 dst_sel:DWORD dst_unused:UNUSED_PAD src0_sel:WORD_1
	v_pk_fma_f32 v[4:5], v[4:5], v[4:5], v[74:75]
	v_cvt_f32_f16_e32 v124, v127
	v_pk_add_f32 v[158:159], v[4:5], v[4:5] op_sel:[0,1] op_sel_hi:[1,0]
	v_cvt_f32_f16_sdwa v5, v126 dst_sel:DWORD dst_unused:UNUSED_PAD src0_sel:WORD_1
	v_cvt_f32_f16_e32 v4, v126
	s_waitcnt vmcnt(56)
	v_cvt_f32_f16_sdwa v75, v130 dst_sel:DWORD dst_unused:UNUSED_PAD src0_sel:WORD_1
	v_cvt_f32_f16_e32 v74, v130
	v_cvt_f32_f16_sdwa v127, v131 dst_sel:DWORD dst_unused:UNUSED_PAD src0_sel:WORD_1
	v_cvt_f32_f16_e32 v126, v131
	v_mul_f32_e32 v0, v5, v5
	v_pk_fma_f32 v[160:161], v[4:5], v[4:5], v[0:1] op_sel_hi:[1,1,0]
	v_mul_f32_e32 v0, v125, v125
	v_pk_fma_f32 v[162:163], v[124:125], v[124:125], v[0:1] op_sel_hi:[1,1,0]
	v_pk_mul_f32 v[130:131], v[74:75], v[74:75]
	v_pk_mul_f32 v[164:165], v[126:127], v[126:127]
	v_mov_b32_e32 v157, v130
	v_mov_b32_e32 v159, v131
	v_mov_b32_e32 v161, v164
	v_mov_b32_e32 v163, v165
	v_pk_add_f32 v[130:131], v[156:157], v[158:159]
	v_pk_add_f32 v[156:157], v[160:161], v[162:163]
	s_lshl_b64 s[8:9], s[4:5], 11
	v_pk_add_f32 v[130:131], v[130:131], v[156:157]
	s_lshl_b64 s[12:13], s[10:11], 11
	v_add_f32_e32 v0, v130, v131
	s_waitcnt lgkmcnt(0)
	s_barrier
; #define GAS __attribute__((address_space(1)))
; #define LAS __attribute__((address_space(3)))
; #define NR_LOAD(dst, k_) do { const GAS v2u* xr_ = (const GAS v2u*)(X + (size_t)(nw + 2048 * (k_)) * D) + F.lane; \
;         _Pragma("unroll") for (int j = 0; j < 8; ++j) dst[j] = __builtin_nontemporal_load(xr_ + 64 * j); } while (0)
; __device__ __forceinline__ void norm_mod_phase2(const Args& a, Frame& F, const float* gain, const float* modl, int sh_off, int sc_off, int nrows, const float* slab_gate) {
;     ...
;     NR_LOAD(r0, 0); NR_LOAD(r1, 1); NR_LOAD(r2, 2); NR_LOAD(r3, 3); NR_LOAD(r4, 4); NR_LOAD(r5, 5); NR_LOAD(r6, 6); NR_LOAD(r7, 7);
;     { const GAS f32x4* g4 = (const GAS f32x4*)gain;
;       for (int q = F.tid; q < 5 * D / 4; q += NWAVES * 64) { const int bq = q >> 9, cq = q & 511; const GAS f32x4* mb4 = (const GAS f32x4*)(modl + (size_t)bq * MOD_LD);
;           ((LAS f32x4*)CA)[q] = g4[cq] * (mb4[sc_off / 4 + cq] + 1.0f); ((LAS f32x4*)CB)[q] = mb4[sh_off / 4 + cq]; } }
;     asm volatile("s_waitcnt lgkmcnt(0)" ::: "memory"); __builtin_amdgcn_s_barrier(); asm volatile("" ::: "memory");
;     NR_FINISH(r0, nw,            (nw) >> 12);
	s_lshl_b64 s[40:41], s[36:37], 11
	v_add_f32_dpp v0, v0, v0 quad_perm:[1,0,3,2] row_mask:0xf bank_mask:0xf bound_ctrl:1
	s_lshl_b64 s[34:35], s[30:31], 11
	s_lshl_b64 s[28:29], s[26:27], 11
	v_add_f32_dpp v0, v0, v0 quad_perm:[2,3,0,1] row_mask:0xf bank_mask:0xf bound_ctrl:1
	s_lshl_b64 s[24:25], s[22:23], 11
	s_lshl_b64 s[20:21], s[18:19], 11
	v_add_f32_dpp v0, v0, v0 row_half_mirror row_mask:0xf bank_mask:0xf bound_ctrl:1
	s_lshl_b64 s[16:17], s[14:15], 11
	s_nop 0
	v_add_f32_dpp v0, v0, v0 row_mirror row_mask:0xf bank_mask:0xf bound_ctrl:1
	s_nop 0
	v_readlane_b32 s5, v0, 16
	v_readlane_b32 s11, v0, 48
	v_readlane_b32 s6, v0, 0
	v_readlane_b32 s7, v0, 32
	v_mov_b32_e32 v130, s5
	v_mov_b32_e32 v131, s11
	v_pk_add_f32 v[130:131], s[6:7], v[130:131]
	s_lshl_b32 s5, s4, 1
	v_add_f32_e32 v0, v130, v131
	v_fmamk_f32 v0, v0, 0x3a000000, v252
	v_cmp_gt_f32_e32 vcc, s55, v0
	v_mul_f32_e32 v7, 0x4f800000, v0
	s_and_b32 s5, s5, 0xffffe000
	v_cndmask_b32_e32 v0, v0, v7, vcc
	v_sqrt_f32_e32 v7, v0
	s_add_i32 s5, s5, 0
	v_add_u32_e32 v130, -1, v7
	v_fma_f32 v131, -v130, v7, v0
	v_cmp_ge_f32_e64 s[6:7], 0, v131
	v_add_u32_e32 v131, 1, v7
	s_nop 0
	v_cndmask_b32_e64 v130, v7, v130, s[6:7]
	v_fma_f32 v7, -v131, v7, v0
	v_cmp_lt_f32_e64 s[6:7], 0, v7
	s_nop 1
	v_cndmask_b32_e64 v7, v130, v131, s[6:7]
	v_mul_f32_e32 v130, 0x37800000, v7
	v_cndmask_b32_e32 v7, v7, v130, vcc
	v_cmp_class_f32_e32 vcc, v0, v253
	s_nop 1
	v_cndmask_b32_e32 v0, v7, v0, vcc
	v_div_scale_f32 v7, s[6:7], v0, v0, 1.0
	v_rcp_f32_e32 v130, v7
	s_nop 0
	v_fma_f32 v131, -v7, v130, 1.0
	v_fmac_f32_e32 v130, v131, v130
	v_div_scale_f32 v131, vcc, 1.0, v0, 1.0
	v_mul_f32_e32 v142, v131, v130
	v_fma_f32 v156, -v7, v142, v131
	v_fmac_f32_e32 v142, v156, v130
	v_fma_f32 v7, -v7, v142, v131
	v_div_fmas_f32 v7, v7, v130, v142
	v_div_fixup_f32 v142, v7, v0, 1.0
	v_lshlrev_b32_e32 v0, 4, v143
	v_add_u32_e32 v164, s5, v0
	v_pk_mul_f32 v[160:161], v[152:153], v[142:143] op_sel_hi:[1,0]
	v_pk_mul_f32 v[162:163], v[154:155], v[142:143] op_sel_hi:[1,0]
	ds_read_b128 v[152:155], v164
	ds_read_b128 v[156:159], v164 offset:40960
	v_lshl_add_u64 v[130:131], s[8:9], 1, v[2:3]
	v_mov_b32_e32 v7, v1
	v_lshl_add_u64 v[130:131], v[130:131], 0, v[6:7]
	v_pk_mul_f32 v[128:129], v[128:129], v[142:143] op_sel_hi:[1,0]
	s_waitcnt lgkmcnt(0)
	v_pk_fma_f32 v[154:155], v[154:155], v[162:163], v[158:159]
	v_pk_fma_f32 v[152:153], v[152:153], v[160:161], v[156:157]
	v_pk_mul_f32 v[156:157], v[148:149], v[142:143] op_sel_hi:[1,0]
	v_cvt_pk_bf16_f32 v152, v152, v153
	v_cvt_pk_bf16_f32 v153, v154, v155
	global_store_dwordx2 v[130:131], v[152:153], off
	v_pk_mul_f32 v[158:159], v[150:151], v[142:143] op_sel_hi:[1,0]
	ds_read_b128 v[148:151], v164 offset:1024
	ds_read_b128 v[152:155], v164 offset:41984
	v_pk_mul_f32 v[132:133], v[132:133], v[142:143] op_sel_hi:[1,0]
	v_pk_mul_f32 v[4:5], v[4:5], v[142:143] op_sel_hi:[1,0]
	v_pk_mul_f32 v[124:125], v[124:125], v[142:143] op_sel_hi:[1,0]
	s_waitcnt lgkmcnt(0)
	v_pk_fma_f32 v[150:151], v[150:151], v[158:159], v[154:155]
	v_pk_fma_f32 v[148:149], v[148:149], v[156:157], v[152:153]
	v_pk_mul_f32 v[152:153], v[138:139], v[142:143] op_sel_hi:[1,0]
	v_cvt_pk_bf16_f32 v148, v148, v149
	v_cvt_pk_bf16_f32 v149, v150, v151
	global_store_dwordx2 v[130:131], v[148:149], off offset:512
	v_pk_mul_f32 v[154:155], v[140:141], v[142:143] op_sel_hi:[1,0]
	ds_read_b128 v[138:141], v164 offset:2048
	ds_read_b128 v[148:151], v164 offset:43008
	s_waitcnt lgkmcnt(0)
	v_pk_fma_f32 v[140:141], v[140:141], v[154:155], v[150:151]
	v_pk_fma_f32 v[138:139], v[138:139], v[152:153], v[148:149]
	v_pk_mul_f32 v[148:149], v[144:145], v[142:143] op_sel_hi:[1,0]
	v_cvt_pk_bf16_f32 v138, v138, v139
	v_cvt_pk_bf16_f32 v139, v140, v141
	global_store_dwordx2 v[130:131], v[138:139], off offset:1024
	v_pk_mul_f32 v[150:151], v[146:147], v[142:143] op_sel_hi:[1,0]
	ds_read_b128 v[138:141], v164 offset:3072
	ds_read_b128 v[144:147], v164 offset:44032
	s_waitcnt lgkmcnt(0)
	v_pk_fma_f32 v[140:141], v[150:151], v[140:141], v[146:147]
	v_pk_fma_f32 v[138:139], v[148:149], v[138:139], v[144:145]
	s_nop 0
	v_cvt_pk_bf16_f32 v138, v138, v139
	v_cvt_pk_bf16_f32 v139, v140, v141
	global_store_dwordx2 v[130:131], v[138:139], off offset:1536
	ds_read_b128 v[138:141], v164 offset:4096
	ds_read_b128 v[144:147], v164 offset:45056
	s_waitcnt lgkmcnt(0)
	v_pk_fma_f32 v[132:133], v[132:133], v[140:141], v[146:147]
	v_pk_fma_f32 v[128:129], v[128:129], v[138:139], v[144:145]
	v_pk_mul_f32 v[140:141], v[136:137], v[142:143] op_sel_hi:[1,0]
	v_cvt_pk_bf16_f32 v128, v128, v129
	v_cvt_pk_bf16_f32 v129, v132, v133
	global_store_dwordx2 v[130:131], v[128:129], off offset:2048
	v_pk_mul_f32 v[128:129], v[134:135], v[142:143] op_sel_hi:[1,0]
	ds_read_b128 v[132:135], v164 offset:5120
	ds_read_b128 v[136:139], v164 offset:46080
	s_waitcnt lgkmcnt(0)
	v_pk_fma_f32 v[134:135], v[140:141], v[134:135], v[138:139]
	v_pk_fma_f32 v[128:129], v[128:129], v[132:133], v[136:137]
	s_nop 0
	v_cvt_pk_bf16_f32 v128, v128, v129
	v_cvt_pk_bf16_f32 v129, v134, v135
	global_store_dwordx2 v[130:131], v[128:129], off offset:2560
	ds_read_b128 v[132:135], v164 offset:6144
	ds_read_b128 v[136:139], v164 offset:47104
	s_waitcnt vmcnt(58)
	v_cvt_f32_f16_sdwa v129, v117 dst_sel:DWORD dst_unused:UNUSED_PAD src0_sel:WORD_1
	v_cvt_f32_f16_e32 v128, v117
	s_waitcnt lgkmcnt(0)
; #define GAS __attribute__((address_space(1)))
; #define LAS __attribute__((address_space(3)))
; #define NR_LOAD(dst, k_) do { const GAS v2u* xr_ = (const GAS v2u*)(X + (size_t)(nw + 2048 * (k_)) * D) + F.lane; \
;         _Pragma("unroll") for (int j = 0; j < 8; ++j) dst[j] = __builtin_nontemporal_load(xr_ + 64 * j); } while (0)
; __device__ __forceinline__ void norm_mod_phase2(const Args& a, Frame& F, const float* gain, const float* modl, int sh_off, int sc_off, int nrows, const float* slab_gate) {
;     ...
;     NR_LOAD(r0, 0); NR_LOAD(r1, 1); NR_LOAD(r2, 2); NR_LOAD(r3, 3); NR_LOAD(r4, 4); NR_LOAD(r5, 5); NR_LOAD(r6, 6); NR_LOAD(r7, 7);
;     { const GAS f32x4* g4 = (const GAS f32x4*)gain;
;       for (int q = F.tid; q < 5 * D / 4; q += NWAVES * 64) { const int bq = q >> 9, cq = q & 511; const GAS f32x4* mb4 = (const GAS f32x4*)(modl + (size_t)bq * MOD_LD);
;           ((LAS f32x4*)CA)[q] = g4[cq] * (mb4[sc_off / 4 + cq] + 1.0f); ((LAS f32x4*)CB)[q] = mb4[sh_off / 4 + cq]; } }
;     asm volatile("s_waitcnt lgkmcnt(0)" ::: "memory"); __builtin_amdgcn_s_barrier(); asm volatile("" ::: "memory");
;     NR_FINISH(r0, nw,            (nw) >> 12);
;     NR_FINISH(r1, nw + 2048,     (nw + 2048) >> 12);
;     NR_FINISH(r2, nw + 2 * 2048, (nw + 2 * 2048) >> 12);
;     NR_FINISH(r3, nw + 3 * 2048, (nw + 3 * 2048) >> 12);
;     NR_FINISH(r4, nw + 4 * 2048, (nw + 4 * 2048) >> 12);
;     NR_FINISH(r5, nw + 5 * 2048, (nw + 5 * 2048) >> 12);
;     NR_FINISH(r6, nw + 6 * 2048, (nw + 6 * 2048) >> 12);
;     NR_FINISH(r7, nw + 7 * 2048, (nw + 7 * 2048) >> 12);
	v_pk_fma_f32 v[124:125], v[124:125], v[134:135], v[138:139]
	v_pk_fma_f32 v[4:5], v[4:5], v[132:133], v[136:137]
	v_cvt_f32_f16_sdwa v137, v122 dst_sel:DWORD dst_unused:UNUSED_PAD src0_sel:WORD_1
	v_cvt_pk_bf16_f32 v4, v4, v5
	v_cvt_pk_bf16_f32 v5, v124, v125
	global_store_dwordx2 v[130:131], v[4:5], off offset:3072
	v_pk_mul_f32 v[4:5], v[74:75], v[142:143] op_sel_hi:[1,0]
	v_pk_mul_f32 v[74:75], v[126:127], v[142:143] op_sel_hi:[1,0]
	ds_read_b128 v[124:127], v164 offset:7168
	ds_read_b128 v[132:135], v164 offset:48128
	v_cvt_f32_f16_e32 v136, v122
	v_cvt_f32_f16_sdwa v139, v123 dst_sel:DWORD dst_unused:UNUSED_PAD src0_sel:WORD_1
	v_cvt_f32_f16_e32 v138, v123
	v_cvt_f32_f16_sdwa v123, v118 dst_sel:DWORD dst_unused:UNUSED_PAD src0_sel:WORD_1
	s_waitcnt lgkmcnt(0)
	v_pk_fma_f32 v[4:5], v[4:5], v[124:125], v[132:133]
	v_cvt_f32_f16_sdwa v133, v120 dst_sel:DWORD dst_unused:UNUSED_PAD src0_sel:WORD_1
	v_pk_fma_f32 v[74:75], v[74:75], v[126:127], v[134:135]
	v_cvt_f32_f16_e32 v132, v120
	v_cvt_f32_f16_sdwa v135, v121 dst_sel:DWORD dst_unused:UNUSED_PAD src0_sel:WORD_1
	v_cvt_f32_f16_e32 v134, v121
	v_cvt_f32_f16_sdwa v125, v119 dst_sel:DWORD dst_unused:UNUSED_PAD src0_sel:WORD_1
	v_cvt_f32_f16_sdwa v127, v116 dst_sel:DWORD dst_unused:UNUSED_PAD src0_sel:WORD_1
	v_cvt_pk_bf16_f32 v4, v4, v5
	v_cvt_pk_bf16_f32 v5, v74, v75
	v_mov_b32_e32 v74, v137
	v_mov_b32_e32 v75, v133
	v_cvt_f32_f16_e32 v122, v118
	v_cvt_f32_f16_e32 v124, v119
	v_cvt_f32_f16_e32 v126, v116
	global_store_dwordx2 v[130:131], v[4:5], off offset:3584
	v_mov_b32_e32 v4, v136
	v_mov_b32_e32 v5, v132
	v_pk_mul_f32 v[74:75], v[74:75], v[74:75]
	v_mov_b32_e32 v120, v139
	v_mov_b32_e32 v121, v135
	v_pk_fma_f32 v[4:5], v[4:5], v[4:5], v[74:75]
	v_mov_b32_e32 v74, v138
	v_mov_b32_e32 v75, v134
	v_pk_mul_f32 v[120:121], v[120:121], v[120:121]
	v_mov_b32_e32 v118, v123
	v_pk_fma_f32 v[74:75], v[74:75], v[74:75], v[120:121]
	v_mov_b32_e32 v119, v125
	v_mul_f32_e32 v116, v127, v127
	v_pk_add_f32 v[4:5], v[4:5], v[74:75]
	v_mov_b32_e32 v74, v122
	v_mov_b32_e32 v75, v124
	v_pk_mul_f32 v[118:119], v[118:119], v[118:119]
	v_pk_fma_f32 v[120:121], v[126:127], v[126:127], v[116:117] op_sel_hi:[1,1,0]
	v_mul_f32_e32 v116, v129, v129
	v_pk_fma_f32 v[74:75], v[74:75], v[74:75], v[118:119]
	v_pk_fma_f32 v[130:131], v[128:129], v[128:129], v[116:117] op_sel_hi:[1,1,0]
	s_waitcnt vmcnt(59)
	v_cvt_f32_f16_sdwa v117, v114 dst_sel:DWORD dst_unused:UNUSED_PAD src0_sel:WORD_1
	v_cvt_f32_f16_e32 v116, v114
	v_cvt_f32_f16_sdwa v119, v115 dst_sel:DWORD dst_unused:UNUSED_PAD src0_sel:WORD_1
	v_cvt_f32_f16_e32 v118, v115
	v_pk_add_f32 v[4:5], v[4:5], v[4:5] op_sel:[0,1] op_sel_hi:[1,0]
	v_pk_add_f32 v[74:75], v[74:75], v[74:75] op_sel:[0,1] op_sel_hi:[1,0]
	v_pk_mul_f32 v[114:115], v[116:117], v[116:117]
	v_pk_mul_f32 v[140:141], v[118:119], v[118:119]
	v_mov_b32_e32 v5, v114
	v_mov_b32_e32 v75, v115
	v_mov_b32_e32 v121, v140
	v_mov_b32_e32 v131, v141
	v_pk_add_f32 v[4:5], v[4:5], v[74:75]
	v_pk_add_f32 v[74:75], v[120:121], v[130:131]
	s_waitcnt vmcnt(58)
	v_cvt_f32_f16_sdwa v115, v112 dst_sel:DWORD dst_unused:UNUSED_PAD src0_sel:WORD_1
	v_cvt_f32_f16_sdwa v121, v113 dst_sel:DWORD dst_unused:UNUSED_PAD src0_sel:WORD_1
	v_cvt_f32_f16_e32 v114, v112
	v_cvt_f32_f16_e32 v120, v113
	v_pk_add_f32 v[4:5], v[4:5], v[74:75]
	v_mov_b32_e32 v74, v115
	v_mov_b32_e32 v75, v121
	v_pk_add_f32 v[130:131], v[4:5], v[4:5] op_sel:[0,1] op_sel_hi:[1,0]
	v_mov_b32_e32 v4, v114
	v_mov_b32_e32 v5, v120
	v_pk_mul_f32 v[74:75], v[74:75], v[74:75]
	s_waitcnt vmcnt(57)
	v_cvt_f32_f16_sdwa v113, v111 dst_sel:DWORD dst_unused:UNUSED_PAD src0_sel:WORD_1
	v_pk_fma_f32 v[4:5], v[4:5], v[4:5], v[74:75]
	v_cvt_f32_f16_e32 v112, v111
	v_pk_add_f32 v[140:141], v[4:5], v[4:5] op_sel:[0,1] op_sel_hi:[1,0]
	v_cvt_f32_f16_sdwa v5, v110 dst_sel:DWORD dst_unused:UNUSED_PAD src0_sel:WORD_1
	v_cvt_f32_f16_e32 v4, v110
	s_waitcnt vmcnt(56)
	v_cvt_f32_f16_sdwa v111, v109 dst_sel:DWORD dst_unused:UNUSED_PAD src0_sel:WORD_1
	v_cvt_f32_f16_e32 v110, v109
	v_mul_f32_e32 v74, v5, v5
	v_pk_fma_f32 v[144:145], v[4:5], v[4:5], v[74:75] op_sel_hi:[1,1,0]
	v_mul_f32_e32 v74, v113, v113
	v_pk_fma_f32 v[146:147], v[112:113], v[112:113], v[74:75] op_sel_hi:[1,1,0]
	v_cvt_f32_f16_sdwa v75, v108 dst_sel:DWORD dst_unused:UNUSED_PAD src0_sel:WORD_1
	v_cvt_f32_f16_e32 v74, v108
	v_pk_mul_f32 v[148:149], v[110:111], v[110:111]
	v_pk_mul_f32 v[108:109], v[74:75], v[74:75]
	s_nop 0
	v_mov_b32_e32 v131, v108
	v_mov_b32_e32 v141, v109
	v_mov_b32_e32 v145, v148
	v_mov_b32_e32 v147, v149
	v_pk_add_f32 v[108:109], v[130:131], v[140:141]
	v_pk_add_f32 v[130:131], v[144:145], v[146:147]
	s_nop 0
	v_pk_add_f32 v[108:109], v[108:109], v[130:131]
	s_nop 0
	v_add_f32_e32 v108, v108, v109
	s_nop 1
	v_add_f32_dpp v108, v108, v108 quad_perm:[1,0,3,2] row_mask:0xf bank_mask:0xf bound_ctrl:1
	s_nop 1
	v_add_f32_dpp v108, v108, v108 quad_perm:[2,3,0,1] row_mask:0xf bank_mask:0xf bound_ctrl:1
	s_nop 1
	v_add_f32_dpp v108, v108, v108 row_half_mirror row_mask:0xf bank_mask:0xf bound_ctrl:1
	s_nop 1
	v_add_f32_dpp v108, v108, v108 row_mirror row_mask:0xf bank_mask:0xf bound_ctrl:1
	s_nop 0
	v_readlane_b32 s5, v108, 16
	v_readlane_b32 s11, v108, 48
	v_readlane_b32 s6, v108, 0
	v_readlane_b32 s7, v108, 32
	v_mov_b32_e32 v108, s5
	v_mov_b32_e32 v109, s11
	v_pk_add_f32 v[108:109], s[6:7], v[108:109]
	s_lshl_b32 s5, s36, 1
	v_add_f32_e32 v108, v108, v109
	v_fmamk_f32 v108, v108, 0x3a000000, v252
	v_cmp_gt_f32_e32 vcc, s55, v108
	v_mul_f32_e32 v109, 0x4f800000, v108
	s_and_b32 s5, s5, 0xffffe000
	v_cndmask_b32_e32 v108, v108, v109, vcc
	v_sqrt_f32_e32 v109, v108
	s_add_i32 s5, s5, 0
	v_add_u32_e32 v130, -1, v109
	v_fma_f32 v131, -v130, v109, v108
	v_cmp_ge_f32_e64 s[6:7], 0, v131
	v_add_u32_e32 v131, 1, v109
	s_nop 0
	v_cndmask_b32_e64 v130, v109, v130, s[6:7]
	v_fma_f32 v109, -v131, v109, v108
	v_cmp_lt_f32_e64 s[6:7], 0, v109
	s_nop 1
	v_cndmask_b32_e64 v109, v130, v131, s[6:7]
	v_mul_f32_e32 v130, 0x37800000, v109
	v_cndmask_b32_e32 v109, v109, v130, vcc
	v_cmp_class_f32_e32 vcc, v108, v253
	s_nop 1
	v_cndmask_b32_e32 v108, v109, v108, vcc
	v_div_scale_f32 v109, s[6:7], v108, v108, 1.0
	v_rcp_f32_e32 v130, v109
	s_nop 0
	v_fma_f32 v131, -v109, v130, 1.0
	v_fmac_f32_e32 v130, v131, v130
	v_div_scale_f32 v131, vcc, 1.0, v108, 1.0
	v_mul_f32_e32 v140, v131, v130
	v_fma_f32 v141, -v109, v140, v131
	v_fmac_f32_e32 v140, v141, v130
	v_fma_f32 v109, -v109, v140, v131
	v_div_fmas_f32 v109, v109, v130, v140
	v_div_fixup_f32 v130, v109, v108, 1.0
	v_pk_mul_f32 v[140:141], v[136:137], v[130:131] op_sel_hi:[1,0]
	v_pk_mul_f32 v[148:149], v[138:139], v[130:131] op_sel_hi:[1,0]
	v_add_u32_e32 v131, s5, v0
	ds_read_b128 v[136:139], v131
	ds_read_b128 v[144:147], v131 offset:40960
	v_lshl_add_u64 v[108:109], s[40:41], 1, v[2:3]
	v_lshl_add_u64 v[108:109], v[108:109], 0, v[6:7]
	v_pk_mul_f32 v[4:5], v[4:5], v[130:131] op_sel_hi:[1,0]
	s_waitcnt lgkmcnt(0)
; #define GAS __attribute__((address_space(1)))
; #define LAS __attribute__((address_space(3)))
; #define NR_LOAD(dst, k_) do { const GAS v2u* xr_ = (const GAS v2u*)(X + (size_t)(nw + 2048 * (k_)) * D) + F.lane; \
;         _Pragma("unroll") for (int j = 0; j < 8; ++j) dst[j] = __builtin_nontemporal_load(xr_ + 64 * j); } while (0)
; __device__ __forceinline__ void norm_mod_phase2(const Args& a, Frame& F, const float* gain, const float* modl, int sh_off, int sc_off, int nrows, const float* slab_gate) {
;     ...
;     NR_LOAD(r0, 0); NR_LOAD(r1, 1); NR_LOAD(r2, 2); NR_LOAD(r3, 3); NR_LOAD(r4, 4); NR_LOAD(r5, 5); NR_LOAD(r6, 6); NR_LOAD(r7, 7);
;     { const GAS f32x4* g4 = (const GAS f32x4*)gain;
;       for (int q = F.tid; q < 5 * D / 4; q += NWAVES * 64) { const int bq = q >> 9, cq = q & 511; const GAS f32x4* mb4 = (const GAS f32x4*)(modl + (size_t)bq * MOD_LD);
;           ((LAS f32x4*)CA)[q] = g4[cq] * (mb4[sc_off / 4 + cq] + 1.0f); ((LAS f32x4*)CB)[q] = mb4[sh_off / 4 + cq]; } }
;     asm volatile("s_waitcnt lgkmcnt(0)" ::: "memory"); __builtin_amdgcn_s_barrier(); asm volatile("" ::: "memory");
;     NR_FINISH(r0, nw,            (nw) >> 12);
;     NR_FINISH(r1, nw + 2048,     (nw + 2048) >> 12);
;     NR_FINISH(r2, nw + 2 * 2048, (nw + 2 * 2048) >> 12);
;     NR_FINISH(r3, nw + 3 * 2048, (nw + 3 * 2048) >> 12);
;     NR_FINISH(r4, nw + 4 * 2048, (nw + 4 * 2048) >> 12);
;     NR_FINISH(r5, nw + 5 * 2048, (nw + 5 * 2048) >> 12);
;     NR_FINISH(r6, nw + 6 * 2048, (nw + 6 * 2048) >> 12);
;     NR_FINISH(r7, nw + 7 * 2048, (nw + 7 * 2048) >> 12);
	v_pk_fma_f32 v[138:139], v[138:139], v[148:149], v[146:147]
	v_pk_fma_f32 v[136:137], v[136:137], v[140:141], v[144:145]
	v_pk_mul_f32 v[140:141], v[132:133], v[130:131] op_sel_hi:[1,0]
	v_cvt_pk_bf16_f32 v136, v136, v137
	v_cvt_pk_bf16_f32 v137, v138, v139
	global_store_dwordx2 v[108:109], v[136:137], off
	v_pk_mul_f32 v[144:145], v[134:135], v[130:131] op_sel_hi:[1,0]
	ds_read_b128 v[132:135], v131 offset:1024
	ds_read_b128 v[136:139], v131 offset:41984
	s_waitcnt lgkmcnt(0)
	v_pk_fma_f32 v[134:135], v[134:135], v[144:145], v[138:139]
	v_pk_fma_f32 v[132:133], v[132:133], v[140:141], v[136:137]
	v_pk_mul_f32 v[136:137], v[122:123], v[130:131] op_sel_hi:[1,0]
	v_cvt_pk_bf16_f32 v132, v132, v133
	v_cvt_pk_bf16_f32 v133, v134, v135
	global_store_dwordx2 v[108:109], v[132:133], off offset:512
	v_pk_mul_f32 v[138:139], v[124:125], v[130:131] op_sel_hi:[1,0]
	ds_read_b128 v[122:125], v131 offset:2048
	ds_read_b128 v[132:135], v131 offset:43008
	s_waitcnt lgkmcnt(0)
	v_pk_fma_f32 v[124:125], v[124:125], v[138:139], v[134:135]
	v_pk_fma_f32 v[122:123], v[122:123], v[136:137], v[132:133]
	v_pk_mul_f32 v[132:133], v[126:127], v[130:131] op_sel_hi:[1,0]
	v_cvt_pk_bf16_f32 v122, v122, v123
	v_cvt_pk_bf16_f32 v123, v124, v125
	global_store_dwordx2 v[108:109], v[122:123], off offset:1024
	v_pk_mul_f32 v[134:135], v[128:129], v[130:131] op_sel_hi:[1,0]
	ds_read_b128 v[122:125], v131 offset:3072
	ds_read_b128 v[126:129], v131 offset:44032
	s_waitcnt lgkmcnt(0)
	v_pk_fma_f32 v[124:125], v[134:135], v[124:125], v[128:129]
	v_pk_fma_f32 v[122:123], v[132:133], v[122:123], v[126:127]
	v_pk_mul_f32 v[126:127], v[116:117], v[130:131] op_sel_hi:[1,0]
	v_cvt_pk_bf16_f32 v122, v122, v123
	v_cvt_pk_bf16_f32 v123, v124, v125
	global_store_dwordx2 v[108:109], v[122:123], off offset:1536
	v_pk_mul_f32 v[128:129], v[118:119], v[130:131] op_sel_hi:[1,0]
	ds_read_b128 v[116:119], v131 offset:4096
	ds_read_b128 v[122:125], v131 offset:45056
	s_waitcnt lgkmcnt(0)
	v_pk_fma_f32 v[118:119], v[128:129], v[118:119], v[124:125]
	v_pk_fma_f32 v[116:117], v[126:127], v[116:117], v[122:123]
	v_pk_mul_f32 v[122:123], v[114:115], v[130:131] op_sel_hi:[1,0]
	v_cvt_pk_bf16_f32 v116, v116, v117
	v_cvt_pk_bf16_f32 v117, v118, v119
	global_store_dwordx2 v[108:109], v[116:117], off offset:2048
	v_pk_mul_f32 v[124:125], v[120:121], v[130:131] op_sel_hi:[1,0]
	ds_read_b128 v[114:117], v131 offset:5120
	ds_read_b128 v[118:121], v131 offset:46080
	s_waitcnt lgkmcnt(0)
	v_pk_fma_f32 v[116:117], v[124:125], v[116:117], v[120:121]
	v_pk_fma_f32 v[114:115], v[122:123], v[114:115], v[118:119]
	v_pk_mul_f32 v[120:121], v[112:113], v[130:131] op_sel_hi:[1,0]
	v_cvt_pk_bf16_f32 v114, v114, v115
	v_cvt_pk_bf16_f32 v115, v116, v117
	global_store_dwordx2 v[108:109], v[114:115], off offset:2560
	ds_read_b128 v[112:115], v131 offset:6144
	ds_read_b128 v[116:119], v131 offset:47104
	s_waitcnt vmcnt(61)
	v_cvt_f32_f16_sdwa v123, v107 dst_sel:DWORD dst_unused:UNUSED_PAD src0_sel:WORD_1
	v_cvt_f32_f16_e32 v122, v107
	s_waitcnt vmcnt(59)
	v_cvt_f32_f16_sdwa v107, v102 dst_sel:DWORD dst_unused:UNUSED_PAD src0_sel:WORD_1
	s_waitcnt lgkmcnt(0)
	v_pk_fma_f32 v[114:115], v[120:121], v[114:115], v[118:119]
	v_pk_fma_f32 v[4:5], v[4:5], v[112:113], v[116:117]
	v_cvt_f32_f16_sdwa v121, v106 dst_sel:DWORD dst_unused:UNUSED_PAD src0_sel:WORD_1
	v_cvt_pk_bf16_f32 v4, v4, v5
	v_cvt_pk_bf16_f32 v5, v114, v115
	global_store_dwordx2 v[108:109], v[4:5], off offset:3072
	v_pk_mul_f32 v[4:5], v[74:75], v[130:131] op_sel_hi:[1,0]
	v_pk_mul_f32 v[74:75], v[110:111], v[130:131] op_sel_hi:[1,0]
	ds_read_b128 v[110:113], v131 offset:7168
	ds_read_b128 v[114:117], v131 offset:48128
	v_cvt_f32_f16_e32 v120, v106
	v_cvt_f32_f16_sdwa v119, v105 dst_sel:DWORD dst_unused:UNUSED_PAD src0_sel:WORD_1
	v_cvt_f32_f16_e32 v118, v105
	v_cvt_f32_f16_e32 v106, v102
	s_waitcnt lgkmcnt(0)
	v_pk_fma_f32 v[74:75], v[74:75], v[112:113], v[116:117]
	v_cvt_f32_f16_sdwa v117, v104 dst_sel:DWORD dst_unused:UNUSED_PAD src0_sel:WORD_1
	v_pk_fma_f32 v[4:5], v[4:5], v[110:111], v[114:115]
	v_cvt_f32_f16_e32 v116, v104
	v_cvt_pk_bf16_f32 v4, v4, v5
	v_cvt_pk_bf16_f32 v5, v74, v75
	global_store_dwordx2 v[108:109], v[4:5], off offset:3584
	v_cvt_f32_f16_sdwa v109, v103 dst_sel:DWORD dst_unused:UNUSED_PAD src0_sel:WORD_1
	s_waitcnt vmcnt(60)
	v_cvt_f32_f16_sdwa v111, v100 dst_sel:DWORD dst_unused:UNUSED_PAD src0_sel:WORD_1
	v_mov_b32_e32 v74, v121
	v_mov_b32_e32 v75, v117
	v_cvt_f32_f16_e32 v108, v103
	v_cvt_f32_f16_e32 v110, v100
	v_cvt_f32_f16_sdwa v113, v101 dst_sel:DWORD dst_unused:UNUSED_PAD src0_sel:WORD_1
	v_mov_b32_e32 v4, v120
	v_mov_b32_e32 v5, v116
	v_pk_mul_f32 v[74:75], v[74:75], v[74:75]
	v_mov_b32_e32 v104, v123
	v_mov_b32_e32 v105, v119
	v_cvt_f32_f16_e32 v112, v101
	v_pk_fma_f32 v[4:5], v[4:5], v[4:5], v[74:75]
	v_mov_b32_e32 v74, v122
	v_mov_b32_e32 v75, v118
	v_pk_mul_f32 v[104:105], v[104:105], v[104:105]
	v_mov_b32_e32 v102, v107
	v_pk_fma_f32 v[74:75], v[74:75], v[74:75], v[104:105]
	v_mov_b32_e32 v103, v109
	v_mul_f32_e32 v100, v111, v111
	v_pk_add_f32 v[4:5], v[4:5], v[74:75]
	v_mov_b32_e32 v74, v106
	v_mov_b32_e32 v75, v108
	v_pk_mul_f32 v[102:103], v[102:103], v[102:103]
	v_pk_fma_f32 v[104:105], v[110:111], v[110:111], v[100:101] op_sel_hi:[1,1,0]
	v_mul_f32_e32 v100, v113, v113
	v_pk_fma_f32 v[74:75], v[74:75], v[74:75], v[102:103]
	v_pk_fma_f32 v[114:115], v[112:113], v[112:113], v[100:101] op_sel_hi:[1,1,0]
	s_waitcnt vmcnt(59)
; #define GAS __attribute__((address_space(1)))
; #define LAS __attribute__((address_space(3)))
; #define NR_LOAD(dst, k_) do { const GAS v2u* xr_ = (const GAS v2u*)(X + (size_t)(nw + 2048 * (k_)) * D) + F.lane; \
;         _Pragma("unroll") for (int j = 0; j < 8; ++j) dst[j] = __builtin_nontemporal_load(xr_ + 64 * j); } while (0)
; __device__ __forceinline__ void norm_mod_phase2(const Args& a, Frame& F, const float* gain, const float* modl, int sh_off, int sc_off, int nrows, const float* slab_gate) {
;     ...
;     NR_LOAD(r0, 0); NR_LOAD(r1, 1); NR_LOAD(r2, 2); NR_LOAD(r3, 3); NR_LOAD(r4, 4); NR_LOAD(r5, 5); NR_LOAD(r6, 6); NR_LOAD(r7, 7);
;     { const GAS f32x4* g4 = (const GAS f32x4*)gain;
;       for (int q = F.tid; q < 5 * D / 4; q += NWAVES * 64) { const int bq = q >> 9, cq = q & 511; const GAS f32x4* mb4 = (const GAS f32x4*)(modl + (size_t)bq * MOD_LD);
;           ((LAS f32x4*)CA)[q] = g4[cq] * (mb4[sc_off / 4 + cq] + 1.0f); ((LAS f32x4*)CB)[q] = mb4[sh_off / 4 + cq]; } }
;     asm volatile("s_waitcnt lgkmcnt(0)" ::: "memory"); __builtin_amdgcn_s_barrier(); asm volatile("" ::: "memory");
;     NR_FINISH(r0, nw,            (nw) >> 12);
;     NR_FINISH(r1, nw + 2048,     (nw + 2048) >> 12);
;     NR_FINISH(r2, nw + 2 * 2048, (nw + 2 * 2048) >> 12);
;     NR_FINISH(r3, nw + 3 * 2048, (nw + 3 * 2048) >> 12);
;     NR_FINISH(r4, nw + 4 * 2048, (nw + 4 * 2048) >> 12);
;     NR_FINISH(r5, nw + 5 * 2048, (nw + 5 * 2048) >> 12);
;     NR_FINISH(r6, nw + 6 * 2048, (nw + 6 * 2048) >> 12);
;     NR_FINISH(r7, nw + 7 * 2048, (nw + 7 * 2048) >> 12);
	v_cvt_f32_f16_sdwa v101, v98 dst_sel:DWORD dst_unused:UNUSED_PAD src0_sel:WORD_1
	v_cvt_f32_f16_e32 v100, v98
	v_cvt_f32_f16_sdwa v103, v99 dst_sel:DWORD dst_unused:UNUSED_PAD src0_sel:WORD_1
	v_cvt_f32_f16_e32 v102, v99
	v_pk_add_f32 v[4:5], v[4:5], v[4:5] op_sel:[0,1] op_sel_hi:[1,0]
	v_pk_add_f32 v[74:75], v[74:75], v[74:75] op_sel:[0,1] op_sel_hi:[1,0]
	v_pk_mul_f32 v[98:99], v[100:101], v[100:101]
	v_pk_mul_f32 v[124:125], v[102:103], v[102:103]
	v_mov_b32_e32 v5, v98
	v_mov_b32_e32 v75, v99
	v_mov_b32_e32 v105, v124
	v_mov_b32_e32 v115, v125
	v_pk_add_f32 v[4:5], v[4:5], v[74:75]
	v_pk_add_f32 v[74:75], v[104:105], v[114:115]
	s_waitcnt vmcnt(58)
	v_cvt_f32_f16_sdwa v99, v96 dst_sel:DWORD dst_unused:UNUSED_PAD src0_sel:WORD_1
	v_cvt_f32_f16_sdwa v105, v97 dst_sel:DWORD dst_unused:UNUSED_PAD src0_sel:WORD_1
	v_cvt_f32_f16_e32 v98, v96
	v_cvt_f32_f16_e32 v104, v97
	v_pk_add_f32 v[4:5], v[4:5], v[74:75]
	v_mov_b32_e32 v74, v99
	v_mov_b32_e32 v75, v105
	v_pk_add_f32 v[114:115], v[4:5], v[4:5] op_sel:[0,1] op_sel_hi:[1,0]
	v_mov_b32_e32 v4, v98
	v_mov_b32_e32 v5, v104
	v_pk_mul_f32 v[74:75], v[74:75], v[74:75]
	s_waitcnt vmcnt(57)
	v_cvt_f32_f16_sdwa v97, v95 dst_sel:DWORD dst_unused:UNUSED_PAD src0_sel:WORD_1
	v_pk_fma_f32 v[4:5], v[4:5], v[4:5], v[74:75]
	v_cvt_f32_f16_e32 v96, v95
	v_pk_add_f32 v[124:125], v[4:5], v[4:5] op_sel:[0,1] op_sel_hi:[1,0]
	v_cvt_f32_f16_sdwa v5, v94 dst_sel:DWORD dst_unused:UNUSED_PAD src0_sel:WORD_1
	v_cvt_f32_f16_e32 v4, v94
	s_waitcnt vmcnt(56)
	v_cvt_f32_f16_sdwa v95, v93 dst_sel:DWORD dst_unused:UNUSED_PAD src0_sel:WORD_1
	v_cvt_f32_f16_e32 v94, v93
	v_mul_f32_e32 v74, v5, v5
	v_pk_fma_f32 v[126:127], v[4:5], v[4:5], v[74:75] op_sel_hi:[1,1,0]
	v_mul_f32_e32 v74, v97, v97
	v_pk_fma_f32 v[128:129], v[96:97], v[96:97], v[74:75] op_sel_hi:[1,1,0]
	v_cvt_f32_f16_sdwa v75, v92 dst_sel:DWORD dst_unused:UNUSED_PAD src0_sel:WORD_1
	v_cvt_f32_f16_e32 v74, v92
	v_pk_mul_f32 v[130:131], v[94:95], v[94:95]
	v_pk_mul_f32 v[92:93], v[74:75], v[74:75]
	s_nop 0
	v_mov_b32_e32 v115, v92
	v_mov_b32_e32 v125, v93
	v_mov_b32_e32 v127, v130
	v_mov_b32_e32 v129, v131
	v_pk_add_f32 v[92:93], v[114:115], v[124:125]
	v_pk_add_f32 v[114:115], v[126:127], v[128:129]
	s_nop 0
	v_pk_add_f32 v[92:93], v[92:93], v[114:115]
	s_nop 0
	v_add_f32_e32 v92, v92, v93
	s_nop 1
	v_add_f32_dpp v92, v92, v92 quad_perm:[1,0,3,2] row_mask:0xf bank_mask:0xf bound_ctrl:1
	s_nop 1
	v_add_f32_dpp v92, v92, v92 quad_perm:[2,3,0,1] row_mask:0xf bank_mask:0xf bound_ctrl:1
	s_nop 1
	v_add_f32_dpp v92, v92, v92 row_half_mirror row_mask:0xf bank_mask:0xf bound_ctrl:1
	s_nop 1
	v_add_f32_dpp v92, v92, v92 row_mirror row_mask:0xf bank_mask:0xf bound_ctrl:1
	s_nop 0
	v_readlane_b32 s5, v92, 16
	v_readlane_b32 s11, v92, 48
	v_readlane_b32 s6, v92, 0
	v_readlane_b32 s7, v92, 32
	v_mov_b32_e32 v92, s5
	v_mov_b32_e32 v93, s11
	v_pk_add_f32 v[92:93], s[6:7], v[92:93]
	s_lshl_b32 s5, s30, 1
	v_add_f32_e32 v92, v92, v93
	v_fmamk_f32 v92, v92, 0x3a000000, v252
	v_cmp_gt_f32_e32 vcc, s55, v92
	v_mul_f32_e32 v93, 0x4f800000, v92
	s_and_b32 s5, s5, 0xffffe000
	v_cndmask_b32_e32 v92, v92, v93, vcc
	v_sqrt_f32_e32 v93, v92
	s_add_i32 s5, s5, 0
	v_add_u32_e32 v114, -1, v93
	v_fma_f32 v115, -v114, v93, v92
	v_cmp_ge_f32_e64 s[6:7], 0, v115
	v_add_u32_e32 v115, 1, v93
	s_nop 0
	v_cndmask_b32_e64 v114, v93, v114, s[6:7]
	v_fma_f32 v93, -v115, v93, v92
	v_cmp_lt_f32_e64 s[6:7], 0, v93
	s_nop 1
	v_cndmask_b32_e64 v93, v114, v115, s[6:7]
	v_mul_f32_e32 v114, 0x37800000, v93
	v_cndmask_b32_e32 v93, v93, v114, vcc
	v_cmp_class_f32_e32 vcc, v92, v253
	s_nop 1
	v_cndmask_b32_e32 v92, v93, v92, vcc
	v_div_scale_f32 v93, s[6:7], v92, v92, 1.0
	v_rcp_f32_e32 v114, v93
	s_nop 0
	v_fma_f32 v115, -v93, v114, 1.0
	v_fmac_f32_e32 v114, v115, v114
	v_div_scale_f32 v115, vcc, 1.0, v92, 1.0
	v_mul_f32_e32 v124, v115, v114
	v_fma_f32 v125, -v93, v124, v115
	v_fmac_f32_e32 v124, v125, v114
	v_fma_f32 v93, -v93, v124, v115
	v_div_fmas_f32 v93, v93, v114, v124
	v_div_fixup_f32 v114, v93, v92, 1.0
	v_pk_mul_f32 v[128:129], v[120:121], v[114:115] op_sel_hi:[1,0]
	v_pk_mul_f32 v[130:131], v[122:123], v[114:115] op_sel_hi:[1,0]
	v_add_u32_e32 v115, s5, v0
	ds_read_b128 v[120:123], v115
	ds_read_b128 v[124:127], v115 offset:40960
	v_lshl_add_u64 v[92:93], s[34:35], 1, v[2:3]
	v_lshl_add_u64 v[92:93], v[92:93], 0, v[6:7]
	v_pk_mul_f32 v[4:5], v[4:5], v[114:115] op_sel_hi:[1,0]
	s_waitcnt lgkmcnt(0)
	v_pk_fma_f32 v[122:123], v[122:123], v[130:131], v[126:127]
	v_pk_fma_f32 v[120:121], v[120:121], v[128:129], v[124:125]
	v_pk_mul_f32 v[124:125], v[116:117], v[114:115] op_sel_hi:[1,0]
	v_cvt_pk_bf16_f32 v120, v120, v121
	v_cvt_pk_bf16_f32 v121, v122, v123
	global_store_dwordx2 v[92:93], v[120:121], off
	v_pk_mul_f32 v[126:127], v[118:119], v[114:115] op_sel_hi:[1,0]
	ds_read_b128 v[116:119], v115 offset:1024
	ds_read_b128 v[120:123], v115 offset:41984
	s_waitcnt lgkmcnt(0)
	v_pk_fma_f32 v[118:119], v[118:119], v[126:127], v[122:123]
	v_pk_fma_f32 v[116:117], v[116:117], v[124:125], v[120:121]
	v_pk_mul_f32 v[120:121], v[106:107], v[114:115] op_sel_hi:[1,0]
	v_cvt_pk_bf16_f32 v116, v116, v117
	v_cvt_pk_bf16_f32 v117, v118, v119
	global_store_dwordx2 v[92:93], v[116:117], off offset:512
	v_pk_mul_f32 v[122:123], v[108:109], v[114:115] op_sel_hi:[1,0]
	ds_read_b128 v[106:109], v115 offset:2048
	ds_read_b128 v[116:119], v115 offset:43008
	s_waitcnt lgkmcnt(0)
	v_pk_fma_f32 v[108:109], v[108:109], v[122:123], v[118:119]
	v_pk_fma_f32 v[106:107], v[106:107], v[120:121], v[116:117]
	v_pk_mul_f32 v[116:117], v[110:111], v[114:115] op_sel_hi:[1,0]
	v_cvt_pk_bf16_f32 v106, v106, v107
	v_cvt_pk_bf16_f32 v107, v108, v109
	global_store_dwordx2 v[92:93], v[106:107], off offset:1024
	v_pk_mul_f32 v[118:119], v[112:113], v[114:115] op_sel_hi:[1,0]
	ds_read_b128 v[106:109], v115 offset:3072
	ds_read_b128 v[110:113], v115 offset:44032
	s_waitcnt lgkmcnt(0)
; #define GAS __attribute__((address_space(1)))
; #define LAS __attribute__((address_space(3)))
; #define NR_LOAD(dst, k_) do { const GAS v2u* xr_ = (const GAS v2u*)(X + (size_t)(nw + 2048 * (k_)) * D) + F.lane; \
;         _Pragma("unroll") for (int j = 0; j < 8; ++j) dst[j] = __builtin_nontemporal_load(xr_ + 64 * j); } while (0)
; __device__ __forceinline__ void norm_mod_phase2(const Args& a, Frame& F, const float* gain, const float* modl, int sh_off, int sc_off, int nrows, const float* slab_gate) {
;     ...
;     NR_LOAD(r0, 0); NR_LOAD(r1, 1); NR_LOAD(r2, 2); NR_LOAD(r3, 3); NR_LOAD(r4, 4); NR_LOAD(r5, 5); NR_LOAD(r6, 6); NR_LOAD(r7, 7);
;     { const GAS f32x4* g4 = (const GAS f32x4*)gain;
;       for (int q = F.tid; q < 5 * D / 4; q += NWAVES * 64) { const int bq = q >> 9, cq = q & 511; const GAS f32x4* mb4 = (const GAS f32x4*)(modl + (size_t)bq * MOD_LD);
;           ((LAS f32x4*)CA)[q] = g4[cq] * (mb4[sc_off / 4 + cq] + 1.0f); ((LAS f32x4*)CB)[q] = mb4[sh_off / 4 + cq]; } }
;     asm volatile("s_waitcnt lgkmcnt(0)" ::: "memory"); __builtin_amdgcn_s_barrier(); asm volatile("" ::: "memory");
;     NR_FINISH(r0, nw,            (nw) >> 12);
;     NR_FINISH(r1, nw + 2048,     (nw + 2048) >> 12);
;     NR_FINISH(r2, nw + 2 * 2048, (nw + 2 * 2048) >> 12);
;     NR_FINISH(r3, nw + 3 * 2048, (nw + 3 * 2048) >> 12);
;     NR_FINISH(r4, nw + 4 * 2048, (nw + 4 * 2048) >> 12);
;     NR_FINISH(r5, nw + 5 * 2048, (nw + 5 * 2048) >> 12);
;     NR_FINISH(r6, nw + 6 * 2048, (nw + 6 * 2048) >> 12);
;     NR_FINISH(r7, nw + 7 * 2048, (nw + 7 * 2048) >> 12);
	v_pk_fma_f32 v[108:109], v[118:119], v[108:109], v[112:113]
	v_pk_fma_f32 v[106:107], v[116:117], v[106:107], v[110:111]
	v_pk_mul_f32 v[110:111], v[100:101], v[114:115] op_sel_hi:[1,0]
	v_cvt_pk_bf16_f32 v106, v106, v107
	v_cvt_pk_bf16_f32 v107, v108, v109
	global_store_dwordx2 v[92:93], v[106:107], off offset:1536
	v_pk_mul_f32 v[112:113], v[102:103], v[114:115] op_sel_hi:[1,0]
	ds_read_b128 v[100:103], v115 offset:4096
	ds_read_b128 v[106:109], v115 offset:45056
	s_waitcnt lgkmcnt(0)
	v_pk_fma_f32 v[102:103], v[112:113], v[102:103], v[108:109]
	v_pk_fma_f32 v[100:101], v[110:111], v[100:101], v[106:107]
	v_pk_mul_f32 v[106:107], v[98:99], v[114:115] op_sel_hi:[1,0]
	v_cvt_pk_bf16_f32 v100, v100, v101
	v_cvt_pk_bf16_f32 v101, v102, v103
	global_store_dwordx2 v[92:93], v[100:101], off offset:2048
	v_pk_mul_f32 v[108:109], v[104:105], v[114:115] op_sel_hi:[1,0]
	ds_read_b128 v[98:101], v115 offset:5120
	ds_read_b128 v[102:105], v115 offset:46080
	s_waitcnt lgkmcnt(0)
	v_pk_fma_f32 v[100:101], v[108:109], v[100:101], v[104:105]
	v_pk_fma_f32 v[98:99], v[106:107], v[98:99], v[102:103]
	v_pk_mul_f32 v[104:105], v[96:97], v[114:115] op_sel_hi:[1,0]
	v_cvt_pk_bf16_f32 v98, v98, v99
	v_cvt_pk_bf16_f32 v99, v100, v101
	global_store_dwordx2 v[92:93], v[98:99], off offset:2560
	ds_read_b128 v[96:99], v115 offset:6144
	ds_read_b128 v[100:103], v115 offset:47104
	s_waitcnt vmcnt(61)
	v_cvt_f32_f16_sdwa v107, v91 dst_sel:DWORD dst_unused:UNUSED_PAD src0_sel:WORD_1
	v_cvt_f32_f16_e32 v106, v91
	s_waitcnt vmcnt(59)
	v_cvt_f32_f16_sdwa v91, v86 dst_sel:DWORD dst_unused:UNUSED_PAD src0_sel:WORD_1
	s_waitcnt lgkmcnt(0)
	v_pk_fma_f32 v[98:99], v[104:105], v[98:99], v[102:103]
	v_pk_fma_f32 v[4:5], v[4:5], v[96:97], v[100:101]
	v_cvt_f32_f16_sdwa v105, v90 dst_sel:DWORD dst_unused:UNUSED_PAD src0_sel:WORD_1
	v_cvt_pk_bf16_f32 v4, v4, v5
	v_cvt_pk_bf16_f32 v5, v98, v99
	global_store_dwordx2 v[92:93], v[4:5], off offset:3072
	v_pk_mul_f32 v[4:5], v[74:75], v[114:115] op_sel_hi:[1,0]
	v_pk_mul_f32 v[74:75], v[94:95], v[114:115] op_sel_hi:[1,0]
	ds_read_b128 v[94:97], v115 offset:7168
	ds_read_b128 v[98:101], v115 offset:48128
	v_cvt_f32_f16_e32 v104, v90
	v_cvt_f32_f16_sdwa v103, v89 dst_sel:DWORD dst_unused:UNUSED_PAD src0_sel:WORD_1
	v_cvt_f32_f16_e32 v102, v89
	v_cvt_f32_f16_e32 v90, v86
	s_waitcnt lgkmcnt(0)
	v_pk_fma_f32 v[74:75], v[74:75], v[96:97], v[100:101]
	v_cvt_f32_f16_sdwa v101, v88 dst_sel:DWORD dst_unused:UNUSED_PAD src0_sel:WORD_1
	v_pk_fma_f32 v[4:5], v[4:5], v[94:95], v[98:99]
	v_cvt_f32_f16_e32 v100, v88
	v_cvt_pk_bf16_f32 v4, v4, v5
	v_cvt_pk_bf16_f32 v5, v74, v75
	global_store_dwordx2 v[92:93], v[4:5], off offset:3584
	v_cvt_f32_f16_sdwa v93, v87 dst_sel:DWORD dst_unused:UNUSED_PAD src0_sel:WORD_1
	s_waitcnt vmcnt(60)
	v_cvt_f32_f16_sdwa v95, v84 dst_sel:DWORD dst_unused:UNUSED_PAD src0_sel:WORD_1
	v_mov_b32_e32 v74, v105
	v_mov_b32_e32 v75, v101
	v_cvt_f32_f16_e32 v92, v87
	v_cvt_f32_f16_e32 v94, v84
	v_cvt_f32_f16_sdwa v97, v85 dst_sel:DWORD dst_unused:UNUSED_PAD src0_sel:WORD_1
	v_mov_b32_e32 v4, v104
	v_mov_b32_e32 v5, v100
	v_pk_mul_f32 v[74:75], v[74:75], v[74:75]
	v_mov_b32_e32 v88, v107
	v_mov_b32_e32 v89, v103
	v_cvt_f32_f16_e32 v96, v85
	v_pk_fma_f32 v[4:5], v[4:5], v[4:5], v[74:75]
	v_mov_b32_e32 v74, v106
	v_mov_b32_e32 v75, v102
	v_pk_mul_f32 v[88:89], v[88:89], v[88:89]
	v_mov_b32_e32 v86, v91
	v_pk_fma_f32 v[74:75], v[74:75], v[74:75], v[88:89]
	v_mov_b32_e32 v87, v93
	v_mul_f32_e32 v84, v95, v95
	v_pk_add_f32 v[4:5], v[4:5], v[74:75]
	v_mov_b32_e32 v74, v90
	v_mov_b32_e32 v75, v92
	v_pk_mul_f32 v[86:87], v[86:87], v[86:87]
	v_pk_fma_f32 v[88:89], v[94:95], v[94:95], v[84:85] op_sel_hi:[1,1,0]
	v_mul_f32_e32 v84, v97, v97
	v_pk_fma_f32 v[74:75], v[74:75], v[74:75], v[86:87]
	v_pk_fma_f32 v[98:99], v[96:97], v[96:97], v[84:85] op_sel_hi:[1,1,0]
	s_waitcnt vmcnt(59)
	v_cvt_f32_f16_sdwa v85, v82 dst_sel:DWORD dst_unused:UNUSED_PAD src0_sel:WORD_1
	v_cvt_f32_f16_e32 v84, v82
	v_cvt_f32_f16_sdwa v87, v83 dst_sel:DWORD dst_unused:UNUSED_PAD src0_sel:WORD_1
	v_cvt_f32_f16_e32 v86, v83
	v_pk_add_f32 v[4:5], v[4:5], v[4:5] op_sel:[0,1] op_sel_hi:[1,0]
	v_pk_add_f32 v[74:75], v[74:75], v[74:75] op_sel:[0,1] op_sel_hi:[1,0]
	v_pk_mul_f32 v[82:83], v[84:85], v[84:85]
	v_pk_mul_f32 v[108:109], v[86:87], v[86:87]
	v_mov_b32_e32 v5, v82
	v_mov_b32_e32 v75, v83
	v_mov_b32_e32 v89, v108
	v_mov_b32_e32 v99, v109
	v_pk_add_f32 v[4:5], v[4:5], v[74:75]
	v_pk_add_f32 v[74:75], v[88:89], v[98:99]
	s_waitcnt vmcnt(58)
	v_cvt_f32_f16_sdwa v83, v80 dst_sel:DWORD dst_unused:UNUSED_PAD src0_sel:WORD_1
	v_cvt_f32_f16_sdwa v89, v81 dst_sel:DWORD dst_unused:UNUSED_PAD src0_sel:WORD_1
	v_cvt_f32_f16_e32 v82, v80
	v_cvt_f32_f16_e32 v88, v81
	v_pk_add_f32 v[4:5], v[4:5], v[74:75]
	v_mov_b32_e32 v74, v83
	v_mov_b32_e32 v75, v89
	v_pk_add_f32 v[98:99], v[4:5], v[4:5] op_sel:[0,1] op_sel_hi:[1,0]
	v_mov_b32_e32 v4, v82
	v_mov_b32_e32 v5, v88
	v_pk_mul_f32 v[74:75], v[74:75], v[74:75]
	s_waitcnt vmcnt(57)
	v_cvt_f32_f16_sdwa v81, v79 dst_sel:DWORD dst_unused:UNUSED_PAD src0_sel:WORD_1
	v_pk_fma_f32 v[4:5], v[4:5], v[4:5], v[74:75]
	v_cvt_f32_f16_e32 v80, v79
	v_pk_add_f32 v[108:109], v[4:5], v[4:5] op_sel:[0,1] op_sel_hi:[1,0]
	v_cvt_f32_f16_sdwa v5, v78 dst_sel:DWORD dst_unused:UNUSED_PAD src0_sel:WORD_1
	v_cvt_f32_f16_e32 v4, v78
	s_waitcnt vmcnt(56)
; #define GAS __attribute__((address_space(1)))
; #define LAS __attribute__((address_space(3)))
; #define NR_LOAD(dst, k_) do { const GAS v2u* xr_ = (const GAS v2u*)(X + (size_t)(nw + 2048 * (k_)) * D) + F.lane; \
;         _Pragma("unroll") for (int j = 0; j < 8; ++j) dst[j] = __builtin_nontemporal_load(xr_ + 64 * j); } while (0)
; __device__ __forceinline__ void norm_mod_phase2(const Args& a, Frame& F, const float* gain, const float* modl, int sh_off, int sc_off, int nrows, const float* slab_gate) {
;     ...
;     NR_LOAD(r0, 0); NR_LOAD(r1, 1); NR_LOAD(r2, 2); NR_LOAD(r3, 3); NR_LOAD(r4, 4); NR_LOAD(r5, 5); NR_LOAD(r6, 6); NR_LOAD(r7, 7);
;     { const GAS f32x4* g4 = (const GAS f32x4*)gain;
;       for (int q = F.tid; q < 5 * D / 4; q += NWAVES * 64) { const int bq = q >> 9, cq = q & 511; const GAS f32x4* mb4 = (const GAS f32x4*)(modl + (size_t)bq * MOD_LD);
;           ((LAS f32x4*)CA)[q] = g4[cq] * (mb4[sc_off / 4 + cq] + 1.0f); ((LAS f32x4*)CB)[q] = mb4[sh_off / 4 + cq]; } }
;     asm volatile("s_waitcnt lgkmcnt(0)" ::: "memory"); __builtin_amdgcn_s_barrier(); asm volatile("" ::: "memory");
;     NR_FINISH(r0, nw,            (nw) >> 12);
;     NR_FINISH(r1, nw + 2048,     (nw + 2048) >> 12);
;     NR_FINISH(r2, nw + 2 * 2048, (nw + 2 * 2048) >> 12);
;     NR_FINISH(r3, nw + 3 * 2048, (nw + 3 * 2048) >> 12);
;     NR_FINISH(r4, nw + 4 * 2048, (nw + 4 * 2048) >> 12);
;     NR_FINISH(r5, nw + 5 * 2048, (nw + 5 * 2048) >> 12);
;     NR_FINISH(r6, nw + 6 * 2048, (nw + 6 * 2048) >> 12);
;     NR_FINISH(r7, nw + 7 * 2048, (nw + 7 * 2048) >> 12);
	v_cvt_f32_f16_sdwa v79, v77 dst_sel:DWORD dst_unused:UNUSED_PAD src0_sel:WORD_1
	v_cvt_f32_f16_e32 v78, v77
	v_mul_f32_e32 v74, v5, v5
	v_pk_fma_f32 v[110:111], v[4:5], v[4:5], v[74:75] op_sel_hi:[1,1,0]
	v_mul_f32_e32 v74, v81, v81
	v_pk_fma_f32 v[112:113], v[80:81], v[80:81], v[74:75] op_sel_hi:[1,1,0]
	v_cvt_f32_f16_sdwa v75, v76 dst_sel:DWORD dst_unused:UNUSED_PAD src0_sel:WORD_1
	v_cvt_f32_f16_e32 v74, v76
	v_pk_mul_f32 v[114:115], v[78:79], v[78:79]
	v_pk_mul_f32 v[76:77], v[74:75], v[74:75]
	s_nop 0
	v_mov_b32_e32 v99, v76
	v_mov_b32_e32 v109, v77
	v_mov_b32_e32 v111, v114
	v_mov_b32_e32 v113, v115
	v_pk_add_f32 v[76:77], v[98:99], v[108:109]
	v_pk_add_f32 v[98:99], v[110:111], v[112:113]
	s_nop 0
	v_pk_add_f32 v[76:77], v[76:77], v[98:99]
	s_nop 0
	v_add_f32_e32 v76, v76, v77
	s_nop 1
	v_add_f32_dpp v76, v76, v76 quad_perm:[1,0,3,2] row_mask:0xf bank_mask:0xf bound_ctrl:1
	s_nop 1
	v_add_f32_dpp v76, v76, v76 quad_perm:[2,3,0,1] row_mask:0xf bank_mask:0xf bound_ctrl:1
	s_nop 1
	v_add_f32_dpp v76, v76, v76 row_half_mirror row_mask:0xf bank_mask:0xf bound_ctrl:1
	s_nop 1
	v_add_f32_dpp v76, v76, v76 row_mirror row_mask:0xf bank_mask:0xf bound_ctrl:1
	s_nop 0
	v_readlane_b32 s5, v76, 16
	v_readlane_b32 s11, v76, 48
	v_readlane_b32 s6, v76, 0
	v_readlane_b32 s7, v76, 32
	v_mov_b32_e32 v76, s5
	v_mov_b32_e32 v77, s11
	v_pk_add_f32 v[76:77], s[6:7], v[76:77]
	s_lshl_b32 s5, s26, 1
	v_add_f32_e32 v76, v76, v77
	v_fmamk_f32 v76, v76, 0x3a000000, v252
	v_cmp_gt_f32_e32 vcc, s55, v76
	v_mul_f32_e32 v77, 0x4f800000, v76
	s_and_b32 s5, s5, 0xffffe000
	v_cndmask_b32_e32 v76, v76, v77, vcc
	v_sqrt_f32_e32 v77, v76
	s_add_i32 s5, s5, 0
	v_add_u32_e32 v98, -1, v77
	v_fma_f32 v99, -v98, v77, v76
	v_cmp_ge_f32_e64 s[6:7], 0, v99
	v_add_u32_e32 v99, 1, v77
	s_nop 0
	v_cndmask_b32_e64 v98, v77, v98, s[6:7]
	v_fma_f32 v77, -v99, v77, v76
	v_cmp_lt_f32_e64 s[6:7], 0, v77
	s_nop 1
	v_cndmask_b32_e64 v77, v98, v99, s[6:7]
	v_mul_f32_e32 v98, 0x37800000, v77
	v_cndmask_b32_e32 v77, v77, v98, vcc
	v_cmp_class_f32_e32 vcc, v76, v253
	s_nop 1
	v_cndmask_b32_e32 v76, v77, v76, vcc
	v_div_scale_f32 v77, s[6:7], v76, v76, 1.0
	v_rcp_f32_e32 v98, v77
	s_nop 0
	v_fma_f32 v99, -v77, v98, 1.0
	v_fmac_f32_e32 v98, v99, v98
	v_div_scale_f32 v99, vcc, 1.0, v76, 1.0
	v_mul_f32_e32 v108, v99, v98
	v_fma_f32 v109, -v77, v108, v99
	v_fmac_f32_e32 v108, v109, v98
	v_fma_f32 v77, -v77, v108, v99
	v_div_fmas_f32 v77, v77, v98, v108
	v_div_fixup_f32 v98, v77, v76, 1.0
	v_pk_mul_f32 v[112:113], v[104:105], v[98:99] op_sel_hi:[1,0]
	v_pk_mul_f32 v[114:115], v[106:107], v[98:99] op_sel_hi:[1,0]
	v_add_u32_e32 v99, s5, v0
	ds_read_b128 v[104:107], v99
	ds_read_b128 v[108:111], v99 offset:40960
	v_lshl_add_u64 v[76:77], s[28:29], 1, v[2:3]
	v_lshl_add_u64 v[76:77], v[76:77], 0, v[6:7]
	v_pk_mul_f32 v[4:5], v[4:5], v[98:99] op_sel_hi:[1,0]
	s_waitcnt lgkmcnt(0)
	v_pk_fma_f32 v[106:107], v[106:107], v[114:115], v[110:111]
	v_pk_fma_f32 v[104:105], v[104:105], v[112:113], v[108:109]
	v_pk_mul_f32 v[108:109], v[100:101], v[98:99] op_sel_hi:[1,0]
	v_cvt_pk_bf16_f32 v104, v104, v105
	v_cvt_pk_bf16_f32 v105, v106, v107
	global_store_dwordx2 v[76:77], v[104:105], off
	v_pk_mul_f32 v[110:111], v[102:103], v[98:99] op_sel_hi:[1,0]
	ds_read_b128 v[100:103], v99 offset:1024
	ds_read_b128 v[104:107], v99 offset:41984
	s_waitcnt lgkmcnt(0)
	v_pk_fma_f32 v[102:103], v[102:103], v[110:111], v[106:107]
	v_pk_fma_f32 v[100:101], v[100:101], v[108:109], v[104:105]
	v_pk_mul_f32 v[104:105], v[90:91], v[98:99] op_sel_hi:[1,0]
	v_cvt_pk_bf16_f32 v100, v100, v101
	v_cvt_pk_bf16_f32 v101, v102, v103
	global_store_dwordx2 v[76:77], v[100:101], off offset:512
	v_pk_mul_f32 v[106:107], v[92:93], v[98:99] op_sel_hi:[1,0]
	ds_read_b128 v[90:93], v99 offset:2048
	ds_read_b128 v[100:103], v99 offset:43008
	s_waitcnt lgkmcnt(0)
	v_pk_fma_f32 v[92:93], v[92:93], v[106:107], v[102:103]
	v_pk_fma_f32 v[90:91], v[90:91], v[104:105], v[100:101]
	v_pk_mul_f32 v[100:101], v[94:95], v[98:99] op_sel_hi:[1,0]
	v_cvt_pk_bf16_f32 v90, v90, v91
	v_cvt_pk_bf16_f32 v91, v92, v93
	global_store_dwordx2 v[76:77], v[90:91], off offset:1024
	v_pk_mul_f32 v[102:103], v[96:97], v[98:99] op_sel_hi:[1,0]
	ds_read_b128 v[90:93], v99 offset:3072
	ds_read_b128 v[94:97], v99 offset:44032
	s_waitcnt lgkmcnt(0)
	v_pk_fma_f32 v[92:93], v[102:103], v[92:93], v[96:97]
	v_pk_fma_f32 v[90:91], v[100:101], v[90:91], v[94:95]
	v_pk_mul_f32 v[94:95], v[84:85], v[98:99] op_sel_hi:[1,0]
	v_cvt_pk_bf16_f32 v90, v90, v91
	v_cvt_pk_bf16_f32 v91, v92, v93
	global_store_dwordx2 v[76:77], v[90:91], off offset:1536
	v_pk_mul_f32 v[96:97], v[86:87], v[98:99] op_sel_hi:[1,0]
	ds_read_b128 v[84:87], v99 offset:4096
	ds_read_b128 v[90:93], v99 offset:45056
	s_waitcnt lgkmcnt(0)
	v_pk_fma_f32 v[86:87], v[96:97], v[86:87], v[92:93]
	v_pk_fma_f32 v[84:85], v[94:95], v[84:85], v[90:91]
	v_pk_mul_f32 v[90:91], v[82:83], v[98:99] op_sel_hi:[1,0]
	v_cvt_pk_bf16_f32 v84, v84, v85
	v_cvt_pk_bf16_f32 v85, v86, v87
	global_store_dwordx2 v[76:77], v[84:85], off offset:2048
	v_pk_mul_f32 v[92:93], v[88:89], v[98:99] op_sel_hi:[1,0]
	ds_read_b128 v[82:85], v99 offset:5120
	ds_read_b128 v[86:89], v99 offset:46080
	s_waitcnt lgkmcnt(0)
	v_pk_fma_f32 v[84:85], v[92:93], v[84:85], v[88:89]
	v_pk_fma_f32 v[82:83], v[90:91], v[82:83], v[86:87]
	v_pk_mul_f32 v[88:89], v[80:81], v[98:99] op_sel_hi:[1,0]
	v_cvt_pk_bf16_f32 v82, v82, v83
	v_cvt_pk_bf16_f32 v83, v84, v85
	global_store_dwordx2 v[76:77], v[82:83], off offset:2560
	ds_read_b128 v[80:83], v99 offset:6144
	ds_read_b128 v[84:87], v99 offset:47104
	s_waitcnt vmcnt(61)
; #define GAS __attribute__((address_space(1)))
; #define LAS __attribute__((address_space(3)))
; #define NR_LOAD(dst, k_) do { const GAS v2u* xr_ = (const GAS v2u*)(X + (size_t)(nw + 2048 * (k_)) * D) + F.lane; \
;         _Pragma("unroll") for (int j = 0; j < 8; ++j) dst[j] = __builtin_nontemporal_load(xr_ + 64 * j); } while (0)
; __device__ __forceinline__ void norm_mod_phase2(const Args& a, Frame& F, const float* gain, const float* modl, int sh_off, int sc_off, int nrows, const float* slab_gate) {
;     ...
;     NR_LOAD(r0, 0); NR_LOAD(r1, 1); NR_LOAD(r2, 2); NR_LOAD(r3, 3); NR_LOAD(r4, 4); NR_LOAD(r5, 5); NR_LOAD(r6, 6); NR_LOAD(r7, 7);
;     { const GAS f32x4* g4 = (const GAS f32x4*)gain;
;       for (int q = F.tid; q < 5 * D / 4; q += NWAVES * 64) { const int bq = q >> 9, cq = q & 511; const GAS f32x4* mb4 = (const GAS f32x4*)(modl + (size_t)bq * MOD_LD);
;           ((LAS f32x4*)CA)[q] = g4[cq] * (mb4[sc_off / 4 + cq] + 1.0f); ((LAS f32x4*)CB)[q] = mb4[sh_off / 4 + cq]; } }
;     asm volatile("s_waitcnt lgkmcnt(0)" ::: "memory"); __builtin_amdgcn_s_barrier(); asm volatile("" ::: "memory");
;     NR_FINISH(r0, nw,            (nw) >> 12);
;     NR_FINISH(r1, nw + 2048,     (nw + 2048) >> 12);
;     NR_FINISH(r2, nw + 2 * 2048, (nw + 2 * 2048) >> 12);
;     NR_FINISH(r3, nw + 3 * 2048, (nw + 3 * 2048) >> 12);
;     NR_FINISH(r4, nw + 4 * 2048, (nw + 4 * 2048) >> 12);
;     NR_FINISH(r5, nw + 5 * 2048, (nw + 5 * 2048) >> 12);
;     NR_FINISH(r6, nw + 6 * 2048, (nw + 6 * 2048) >> 12);
;     NR_FINISH(r7, nw + 7 * 2048, (nw + 7 * 2048) >> 12);
	v_cvt_f32_f16_sdwa v91, v73 dst_sel:DWORD dst_unused:UNUSED_PAD src0_sel:WORD_1
	v_cvt_f32_f16_e32 v90, v73
	s_waitcnt lgkmcnt(0)
	v_pk_fma_f32 v[82:83], v[88:89], v[82:83], v[86:87]
	v_pk_fma_f32 v[4:5], v[4:5], v[80:81], v[84:85]
	v_cvt_f32_f16_sdwa v89, v72 dst_sel:DWORD dst_unused:UNUSED_PAD src0_sel:WORD_1
	v_cvt_pk_bf16_f32 v4, v4, v5
	v_cvt_pk_bf16_f32 v5, v82, v83
	global_store_dwordx2 v[76:77], v[4:5], off offset:3072
	v_pk_mul_f32 v[4:5], v[74:75], v[98:99] op_sel_hi:[1,0]
	v_pk_mul_f32 v[74:75], v[78:79], v[98:99] op_sel_hi:[1,0]
	ds_read_b128 v[78:81], v99 offset:7168
	ds_read_b128 v[82:85], v99 offset:48128
	v_cvt_f32_f16_e32 v88, v72
	s_waitcnt vmcnt(61)
	v_cvt_f32_f16_sdwa v87, v71 dst_sel:DWORD dst_unused:UNUSED_PAD src0_sel:WORD_1
	v_cvt_f32_f16_e32 v86, v71
	v_mov_b32_e32 v72, v91
	s_waitcnt lgkmcnt(0)
	v_pk_fma_f32 v[74:75], v[74:75], v[80:81], v[84:85]
	v_cvt_f32_f16_sdwa v85, v70 dst_sel:DWORD dst_unused:UNUSED_PAD src0_sel:WORD_1
	v_cvt_f32_f16_e32 v84, v70
	v_pk_fma_f32 v[4:5], v[4:5], v[78:79], v[82:83]
	v_mov_b32_e32 v70, v89
	v_cvt_pk_bf16_f32 v4, v4, v5
	v_cvt_pk_bf16_f32 v5, v74, v75
	global_store_dwordx2 v[76:77], v[4:5], off offset:3584
	v_mov_b32_e32 v71, v85
	s_waitcnt vmcnt(61)
	v_cvt_f32_f16_sdwa v75, v68 dst_sel:DWORD dst_unused:UNUSED_PAD src0_sel:WORD_1
	v_cvt_f32_f16_sdwa v77, v69 dst_sel:DWORD dst_unused:UNUSED_PAD src0_sel:WORD_1
	v_mov_b32_e32 v4, v88
	v_mov_b32_e32 v5, v84
	v_pk_mul_f32 v[70:71], v[70:71], v[70:71]
	v_mov_b32_e32 v73, v87
	v_cvt_f32_f16_e32 v74, v68
	v_cvt_f32_f16_e32 v76, v69
	s_waitcnt vmcnt(60)
	v_cvt_f32_f16_sdwa v79, v66 dst_sel:DWORD dst_unused:UNUSED_PAD src0_sel:WORD_1
	v_pk_fma_f32 v[4:5], v[4:5], v[4:5], v[70:71]
	v_mov_b32_e32 v70, v90
	v_mov_b32_e32 v71, v86
	v_pk_mul_f32 v[72:73], v[72:73], v[72:73]
	v_cvt_f32_f16_e32 v78, v66
	v_cvt_f32_f16_sdwa v81, v67 dst_sel:DWORD dst_unused:UNUSED_PAD src0_sel:WORD_1
	v_pk_fma_f32 v[70:71], v[70:71], v[70:71], v[72:73]
	v_cvt_f32_f16_e32 v80, v67
	v_pk_add_f32 v[4:5], v[4:5], v[70:71]
	v_mov_b32_e32 v70, v75
	v_mov_b32_e32 v71, v77
	v_mov_b32_e32 v68, v74
	v_mov_b32_e32 v69, v76
	v_pk_mul_f32 v[70:71], v[70:71], v[70:71]
	v_mul_f32_e32 v66, v79, v79
	v_pk_fma_f32 v[68:69], v[68:69], v[68:69], v[70:71]
	v_pk_fma_f32 v[72:73], v[78:79], v[78:79], v[66:67] op_sel_hi:[1,1,0]
	v_mul_f32_e32 v66, v81, v81
	v_pk_add_f32 v[70:71], v[68:69], v[68:69] op_sel:[0,1] op_sel_hi:[1,0]
	v_pk_fma_f32 v[82:83], v[80:81], v[80:81], v[66:67] op_sel_hi:[1,1,0]
	s_waitcnt vmcnt(59)
	v_cvt_f32_f16_sdwa v67, v64 dst_sel:DWORD dst_unused:UNUSED_PAD src0_sel:WORD_1
	v_cvt_f32_f16_e32 v66, v64
	v_cvt_f32_f16_sdwa v69, v65 dst_sel:DWORD dst_unused:UNUSED_PAD src0_sel:WORD_1
	v_cvt_f32_f16_e32 v68, v65
	v_pk_add_f32 v[4:5], v[4:5], v[4:5] op_sel:[0,1] op_sel_hi:[1,0]
	v_pk_mul_f32 v[64:65], v[66:67], v[66:67]
	v_pk_mul_f32 v[92:93], v[68:69], v[68:69]
	v_mov_b32_e32 v5, v64
	v_mov_b32_e32 v71, v65
	v_mov_b32_e32 v73, v92
	v_mov_b32_e32 v83, v93
	v_pk_add_f32 v[4:5], v[4:5], v[70:71]
	v_pk_add_f32 v[64:65], v[72:73], v[82:83]
	s_waitcnt vmcnt(58)
	v_cvt_f32_f16_sdwa v71, v62 dst_sel:DWORD dst_unused:UNUSED_PAD src0_sel:WORD_1
	v_cvt_f32_f16_sdwa v73, v63 dst_sel:DWORD dst_unused:UNUSED_PAD src0_sel:WORD_1
	v_cvt_f32_f16_e32 v70, v62
	v_cvt_f32_f16_e32 v72, v63
	v_pk_add_f32 v[4:5], v[4:5], v[64:65]
	v_mov_b32_e32 v62, v71
	v_mov_b32_e32 v63, v73
	v_pk_add_f32 v[82:83], v[4:5], v[4:5] op_sel:[0,1] op_sel_hi:[1,0]
	v_mov_b32_e32 v4, v70
	v_mov_b32_e32 v5, v72
	v_pk_mul_f32 v[62:63], v[62:63], v[62:63]
	s_waitcnt vmcnt(56)
	v_cvt_f32_f16_sdwa v65, v59 dst_sel:DWORD dst_unused:UNUSED_PAD src0_sel:WORD_1
	v_pk_fma_f32 v[4:5], v[4:5], v[4:5], v[62:63]
	v_cvt_f32_f16_sdwa v63, v61 dst_sel:DWORD dst_unused:UNUSED_PAD src0_sel:WORD_1
	v_pk_add_f32 v[92:93], v[4:5], v[4:5] op_sel:[0,1] op_sel_hi:[1,0]
	v_cvt_f32_f16_sdwa v5, v60 dst_sel:DWORD dst_unused:UNUSED_PAD src0_sel:WORD_1
	v_cvt_f32_f16_e32 v4, v60
	v_cvt_f32_f16_e32 v62, v61
	v_cvt_f32_f16_e32 v64, v59
	v_mul_f32_e32 v60, v5, v5
	v_pk_fma_f32 v[94:95], v[4:5], v[4:5], v[60:61] op_sel_hi:[1,1,0]
	v_mul_f32_e32 v60, v63, v63
	v_pk_fma_f32 v[96:97], v[62:63], v[62:63], v[60:61] op_sel_hi:[1,1,0]
	v_cvt_f32_f16_sdwa v61, v58 dst_sel:DWORD dst_unused:UNUSED_PAD src0_sel:WORD_1
	v_cvt_f32_f16_e32 v60, v58
	v_pk_mul_f32 v[98:99], v[64:65], v[64:65]
	v_pk_mul_f32 v[58:59], v[60:61], v[60:61]
	s_nop 0
	v_mov_b32_e32 v83, v58
	v_mov_b32_e32 v93, v59
	v_mov_b32_e32 v95, v98
	v_mov_b32_e32 v97, v99
	v_pk_add_f32 v[58:59], v[82:83], v[92:93]
	v_pk_add_f32 v[82:83], v[94:95], v[96:97]
	s_nop 0
	v_pk_add_f32 v[58:59], v[58:59], v[82:83]
	s_nop 0
	v_add_f32_e32 v58, v58, v59
	s_nop 1
	v_add_f32_dpp v58, v58, v58 quad_perm:[1,0,3,2] row_mask:0xf bank_mask:0xf bound_ctrl:1
	s_nop 1
	v_add_f32_dpp v58, v58, v58 quad_perm:[2,3,0,1] row_mask:0xf bank_mask:0xf bound_ctrl:1
	s_nop 1
	v_add_f32_dpp v58, v58, v58 row_half_mirror row_mask:0xf bank_mask:0xf bound_ctrl:1
	s_nop 1
	v_add_f32_dpp v58, v58, v58 row_mirror row_mask:0xf bank_mask:0xf bound_ctrl:1
	s_nop 0
	v_readlane_b32 s5, v58, 16
	v_readlane_b32 s11, v58, 48
	v_readlane_b32 s6, v58, 0
	v_readlane_b32 s7, v58, 32
	v_mov_b32_e32 v58, s5
	v_mov_b32_e32 v59, s11
	v_pk_add_f32 v[58:59], s[6:7], v[58:59]
	s_lshl_b32 s5, s22, 1
	v_add_f32_e32 v58, v58, v59
	v_fmamk_f32 v58, v58, 0x3a000000, v252
	v_cmp_gt_f32_e32 vcc, s55, v58
	v_mul_f32_e32 v59, 0x4f800000, v58
	s_and_b32 s5, s5, 0xffffe000
	v_cndmask_b32_e32 v58, v58, v59, vcc
	v_sqrt_f32_e32 v59, v58
	s_add_i32 s5, s5, 0
	v_add_u32_e32 v82, -1, v59
	v_fma_f32 v83, -v82, v59, v58
	v_cmp_ge_f32_e64 s[6:7], 0, v83
	v_add_u32_e32 v83, 1, v59
	s_nop 0
	v_cndmask_b32_e64 v82, v59, v82, s[6:7]
	v_fma_f32 v59, -v83, v59, v58
	v_cmp_lt_f32_e64 s[6:7], 0, v59
	s_nop 1
	v_cndmask_b32_e64 v59, v82, v83, s[6:7]
	v_mul_f32_e32 v82, 0x37800000, v59
	v_cndmask_b32_e32 v59, v59, v82, vcc
	v_cmp_class_f32_e32 vcc, v58, v253
	s_nop 1
	v_cndmask_b32_e32 v58, v59, v58, vcc
	v_div_scale_f32 v59, s[6:7], v58, v58, 1.0
	v_rcp_f32_e32 v82, v59
	s_nop 0
	v_fma_f32 v83, -v59, v82, 1.0
	v_fmac_f32_e32 v82, v83, v82
	v_div_scale_f32 v83, vcc, 1.0, v58, 1.0
	v_mul_f32_e32 v92, v83, v82
	v_fma_f32 v93, -v59, v92, v83
	v_fmac_f32_e32 v92, v93, v82
	v_fma_f32 v59, -v59, v92, v83
	v_div_fmas_f32 v59, v59, v82, v92
	v_div_fixup_f32 v82, v59, v58, 1.0
	v_pk_mul_f32 v[96:97], v[88:89], v[82:83] op_sel_hi:[1,0]
	v_pk_mul_f32 v[98:99], v[90:91], v[82:83] op_sel_hi:[1,0]
	v_add_u32_e32 v83, s5, v0
	ds_read_b128 v[88:91], v83
	ds_read_b128 v[92:95], v83 offset:40960
	v_lshl_add_u64 v[58:59], s[24:25], 1, v[2:3]
	v_lshl_add_u64 v[58:59], v[58:59], 0, v[6:7]
	v_pk_mul_f32 v[4:5], v[4:5], v[82:83] op_sel_hi:[1,0]
	v_pk_mul_f32 v[62:63], v[62:63], v[82:83] op_sel_hi:[1,0]
	s_waitcnt lgkmcnt(0)
	v_pk_fma_f32 v[90:91], v[90:91], v[98:99], v[94:95]
	v_pk_fma_f32 v[88:89], v[88:89], v[96:97], v[92:93]
	v_pk_mul_f32 v[92:93], v[84:85], v[82:83] op_sel_hi:[1,0]
	v_cvt_pk_bf16_f32 v88, v88, v89
	v_cvt_pk_bf16_f32 v89, v90, v91
	global_store_dwordx2 v[58:59], v[88:89], off
	v_pk_mul_f32 v[94:95], v[86:87], v[82:83] op_sel_hi:[1,0]
	ds_read_b128 v[84:87], v83 offset:1024
	ds_read_b128 v[88:91], v83 offset:41984
	s_waitcnt lgkmcnt(0)
	v_pk_fma_f32 v[86:87], v[86:87], v[94:95], v[90:91]
	v_pk_fma_f32 v[84:85], v[84:85], v[92:93], v[88:89]
	v_pk_mul_f32 v[88:89], v[74:75], v[82:83] op_sel_hi:[1,0]
	v_cvt_pk_bf16_f32 v84, v84, v85
	v_cvt_pk_bf16_f32 v85, v86, v87
	global_store_dwordx2 v[58:59], v[84:85], off offset:512
	v_pk_mul_f32 v[90:91], v[76:77], v[82:83] op_sel_hi:[1,0]
	ds_read_b128 v[74:77], v83 offset:2048
	ds_read_b128 v[84:87], v83 offset:43008
	s_waitcnt lgkmcnt(0)
	v_pk_fma_f32 v[76:77], v[76:77], v[90:91], v[86:87]
	v_pk_fma_f32 v[74:75], v[74:75], v[88:89], v[84:85]
	v_pk_mul_f32 v[84:85], v[78:79], v[82:83] op_sel_hi:[1,0]
	v_cvt_pk_bf16_f32 v74, v74, v75
	v_cvt_pk_bf16_f32 v75, v76, v77
	global_store_dwordx2 v[58:59], v[74:75], off offset:1024
	v_pk_mul_f32 v[86:87], v[80:81], v[82:83] op_sel_hi:[1,0]
	ds_read_b128 v[74:77], v83 offset:3072
	ds_read_b128 v[78:81], v83 offset:44032
	s_waitcnt lgkmcnt(0)
	v_pk_fma_f32 v[76:77], v[86:87], v[76:77], v[80:81]
	v_pk_fma_f32 v[74:75], v[84:85], v[74:75], v[78:79]
	v_pk_mul_f32 v[78:79], v[66:67], v[82:83] op_sel_hi:[1,0]
	v_cvt_pk_bf16_f32 v74, v74, v75
	v_cvt_pk_bf16_f32 v75, v76, v77
	global_store_dwordx2 v[58:59], v[74:75], off offset:1536
	v_pk_mul_f32 v[80:81], v[68:69], v[82:83] op_sel_hi:[1,0]
	ds_read_b128 v[66:69], v83 offset:4096
	ds_read_b128 v[74:77], v83 offset:45056
	s_waitcnt lgkmcnt(0)
	v_pk_fma_f32 v[68:69], v[80:81], v[68:69], v[76:77]
	v_pk_fma_f32 v[66:67], v[78:79], v[66:67], v[74:75]
	v_pk_mul_f32 v[74:75], v[70:71], v[82:83] op_sel_hi:[1,0]
	v_cvt_pk_bf16_f32 v66, v66, v67
	v_cvt_pk_bf16_f32 v67, v68, v69
	global_store_dwordx2 v[58:59], v[66:67], off offset:2048
	v_pk_mul_f32 v[76:77], v[72:73], v[82:83] op_sel_hi:[1,0]
	ds_read_b128 v[66:69], v83 offset:5120
	ds_read_b128 v[70:73], v83 offset:46080
	s_waitcnt lgkmcnt(0)
	v_pk_fma_f32 v[68:69], v[76:77], v[68:69], v[72:73]
	v_pk_fma_f32 v[66:67], v[74:75], v[66:67], v[70:71]
	s_waitcnt vmcnt(60)
	v_cvt_f32_f16_sdwa v75, v57 dst_sel:DWORD dst_unused:UNUSED_PAD src0_sel:WORD_1
	v_cvt_pk_bf16_f32 v66, v66, v67
	v_cvt_pk_bf16_f32 v67, v68, v69
	global_store_dwordx2 v[58:59], v[66:67], off offset:2560
	ds_read_b128 v[66:69], v83 offset:6144
	ds_read_b128 v[70:73], v83 offset:47104
	v_cvt_f32_f16_e32 v74, v57
	s_waitcnt lgkmcnt(0)
	v_pk_fma_f32 v[62:63], v[62:63], v[68:69], v[72:73]
	v_pk_fma_f32 v[4:5], v[4:5], v[66:67], v[70:71]
	v_pk_mul_f32 v[68:69], v[64:65], v[82:83] op_sel_hi:[1,0]
	v_cvt_pk_bf16_f32 v4, v4, v5
	v_cvt_pk_bf16_f32 v5, v62, v63
	global_store_dwordx2 v[58:59], v[4:5], off offset:3072
	v_pk_mul_f32 v[4:5], v[60:61], v[82:83] op_sel_hi:[1,0]
	ds_read_b128 v[60:63], v83 offset:7168
	ds_read_b128 v[64:67], v83 offset:48128
	v_cvt_f32_f16_sdwa v73, v56 dst_sel:DWORD dst_unused:UNUSED_PAD src0_sel:WORD_1
	v_cvt_f32_f16_e32 v72, v56
	s_waitcnt vmcnt(61)
	v_cvt_f32_f16_sdwa v71, v55 dst_sel:DWORD dst_unused:UNUSED_PAD src0_sel:WORD_1
	v_cvt_f32_f16_e32 v70, v55
	s_waitcnt lgkmcnt(0)
	v_pk_fma_f32 v[62:63], v[68:69], v[62:63], v[66:67]
	v_cvt_f32_f16_sdwa v69, v54 dst_sel:DWORD dst_unused:UNUSED_PAD src0_sel:WORD_1
	v_cvt_f32_f16_e32 v68, v54
	v_pk_fma_f32 v[4:5], v[4:5], v[60:61], v[64:65]
	v_mov_b32_e32 v54, v73
	v_cvt_pk_bf16_f32 v4, v4, v5
	v_cvt_pk_bf16_f32 v5, v62, v63
	global_store_dwordx2 v[58:59], v[4:5], off offset:3584
	v_mov_b32_e32 v55, v69
	s_waitcnt vmcnt(61)
	v_cvt_f32_f16_sdwa v59, v52 dst_sel:DWORD dst_unused:UNUSED_PAD src0_sel:WORD_1
	v_cvt_f32_f16_sdwa v61, v53 dst_sel:DWORD dst_unused:UNUSED_PAD src0_sel:WORD_1
	v_mov_b32_e32 v4, v72
	v_mov_b32_e32 v5, v68
	v_pk_mul_f32 v[54:55], v[54:55], v[54:55]
	v_mov_b32_e32 v56, v75
	v_mov_b32_e32 v57, v71
	v_cvt_f32_f16_e32 v58, v52
	v_cvt_f32_f16_e32 v60, v53
	s_waitcnt vmcnt(60)
	v_cvt_f32_f16_sdwa v63, v50 dst_sel:DWORD dst_unused:UNUSED_PAD src0_sel:WORD_1
	v_pk_fma_f32 v[4:5], v[4:5], v[4:5], v[54:55]
	v_mov_b32_e32 v54, v74
	v_mov_b32_e32 v55, v70
	v_pk_mul_f32 v[56:57], v[56:57], v[56:57]
	v_cvt_f32_f16_e32 v62, v50
	v_cvt_f32_f16_sdwa v65, v51 dst_sel:DWORD dst_unused:UNUSED_PAD src0_sel:WORD_1
	v_pk_fma_f32 v[54:55], v[54:55], v[54:55], v[56:57]
	v_cvt_f32_f16_e32 v64, v51
	v_pk_add_f32 v[4:5], v[4:5], v[54:55]
	v_mov_b32_e32 v54, v59
	v_mov_b32_e32 v55, v61
	v_mov_b32_e32 v52, v58
	v_mov_b32_e32 v53, v60
	v_pk_mul_f32 v[54:55], v[54:55], v[54:55]
	v_mul_f32_e32 v50, v63, v63
	v_pk_fma_f32 v[52:53], v[52:53], v[52:53], v[54:55]
	v_pk_fma_f32 v[56:57], v[62:63], v[62:63], v[50:51] op_sel_hi:[1,1,0]
	v_mul_f32_e32 v50, v65, v65
	v_pk_add_f32 v[54:55], v[52:53], v[52:53] op_sel:[0,1] op_sel_hi:[1,0]
	v_pk_fma_f32 v[66:67], v[64:65], v[64:65], v[50:51] op_sel_hi:[1,1,0]
	s_waitcnt vmcnt(59)
	v_cvt_f32_f16_sdwa v51, v48 dst_sel:DWORD dst_unused:UNUSED_PAD src0_sel:WORD_1
	v_cvt_f32_f16_e32 v50, v48
	v_cvt_f32_f16_sdwa v53, v49 dst_sel:DWORD dst_unused:UNUSED_PAD src0_sel:WORD_1
	v_cvt_f32_f16_e32 v52, v49
	v_pk_add_f32 v[4:5], v[4:5], v[4:5] op_sel:[0,1] op_sel_hi:[1,0]
	v_pk_mul_f32 v[48:49], v[50:51], v[50:51]
	v_pk_mul_f32 v[76:77], v[52:53], v[52:53]
	v_mov_b32_e32 v5, v48
	v_mov_b32_e32 v55, v49
	v_mov_b32_e32 v57, v76
	v_mov_b32_e32 v67, v77
	v_pk_add_f32 v[4:5], v[4:5], v[54:55]
	v_pk_add_f32 v[48:49], v[56:57], v[66:67]
	s_waitcnt vmcnt(58)
	v_cvt_f32_f16_sdwa v55, v46 dst_sel:DWORD dst_unused:UNUSED_PAD src0_sel:WORD_1
	v_cvt_f32_f16_sdwa v57, v47 dst_sel:DWORD dst_unused:UNUSED_PAD src0_sel:WORD_1
	v_cvt_f32_f16_e32 v54, v46
	v_cvt_f32_f16_e32 v56, v47
	v_pk_add_f32 v[4:5], v[4:5], v[48:49]
	v_mov_b32_e32 v46, v55
	v_mov_b32_e32 v47, v57
	v_pk_add_f32 v[66:67], v[4:5], v[4:5] op_sel:[0,1] op_sel_hi:[1,0]
	v_mov_b32_e32 v4, v54
	v_mov_b32_e32 v5, v56
	v_pk_mul_f32 v[46:47], v[46:47], v[46:47]
	s_waitcnt vmcnt(56)
	v_cvt_f32_f16_sdwa v49, v43 dst_sel:DWORD dst_unused:UNUSED_PAD src0_sel:WORD_1
	v_pk_fma_f32 v[4:5], v[4:5], v[4:5], v[46:47]
	v_cvt_f32_f16_sdwa v47, v45 dst_sel:DWORD dst_unused:UNUSED_PAD src0_sel:WORD_1
	v_pk_add_f32 v[76:77], v[4:5], v[4:5] op_sel:[0,1] op_sel_hi:[1,0]
	v_cvt_f32_f16_sdwa v5, v44 dst_sel:DWORD dst_unused:UNUSED_PAD src0_sel:WORD_1
	v_cvt_f32_f16_e32 v4, v44
	v_cvt_f32_f16_e32 v46, v45
	v_cvt_f32_f16_e32 v48, v43
	v_mul_f32_e32 v44, v5, v5
	v_pk_fma_f32 v[78:79], v[4:5], v[4:5], v[44:45] op_sel_hi:[1,1,0]
	v_mul_f32_e32 v44, v47, v47
	v_pk_fma_f32 v[80:81], v[46:47], v[46:47], v[44:45] op_sel_hi:[1,1,0]
	v_cvt_f32_f16_sdwa v45, v42 dst_sel:DWORD dst_unused:UNUSED_PAD src0_sel:WORD_1
	v_cvt_f32_f16_e32 v44, v42
	v_pk_mul_f32 v[82:83], v[48:49], v[48:49]
	v_pk_mul_f32 v[42:43], v[44:45], v[44:45]
	s_nop 0
	v_mov_b32_e32 v67, v42
	v_mov_b32_e32 v77, v43
	v_mov_b32_e32 v79, v82
	v_mov_b32_e32 v81, v83
	v_pk_add_f32 v[42:43], v[66:67], v[76:77]
	v_pk_add_f32 v[66:67], v[78:79], v[80:81]
	s_nop 0
	v_pk_add_f32 v[42:43], v[42:43], v[66:67]
	s_nop 0
	v_add_f32_e32 v42, v42, v43
	s_nop 1
	v_add_f32_dpp v42, v42, v42 quad_perm:[1,0,3,2] row_mask:0xf bank_mask:0xf bound_ctrl:1
	s_nop 1
	v_add_f32_dpp v42, v42, v42 quad_perm:[2,3,0,1] row_mask:0xf bank_mask:0xf bound_ctrl:1
	s_nop 1
	v_add_f32_dpp v42, v42, v42 row_half_mirror row_mask:0xf bank_mask:0xf bound_ctrl:1
	s_nop 1
	v_add_f32_dpp v42, v42, v42 row_mirror row_mask:0xf bank_mask:0xf bound_ctrl:1
	s_nop 0
	v_readlane_b32 s5, v42, 16
	v_readlane_b32 s11, v42, 48
	v_readlane_b32 s6, v42, 0
	v_readlane_b32 s7, v42, 32
	v_mov_b32_e32 v42, s5
	v_mov_b32_e32 v43, s11
	v_pk_add_f32 v[42:43], s[6:7], v[42:43]
	s_lshl_b32 s5, s18, 1
	v_add_f32_e32 v42, v42, v43
	v_fmamk_f32 v42, v42, 0x3a000000, v252
	v_cmp_gt_f32_e32 vcc, s55, v42
	v_mul_f32_e32 v43, 0x4f800000, v42
	s_and_b32 s5, s5, 0xffffe000
	v_cndmask_b32_e32 v42, v42, v43, vcc
	v_sqrt_f32_e32 v43, v42
	s_add_i32 s5, s5, 0
	v_add_u32_e32 v66, -1, v43
	v_fma_f32 v67, -v66, v43, v42
	v_cmp_ge_f32_e64 s[6:7], 0, v67
	v_add_u32_e32 v67, 1, v43
	s_nop 0
	v_cndmask_b32_e64 v66, v43, v66, s[6:7]
	v_fma_f32 v43, -v67, v43, v42
	v_cmp_lt_f32_e64 s[6:7], 0, v43
	s_nop 1
	v_cndmask_b32_e64 v43, v66, v67, s[6:7]
	v_mul_f32_e32 v66, 0x37800000, v43
	v_cndmask_b32_e32 v43, v43, v66, vcc
	v_cmp_class_f32_e32 vcc, v42, v253
	s_nop 1
	v_cndmask_b32_e32 v42, v43, v42, vcc
	v_div_scale_f32 v43, s[6:7], v42, v42, 1.0
	v_rcp_f32_e32 v66, v43
	s_nop 0
	v_fma_f32 v67, -v43, v66, 1.0
	v_fmac_f32_e32 v66, v67, v66
	v_div_scale_f32 v67, vcc, 1.0, v42, 1.0
	v_mul_f32_e32 v76, v67, v66
	v_fma_f32 v77, -v43, v76, v67
	v_fmac_f32_e32 v76, v77, v66
	v_fma_f32 v43, -v43, v76, v67
	v_div_fmas_f32 v43, v43, v66, v76
	v_div_fixup_f32 v66, v43, v42, 1.0
	v_pk_mul_f32 v[80:81], v[72:73], v[66:67] op_sel_hi:[1,0]
	v_pk_mul_f32 v[82:83], v[74:75], v[66:67] op_sel_hi:[1,0]
	v_add_u32_e32 v67, s5, v0
	ds_read_b128 v[72:75], v67
	ds_read_b128 v[76:79], v67 offset:40960
	v_lshl_add_u64 v[42:43], s[20:21], 1, v[2:3]
	v_lshl_add_u64 v[42:43], v[42:43], 0, v[6:7]
	v_pk_mul_f32 v[4:5], v[4:5], v[66:67] op_sel_hi:[1,0]
	v_pk_mul_f32 v[46:47], v[46:47], v[66:67] op_sel_hi:[1,0]
	s_waitcnt lgkmcnt(0)
	v_pk_fma_f32 v[74:75], v[74:75], v[82:83], v[78:79]
	v_pk_fma_f32 v[72:73], v[72:73], v[80:81], v[76:77]
	v_pk_mul_f32 v[76:77], v[68:69], v[66:67] op_sel_hi:[1,0]
	v_cvt_pk_bf16_f32 v72, v72, v73
	v_cvt_pk_bf16_f32 v73, v74, v75
	global_store_dwordx2 v[42:43], v[72:73], off
	v_pk_mul_f32 v[78:79], v[70:71], v[66:67] op_sel_hi:[1,0]
	ds_read_b128 v[68:71], v67 offset:1024
	ds_read_b128 v[72:75], v67 offset:41984
	s_waitcnt lgkmcnt(0)
	v_pk_fma_f32 v[70:71], v[70:71], v[78:79], v[74:75]
	v_pk_fma_f32 v[68:69], v[68:69], v[76:77], v[72:73]
	v_pk_mul_f32 v[72:73], v[58:59], v[66:67] op_sel_hi:[1,0]
	v_cvt_pk_bf16_f32 v68, v68, v69
	v_cvt_pk_bf16_f32 v69, v70, v71
	global_store_dwordx2 v[42:43], v[68:69], off offset:512
	v_pk_mul_f32 v[74:75], v[60:61], v[66:67] op_sel_hi:[1,0]
	ds_read_b128 v[58:61], v67 offset:2048
	ds_read_b128 v[68:71], v67 offset:43008
	s_waitcnt lgkmcnt(0)
	v_pk_fma_f32 v[60:61], v[60:61], v[74:75], v[70:71]
	v_pk_fma_f32 v[58:59], v[58:59], v[72:73], v[68:69]
	v_pk_mul_f32 v[68:69], v[62:63], v[66:67] op_sel_hi:[1,0]
	v_cvt_pk_bf16_f32 v58, v58, v59
	v_cvt_pk_bf16_f32 v59, v60, v61
	global_store_dwordx2 v[42:43], v[58:59], off offset:1024
	v_pk_mul_f32 v[70:71], v[64:65], v[66:67] op_sel_hi:[1,0]
	ds_read_b128 v[58:61], v67 offset:3072
	ds_read_b128 v[62:65], v67 offset:44032
	s_waitcnt lgkmcnt(0)
	v_pk_fma_f32 v[60:61], v[70:71], v[60:61], v[64:65]
	v_pk_fma_f32 v[58:59], v[68:69], v[58:59], v[62:63]
	v_pk_mul_f32 v[62:63], v[50:51], v[66:67] op_sel_hi:[1,0]
	v_cvt_pk_bf16_f32 v58, v58, v59
	v_cvt_pk_bf16_f32 v59, v60, v61
	global_store_dwordx2 v[42:43], v[58:59], off offset:1536
	v_pk_mul_f32 v[64:65], v[52:53], v[66:67] op_sel_hi:[1,0]
	ds_read_b128 v[50:53], v67 offset:4096
	ds_read_b128 v[58:61], v67 offset:45056
	s_waitcnt lgkmcnt(0)
	v_pk_fma_f32 v[52:53], v[64:65], v[52:53], v[60:61]
	v_pk_fma_f32 v[50:51], v[62:63], v[50:51], v[58:59]
	v_pk_mul_f32 v[58:59], v[54:55], v[66:67] op_sel_hi:[1,0]
	v_cvt_pk_bf16_f32 v50, v50, v51
	v_cvt_pk_bf16_f32 v51, v52, v53
	global_store_dwordx2 v[42:43], v[50:51], off offset:2048
	v_pk_mul_f32 v[60:61], v[56:57], v[66:67] op_sel_hi:[1,0]
	ds_read_b128 v[50:53], v67 offset:5120
	ds_read_b128 v[54:57], v67 offset:46080
	s_waitcnt lgkmcnt(0)
	v_pk_fma_f32 v[52:53], v[60:61], v[52:53], v[56:57]
	v_pk_fma_f32 v[50:51], v[58:59], v[50:51], v[54:55]
	s_waitcnt vmcnt(60)
	v_cvt_f32_f16_sdwa v59, v41 dst_sel:DWORD dst_unused:UNUSED_PAD src0_sel:WORD_1
	v_cvt_pk_bf16_f32 v50, v50, v51
	v_cvt_pk_bf16_f32 v51, v52, v53
	global_store_dwordx2 v[42:43], v[50:51], off offset:2560
	ds_read_b128 v[50:53], v67 offset:6144
	ds_read_b128 v[54:57], v67 offset:47104
	v_cvt_f32_f16_e32 v58, v41
	s_waitcnt lgkmcnt(0)
	v_pk_fma_f32 v[46:47], v[46:47], v[52:53], v[56:57]
	v_pk_fma_f32 v[4:5], v[4:5], v[50:51], v[54:55]
	v_pk_mul_f32 v[52:53], v[48:49], v[66:67] op_sel_hi:[1,0]
	v_cvt_pk_bf16_f32 v4, v4, v5
	v_cvt_pk_bf16_f32 v5, v46, v47
	global_store_dwordx2 v[42:43], v[4:5], off offset:3072
	v_pk_mul_f32 v[4:5], v[44:45], v[66:67] op_sel_hi:[1,0]
	ds_read_b128 v[44:47], v67 offset:7168
	ds_read_b128 v[48:51], v67 offset:48128
	v_cvt_f32_f16_sdwa v57, v40 dst_sel:DWORD dst_unused:UNUSED_PAD src0_sel:WORD_1
	v_cvt_f32_f16_e32 v56, v40
	s_waitcnt vmcnt(61)
	v_cvt_f32_f16_sdwa v55, v39 dst_sel:DWORD dst_unused:UNUSED_PAD src0_sel:WORD_1
	v_cvt_f32_f16_e32 v54, v39
	s_waitcnt lgkmcnt(0)
	v_pk_fma_f32 v[46:47], v[52:53], v[46:47], v[50:51]
	v_cvt_f32_f16_sdwa v53, v38 dst_sel:DWORD dst_unused:UNUSED_PAD src0_sel:WORD_1
	v_cvt_f32_f16_e32 v52, v38
	v_pk_fma_f32 v[4:5], v[4:5], v[44:45], v[48:49]
	v_mov_b32_e32 v38, v57
	v_cvt_pk_bf16_f32 v4, v4, v5
	v_cvt_pk_bf16_f32 v5, v46, v47
	global_store_dwordx2 v[42:43], v[4:5], off offset:3584
	v_mov_b32_e32 v39, v53
	s_waitcnt vmcnt(61)
	v_cvt_f32_f16_sdwa v43, v36 dst_sel:DWORD dst_unused:UNUSED_PAD src0_sel:WORD_1
	v_cvt_f32_f16_sdwa v45, v37 dst_sel:DWORD dst_unused:UNUSED_PAD src0_sel:WORD_1
	v_mov_b32_e32 v4, v56
	v_mov_b32_e32 v5, v52
	v_pk_mul_f32 v[38:39], v[38:39], v[38:39]
	v_mov_b32_e32 v40, v59
	v_mov_b32_e32 v41, v55
	v_cvt_f32_f16_e32 v42, v36
	v_cvt_f32_f16_e32 v44, v37
	s_waitcnt vmcnt(60)
	v_cvt_f32_f16_sdwa v47, v34 dst_sel:DWORD dst_unused:UNUSED_PAD src0_sel:WORD_1
	v_pk_fma_f32 v[4:5], v[4:5], v[4:5], v[38:39]
	v_mov_b32_e32 v38, v58
	v_mov_b32_e32 v39, v54
	v_pk_mul_f32 v[40:41], v[40:41], v[40:41]
	v_cvt_f32_f16_e32 v46, v34
	v_cvt_f32_f16_sdwa v49, v35 dst_sel:DWORD dst_unused:UNUSED_PAD src0_sel:WORD_1
	v_pk_fma_f32 v[38:39], v[38:39], v[38:39], v[40:41]
	v_cvt_f32_f16_e32 v48, v35
	v_pk_add_f32 v[4:5], v[4:5], v[38:39]
	v_mov_b32_e32 v38, v43
	v_mov_b32_e32 v39, v45
	v_mov_b32_e32 v36, v42
	v_mov_b32_e32 v37, v44
	v_pk_mul_f32 v[38:39], v[38:39], v[38:39]
	v_mul_f32_e32 v34, v47, v47
	v_pk_fma_f32 v[36:37], v[36:37], v[36:37], v[38:39]
	v_pk_fma_f32 v[40:41], v[46:47], v[46:47], v[34:35] op_sel_hi:[1,1,0]
	v_mul_f32_e32 v34, v49, v49
	v_pk_add_f32 v[38:39], v[36:37], v[36:37] op_sel:[0,1] op_sel_hi:[1,0]
	v_pk_fma_f32 v[50:51], v[48:49], v[48:49], v[34:35] op_sel_hi:[1,1,0]
	s_waitcnt vmcnt(59)
	v_cvt_f32_f16_sdwa v35, v32 dst_sel:DWORD dst_unused:UNUSED_PAD src0_sel:WORD_1
	v_cvt_f32_f16_e32 v34, v32
	v_cvt_f32_f16_sdwa v37, v33 dst_sel:DWORD dst_unused:UNUSED_PAD src0_sel:WORD_1
	v_cvt_f32_f16_e32 v36, v33
	v_pk_add_f32 v[4:5], v[4:5], v[4:5] op_sel:[0,1] op_sel_hi:[1,0]
	v_pk_mul_f32 v[32:33], v[34:35], v[34:35]
	v_pk_mul_f32 v[60:61], v[36:37], v[36:37]
	v_mov_b32_e32 v5, v32
	v_mov_b32_e32 v39, v33
	v_mov_b32_e32 v41, v60
	v_mov_b32_e32 v51, v61
	v_pk_add_f32 v[4:5], v[4:5], v[38:39]
	v_pk_add_f32 v[32:33], v[40:41], v[50:51]
	s_waitcnt vmcnt(58)
	v_cvt_f32_f16_sdwa v39, v30 dst_sel:DWORD dst_unused:UNUSED_PAD src0_sel:WORD_1
	v_cvt_f32_f16_sdwa v41, v31 dst_sel:DWORD dst_unused:UNUSED_PAD src0_sel:WORD_1
	v_cvt_f32_f16_e32 v38, v30
	v_cvt_f32_f16_e32 v40, v31
	v_pk_add_f32 v[4:5], v[4:5], v[32:33]
	v_mov_b32_e32 v30, v39
	v_mov_b32_e32 v31, v41
	v_pk_add_f32 v[50:51], v[4:5], v[4:5] op_sel:[0,1] op_sel_hi:[1,0]
	v_mov_b32_e32 v4, v38
	v_mov_b32_e32 v5, v40
	v_pk_mul_f32 v[30:31], v[30:31], v[30:31]
	s_waitcnt vmcnt(56)
	v_cvt_f32_f16_sdwa v33, v27 dst_sel:DWORD dst_unused:UNUSED_PAD src0_sel:WORD_1
	v_pk_fma_f32 v[4:5], v[4:5], v[4:5], v[30:31]
	v_cvt_f32_f16_sdwa v31, v29 dst_sel:DWORD dst_unused:UNUSED_PAD src0_sel:WORD_1
	v_pk_add_f32 v[60:61], v[4:5], v[4:5] op_sel:[0,1] op_sel_hi:[1,0]
	v_cvt_f32_f16_sdwa v5, v28 dst_sel:DWORD dst_unused:UNUSED_PAD src0_sel:WORD_1
	v_cvt_f32_f16_e32 v4, v28
	v_cvt_f32_f16_e32 v30, v29
	v_cvt_f32_f16_e32 v32, v27
	v_mul_f32_e32 v28, v5, v5
	v_pk_fma_f32 v[62:63], v[4:5], v[4:5], v[28:29] op_sel_hi:[1,1,0]
	v_mul_f32_e32 v28, v31, v31
	v_pk_fma_f32 v[64:65], v[30:31], v[30:31], v[28:29] op_sel_hi:[1,1,0]
	v_cvt_f32_f16_sdwa v29, v26 dst_sel:DWORD dst_unused:UNUSED_PAD src0_sel:WORD_1
	v_cvt_f32_f16_e32 v28, v26
	v_pk_mul_f32 v[66:67], v[32:33], v[32:33]
	v_pk_mul_f32 v[26:27], v[28:29], v[28:29]
	s_nop 0
	v_mov_b32_e32 v51, v26
	v_mov_b32_e32 v61, v27
	v_mov_b32_e32 v63, v66
	v_mov_b32_e32 v65, v67
	v_pk_add_f32 v[26:27], v[50:51], v[60:61]
	v_pk_add_f32 v[50:51], v[62:63], v[64:65]
	s_nop 0
	v_pk_add_f32 v[26:27], v[26:27], v[50:51]
	s_nop 0
	v_add_f32_e32 v26, v26, v27
	s_nop 1
	v_add_f32_dpp v26, v26, v26 quad_perm:[1,0,3,2] row_mask:0xf bank_mask:0xf bound_ctrl:1
	s_nop 1
	v_add_f32_dpp v26, v26, v26 quad_perm:[2,3,0,1] row_mask:0xf bank_mask:0xf bound_ctrl:1
	s_nop 1
	v_add_f32_dpp v26, v26, v26 row_half_mirror row_mask:0xf bank_mask:0xf bound_ctrl:1
	s_nop 1
	v_add_f32_dpp v26, v26, v26 row_mirror row_mask:0xf bank_mask:0xf bound_ctrl:1
	s_nop 0
	v_readlane_b32 s5, v26, 16
	v_readlane_b32 s11, v26, 48
	v_readlane_b32 s6, v26, 0
	v_readlane_b32 s7, v26, 32
	v_mov_b32_e32 v26, s5
	v_mov_b32_e32 v27, s11
	v_pk_add_f32 v[26:27], s[6:7], v[26:27]
	s_lshl_b32 s5, s14, 1
	v_add_f32_e32 v26, v26, v27
	v_fmamk_f32 v26, v26, 0x3a000000, v252
	v_cmp_gt_f32_e32 vcc, s55, v26
	v_mul_f32_e32 v27, 0x4f800000, v26
	s_and_b32 s5, s5, 0xffffe000
	v_cndmask_b32_e32 v26, v26, v27, vcc
	v_sqrt_f32_e32 v27, v26
	s_add_i32 s5, s5, 0
	v_add_u32_e32 v50, -1, v27
	v_fma_f32 v51, -v50, v27, v26
	v_cmp_ge_f32_e64 s[6:7], 0, v51
	v_add_u32_e32 v51, 1, v27
	s_nop 0
	v_cndmask_b32_e64 v50, v27, v50, s[6:7]
	v_fma_f32 v27, -v51, v27, v26
	v_cmp_lt_f32_e64 s[6:7], 0, v27
	s_nop 1
	v_cndmask_b32_e64 v27, v50, v51, s[6:7]
	v_mul_f32_e32 v50, 0x37800000, v27
	v_cndmask_b32_e32 v27, v27, v50, vcc
	v_cmp_class_f32_e32 vcc, v26, v253
	s_nop 1
	v_cndmask_b32_e32 v26, v27, v26, vcc
	v_div_scale_f32 v27, s[6:7], v26, v26, 1.0
	v_rcp_f32_e32 v50, v27
	s_nop 0
	v_fma_f32 v51, -v27, v50, 1.0
	v_fmac_f32_e32 v50, v51, v50
	v_div_scale_f32 v51, vcc, 1.0, v26, 1.0
	v_mul_f32_e32 v60, v51, v50
	v_fma_f32 v61, -v27, v60, v51
	v_fmac_f32_e32 v60, v61, v50
	v_fma_f32 v27, -v27, v60, v51
	v_div_fmas_f32 v27, v27, v50, v60
	v_div_fixup_f32 v50, v27, v26, 1.0
	v_pk_mul_f32 v[64:65], v[56:57], v[50:51] op_sel_hi:[1,0]
	v_pk_mul_f32 v[66:67], v[58:59], v[50:51] op_sel_hi:[1,0]
	v_add_u32_e32 v51, s5, v0
	ds_read_b128 v[56:59], v51
	ds_read_b128 v[60:63], v51 offset:40960
	v_lshl_add_u64 v[26:27], s[16:17], 1, v[2:3]
	v_lshl_add_u64 v[26:27], v[26:27], 0, v[6:7]
	v_pk_mul_f32 v[4:5], v[4:5], v[50:51] op_sel_hi:[1,0]
	v_pk_mul_f32 v[30:31], v[30:31], v[50:51] op_sel_hi:[1,0]
	s_waitcnt lgkmcnt(0)
	v_pk_fma_f32 v[58:59], v[58:59], v[66:67], v[62:63]
	v_pk_fma_f32 v[56:57], v[56:57], v[64:65], v[60:61]
	v_pk_mul_f32 v[60:61], v[52:53], v[50:51] op_sel_hi:[1,0]
	v_cvt_pk_bf16_f32 v56, v56, v57
	v_cvt_pk_bf16_f32 v57, v58, v59
	global_store_dwordx2 v[26:27], v[56:57], off
	v_pk_mul_f32 v[62:63], v[54:55], v[50:51] op_sel_hi:[1,0]
	ds_read_b128 v[52:55], v51 offset:1024
	ds_read_b128 v[56:59], v51 offset:41984
	s_waitcnt lgkmcnt(0)
	v_pk_fma_f32 v[54:55], v[54:55], v[62:63], v[58:59]
	v_pk_fma_f32 v[52:53], v[52:53], v[60:61], v[56:57]
	v_pk_mul_f32 v[56:57], v[42:43], v[50:51] op_sel_hi:[1,0]
	v_cvt_pk_bf16_f32 v52, v52, v53
	v_cvt_pk_bf16_f32 v53, v54, v55
	global_store_dwordx2 v[26:27], v[52:53], off offset:512
	v_pk_mul_f32 v[58:59], v[44:45], v[50:51] op_sel_hi:[1,0]
	ds_read_b128 v[42:45], v51 offset:2048
	ds_read_b128 v[52:55], v51 offset:43008
	s_waitcnt lgkmcnt(0)
	v_pk_fma_f32 v[44:45], v[44:45], v[58:59], v[54:55]
	v_pk_fma_f32 v[42:43], v[42:43], v[56:57], v[52:53]
	v_pk_mul_f32 v[52:53], v[46:47], v[50:51] op_sel_hi:[1,0]
	v_cvt_pk_bf16_f32 v42, v42, v43
	v_cvt_pk_bf16_f32 v43, v44, v45
	global_store_dwordx2 v[26:27], v[42:43], off offset:1024
	v_pk_mul_f32 v[54:55], v[48:49], v[50:51] op_sel_hi:[1,0]
	ds_read_b128 v[42:45], v51 offset:3072
	ds_read_b128 v[46:49], v51 offset:44032
	s_waitcnt lgkmcnt(0)
	v_pk_fma_f32 v[44:45], v[54:55], v[44:45], v[48:49]
	v_pk_fma_f32 v[42:43], v[52:53], v[42:43], v[46:47]
	v_pk_mul_f32 v[46:47], v[34:35], v[50:51] op_sel_hi:[1,0]
	v_cvt_pk_bf16_f32 v42, v42, v43
	v_cvt_pk_bf16_f32 v43, v44, v45
	global_store_dwordx2 v[26:27], v[42:43], off offset:1536
	v_pk_mul_f32 v[48:49], v[36:37], v[50:51] op_sel_hi:[1,0]
	ds_read_b128 v[34:37], v51 offset:4096
	ds_read_b128 v[42:45], v51 offset:45056
	s_waitcnt lgkmcnt(0)
	v_pk_fma_f32 v[36:37], v[48:49], v[36:37], v[44:45]
	v_pk_fma_f32 v[34:35], v[46:47], v[34:35], v[42:43]
	v_pk_mul_f32 v[42:43], v[38:39], v[50:51] op_sel_hi:[1,0]
	v_cvt_pk_bf16_f32 v34, v34, v35
	v_cvt_pk_bf16_f32 v35, v36, v37
	global_store_dwordx2 v[26:27], v[34:35], off offset:2048
	v_pk_mul_f32 v[44:45], v[40:41], v[50:51] op_sel_hi:[1,0]
	ds_read_b128 v[34:37], v51 offset:5120
	ds_read_b128 v[38:41], v51 offset:46080
	s_waitcnt lgkmcnt(0)
	v_pk_fma_f32 v[36:37], v[44:45], v[36:37], v[40:41]
	v_pk_fma_f32 v[34:35], v[42:43], v[34:35], v[38:39]
	s_waitcnt vmcnt(60)
	v_cvt_f32_f16_sdwa v43, v25 dst_sel:DWORD dst_unused:UNUSED_PAD src0_sel:WORD_1
	v_cvt_pk_bf16_f32 v34, v34, v35
	v_cvt_pk_bf16_f32 v35, v36, v37
	global_store_dwordx2 v[26:27], v[34:35], off offset:2560
	ds_read_b128 v[34:37], v51 offset:6144
	ds_read_b128 v[38:41], v51 offset:47104
	v_cvt_f32_f16_e32 v42, v25
	s_waitcnt lgkmcnt(0)
	v_pk_fma_f32 v[30:31], v[30:31], v[36:37], v[40:41]
	v_pk_fma_f32 v[4:5], v[4:5], v[34:35], v[38:39]
	v_pk_mul_f32 v[36:37], v[32:33], v[50:51] op_sel_hi:[1,0]
	v_cvt_pk_bf16_f32 v4, v4, v5
	v_cvt_pk_bf16_f32 v5, v30, v31
	global_store_dwordx2 v[26:27], v[4:5], off offset:3072
	v_pk_mul_f32 v[4:5], v[28:29], v[50:51] op_sel_hi:[1,0]
	ds_read_b128 v[28:31], v51 offset:7168
	ds_read_b128 v[32:35], v51 offset:48128
	v_cvt_f32_f16_sdwa v41, v24 dst_sel:DWORD dst_unused:UNUSED_PAD src0_sel:WORD_1
	v_cvt_f32_f16_e32 v40, v24
	s_waitcnt vmcnt(61)
	v_cvt_f32_f16_sdwa v39, v23 dst_sel:DWORD dst_unused:UNUSED_PAD src0_sel:WORD_1
	v_cvt_f32_f16_e32 v38, v23
	s_waitcnt lgkmcnt(0)
	v_pk_fma_f32 v[30:31], v[36:37], v[30:31], v[34:35]
	v_cvt_f32_f16_sdwa v37, v22 dst_sel:DWORD dst_unused:UNUSED_PAD src0_sel:WORD_1
	v_cvt_f32_f16_e32 v36, v22
	v_pk_fma_f32 v[4:5], v[4:5], v[28:29], v[32:33]
	v_mov_b32_e32 v22, v41
	v_cvt_pk_bf16_f32 v4, v4, v5
	v_cvt_pk_bf16_f32 v5, v30, v31
	global_store_dwordx2 v[26:27], v[4:5], off offset:3584
	v_mov_b32_e32 v23, v37
	s_waitcnt vmcnt(61)
	v_cvt_f32_f16_sdwa v27, v20 dst_sel:DWORD dst_unused:UNUSED_PAD src0_sel:WORD_1
	v_cvt_f32_f16_sdwa v29, v21 dst_sel:DWORD dst_unused:UNUSED_PAD src0_sel:WORD_1
	v_mov_b32_e32 v4, v40
	v_mov_b32_e32 v5, v36
	v_pk_mul_f32 v[22:23], v[22:23], v[22:23]
	v_mov_b32_e32 v24, v43
	v_mov_b32_e32 v25, v39
	v_cvt_f32_f16_e32 v26, v20
	v_cvt_f32_f16_e32 v28, v21
	s_waitcnt vmcnt(60)
	v_cvt_f32_f16_sdwa v31, v18 dst_sel:DWORD dst_unused:UNUSED_PAD src0_sel:WORD_1
	v_pk_fma_f32 v[4:5], v[4:5], v[4:5], v[22:23]
	v_mov_b32_e32 v22, v42
	v_mov_b32_e32 v23, v38
	v_pk_mul_f32 v[24:25], v[24:25], v[24:25]
	v_cvt_f32_f16_e32 v30, v18
	v_cvt_f32_f16_sdwa v33, v19 dst_sel:DWORD dst_unused:UNUSED_PAD src0_sel:WORD_1
	v_pk_fma_f32 v[22:23], v[22:23], v[22:23], v[24:25]
	v_cvt_f32_f16_e32 v32, v19
	v_pk_add_f32 v[4:5], v[4:5], v[22:23]
	v_mov_b32_e32 v22, v27
	v_mov_b32_e32 v23, v29
	v_mov_b32_e32 v20, v26
	v_mov_b32_e32 v21, v28
	v_pk_mul_f32 v[22:23], v[22:23], v[22:23]
	v_mul_f32_e32 v18, v31, v31
	v_pk_fma_f32 v[20:21], v[20:21], v[20:21], v[22:23]
	v_pk_fma_f32 v[24:25], v[30:31], v[30:31], v[18:19] op_sel_hi:[1,1,0]
	v_mul_f32_e32 v18, v33, v33
	v_pk_add_f32 v[22:23], v[20:21], v[20:21] op_sel:[0,1] op_sel_hi:[1,0]
	v_pk_fma_f32 v[34:35], v[32:33], v[32:33], v[18:19] op_sel_hi:[1,1,0]
	s_waitcnt vmcnt(59)
	v_cvt_f32_f16_sdwa v19, v16 dst_sel:DWORD dst_unused:UNUSED_PAD src0_sel:WORD_1
	v_cvt_f32_f16_e32 v18, v16
	v_cvt_f32_f16_sdwa v21, v17 dst_sel:DWORD dst_unused:UNUSED_PAD src0_sel:WORD_1
	v_cvt_f32_f16_e32 v20, v17
	v_pk_add_f32 v[4:5], v[4:5], v[4:5] op_sel:[0,1] op_sel_hi:[1,0]
	v_pk_mul_f32 v[16:17], v[18:19], v[18:19]
	v_pk_mul_f32 v[44:45], v[20:21], v[20:21]
	v_mov_b32_e32 v5, v16
	v_mov_b32_e32 v23, v17
	v_mov_b32_e32 v25, v44
	v_mov_b32_e32 v35, v45
	v_pk_add_f32 v[4:5], v[4:5], v[22:23]
	v_pk_add_f32 v[16:17], v[24:25], v[34:35]
	s_waitcnt vmcnt(58)
	v_cvt_f32_f16_sdwa v23, v14 dst_sel:DWORD dst_unused:UNUSED_PAD src0_sel:WORD_1
	v_cvt_f32_f16_sdwa v25, v15 dst_sel:DWORD dst_unused:UNUSED_PAD src0_sel:WORD_1
	v_cvt_f32_f16_e32 v22, v14
	v_cvt_f32_f16_e32 v24, v15
	v_pk_add_f32 v[4:5], v[4:5], v[16:17]
	v_mov_b32_e32 v14, v23
	v_mov_b32_e32 v15, v25
	v_pk_add_f32 v[34:35], v[4:5], v[4:5] op_sel:[0,1] op_sel_hi:[1,0]
	v_mov_b32_e32 v4, v22
	v_mov_b32_e32 v5, v24
	v_pk_mul_f32 v[14:15], v[14:15], v[14:15]
	s_waitcnt vmcnt(56)
	v_cvt_f32_f16_sdwa v17, v11 dst_sel:DWORD dst_unused:UNUSED_PAD src0_sel:WORD_1
	v_pk_fma_f32 v[4:5], v[4:5], v[4:5], v[14:15]
	v_cvt_f32_f16_sdwa v15, v13 dst_sel:DWORD dst_unused:UNUSED_PAD src0_sel:WORD_1
	v_pk_add_f32 v[44:45], v[4:5], v[4:5] op_sel:[0,1] op_sel_hi:[1,0]
	v_cvt_f32_f16_sdwa v5, v12 dst_sel:DWORD dst_unused:UNUSED_PAD src0_sel:WORD_1
	v_cvt_f32_f16_e32 v4, v12
	v_cvt_f32_f16_e32 v14, v13
	v_cvt_f32_f16_e32 v16, v11
	v_mul_f32_e32 v12, v5, v5
	v_pk_fma_f32 v[46:47], v[4:5], v[4:5], v[12:13] op_sel_hi:[1,1,0]
	v_mul_f32_e32 v12, v15, v15
	v_pk_fma_f32 v[48:49], v[14:15], v[14:15], v[12:13] op_sel_hi:[1,1,0]
	v_cvt_f32_f16_sdwa v13, v10 dst_sel:DWORD dst_unused:UNUSED_PAD src0_sel:WORD_1
	v_cvt_f32_f16_e32 v12, v10
	v_pk_mul_f32 v[50:51], v[16:17], v[16:17]
	v_pk_mul_f32 v[10:11], v[12:13], v[12:13]
	s_nop 0
	v_mov_b32_e32 v35, v10
	v_mov_b32_e32 v45, v11
	v_mov_b32_e32 v47, v50
	v_mov_b32_e32 v49, v51
	v_pk_add_f32 v[10:11], v[34:35], v[44:45]
	v_pk_add_f32 v[34:35], v[46:47], v[48:49]
	s_nop 0
	v_pk_add_f32 v[10:11], v[10:11], v[34:35]
	s_nop 0
	v_add_f32_e32 v10, v10, v11
	s_nop 1
	v_add_f32_dpp v10, v10, v10 quad_perm:[1,0,3,2] row_mask:0xf bank_mask:0xf bound_ctrl:1
	s_nop 1
	v_add_f32_dpp v10, v10, v10 quad_perm:[2,3,0,1] row_mask:0xf bank_mask:0xf bound_ctrl:1
	s_nop 1
	v_add_f32_dpp v10, v10, v10 row_half_mirror row_mask:0xf bank_mask:0xf bound_ctrl:1
	s_nop 1
	v_add_f32_dpp v10, v10, v10 row_mirror row_mask:0xf bank_mask:0xf bound_ctrl:1
	s_nop 0
	v_readlane_b32 s5, v10, 16
	v_readlane_b32 s11, v10, 48
	v_readlane_b32 s6, v10, 0
	v_readlane_b32 s7, v10, 32
	v_mov_b32_e32 v10, s5
	v_mov_b32_e32 v11, s11
	v_pk_add_f32 v[10:11], s[6:7], v[10:11]
	s_lshl_b32 s5, s10, 1
	v_add_f32_e32 v10, v10, v11
	v_fmamk_f32 v10, v10, 0x3a000000, v252
	v_cmp_gt_f32_e32 vcc, s55, v10
	v_mul_f32_e32 v11, 0x4f800000, v10
	s_and_b32 s5, s5, 0xffffe000
	v_cndmask_b32_e32 v10, v10, v11, vcc
	v_sqrt_f32_e32 v11, v10
	s_add_i32 s5, s5, 0
	s_cmpk_lt_i32 s4, 0x400
	v_add_u32_e32 v34, -1, v11
	v_fma_f32 v35, -v34, v11, v10
	v_cmp_ge_f32_e64 s[6:7], 0, v35
	v_add_u32_e32 v35, 1, v11
	s_nop 0
	v_cndmask_b32_e64 v34, v11, v34, s[6:7]
	v_fma_f32 v11, -v35, v11, v10
	v_cmp_lt_f32_e64 s[6:7], 0, v11
	s_nop 1
	v_cndmask_b32_e64 v11, v34, v35, s[6:7]
	v_mul_f32_e32 v34, 0x37800000, v11
	v_cndmask_b32_e32 v11, v11, v34, vcc
	v_cmp_class_f32_e32 vcc, v10, v253
	s_nop 1
	v_cndmask_b32_e32 v10, v11, v10, vcc
	v_div_scale_f32 v11, s[6:7], v10, v10, 1.0
	v_rcp_f32_e32 v34, v11
	s_nop 0
	v_fma_f32 v35, -v11, v34, 1.0
	v_fmac_f32_e32 v34, v35, v34
	v_div_scale_f32 v35, vcc, 1.0, v10, 1.0
	v_mul_f32_e32 v44, v35, v34
	v_fma_f32 v45, -v11, v44, v35
	v_fmac_f32_e32 v44, v45, v34
	v_fma_f32 v11, -v11, v44, v35
	v_div_fmas_f32 v11, v11, v34, v44
	v_div_fixup_f32 v34, v11, v10, 1.0
	v_pk_mul_f32 v[48:49], v[40:41], v[34:35] op_sel_hi:[1,0]
	v_pk_mul_f32 v[50:51], v[42:43], v[34:35] op_sel_hi:[1,0]
	v_add_u32_e32 v35, s5, v0
	ds_read_b128 v[40:43], v35
	ds_read_b128 v[44:47], v35 offset:40960
	v_lshl_add_u64 v[10:11], s[12:13], 1, v[2:3]
	v_lshl_add_u64 v[10:11], v[10:11], 0, v[6:7]
	v_pk_mul_f32 v[4:5], v[4:5], v[34:35] op_sel_hi:[1,0]
	v_pk_mul_f32 v[14:15], v[14:15], v[34:35] op_sel_hi:[1,0]
	s_waitcnt lgkmcnt(0)
; #define GAS __attribute__((address_space(1)))
; __device__ __forceinline__ void norm_mod_phase2(const Args& a, Frame& F, const float* gain, const float* modl, int sh_off, int sc_off, int nrows, const float* slab_gate) {
;     ...
;     if (ML + nw < nrows) {
;         const int r = ML + nw, rc = nw;
;         const GAS v2u* xr = (const GAS v2u*)(X + (size_t)r * D) + F.lane;
; #pragma unroll
;         for (int j = 0; j < 8; ++j) r0[j] = xr[64 * j];
;         if (slab_gate != nullptr) { const GAS f32x4* sl = (const GAS f32x4*)((const float*)(a.ws + WS_SLAB) + (size_t)rc * D) + F.lane;
; #pragma unroll
;             for (int j = 0; j < 8; ++j) { const f32x4 p = (sl[64 * j] + sl[64 * j + (size_t)MC * D / 4]) + (sl[64 * j + 2 * ((size_t)MC * D / 4)] + sl[64 * j + 3 * ((size_t)MC * D / 4)]);
	v_pk_fma_f32 v[42:43], v[42:43], v[50:51], v[46:47]
	v_pk_fma_f32 v[40:41], v[40:41], v[48:49], v[44:45]
	v_pk_mul_f32 v[44:45], v[36:37], v[34:35] op_sel_hi:[1,0]
	v_cvt_pk_bf16_f32 v40, v40, v41
	v_cvt_pk_bf16_f32 v41, v42, v43
	global_store_dwordx2 v[10:11], v[40:41], off
	v_pk_mul_f32 v[46:47], v[38:39], v[34:35] op_sel_hi:[1,0]
	ds_read_b128 v[36:39], v35 offset:1024
	ds_read_b128 v[40:43], v35 offset:41984
	s_waitcnt lgkmcnt(0)
	v_pk_fma_f32 v[38:39], v[38:39], v[46:47], v[42:43]
	v_pk_fma_f32 v[36:37], v[36:37], v[44:45], v[40:41]
	v_pk_mul_f32 v[40:41], v[26:27], v[34:35] op_sel_hi:[1,0]
	v_cvt_pk_bf16_f32 v36, v36, v37
	v_cvt_pk_bf16_f32 v37, v38, v39
	global_store_dwordx2 v[10:11], v[36:37], off offset:512
	v_pk_mul_f32 v[42:43], v[28:29], v[34:35] op_sel_hi:[1,0]
	ds_read_b128 v[26:29], v35 offset:2048
	ds_read_b128 v[36:39], v35 offset:43008
	s_waitcnt lgkmcnt(0)
	v_pk_fma_f32 v[28:29], v[28:29], v[42:43], v[38:39]
	v_pk_fma_f32 v[26:27], v[26:27], v[40:41], v[36:37]
	v_pk_mul_f32 v[36:37], v[30:31], v[34:35] op_sel_hi:[1,0]
	v_cvt_pk_bf16_f32 v26, v26, v27
	v_cvt_pk_bf16_f32 v27, v28, v29
	global_store_dwordx2 v[10:11], v[26:27], off offset:1024
	v_pk_mul_f32 v[38:39], v[32:33], v[34:35] op_sel_hi:[1,0]
	ds_read_b128 v[26:29], v35 offset:3072
	ds_read_b128 v[30:33], v35 offset:44032
	s_waitcnt lgkmcnt(0)
	v_pk_fma_f32 v[28:29], v[38:39], v[28:29], v[32:33]
	v_pk_fma_f32 v[26:27], v[36:37], v[26:27], v[30:31]
	v_pk_mul_f32 v[30:31], v[18:19], v[34:35] op_sel_hi:[1,0]
	v_cvt_pk_bf16_f32 v26, v26, v27
	v_cvt_pk_bf16_f32 v27, v28, v29
	global_store_dwordx2 v[10:11], v[26:27], off offset:1536
	v_pk_mul_f32 v[32:33], v[20:21], v[34:35] op_sel_hi:[1,0]
	ds_read_b128 v[18:21], v35 offset:4096
	ds_read_b128 v[26:29], v35 offset:45056
	s_waitcnt lgkmcnt(0)
	v_pk_fma_f32 v[20:21], v[32:33], v[20:21], v[28:29]
	v_pk_fma_f32 v[18:19], v[30:31], v[18:19], v[26:27]
	v_pk_mul_f32 v[26:27], v[22:23], v[34:35] op_sel_hi:[1,0]
	v_cvt_pk_bf16_f32 v18, v18, v19
	v_cvt_pk_bf16_f32 v19, v20, v21
	global_store_dwordx2 v[10:11], v[18:19], off offset:2048
	v_pk_mul_f32 v[28:29], v[24:25], v[34:35] op_sel_hi:[1,0]
	ds_read_b128 v[18:21], v35 offset:5120
	ds_read_b128 v[22:25], v35 offset:46080
	s_waitcnt lgkmcnt(0)
	v_pk_fma_f32 v[20:21], v[28:29], v[20:21], v[24:25]
	v_pk_fma_f32 v[18:19], v[26:27], v[18:19], v[22:23]
	s_nop 0
	v_cvt_pk_bf16_f32 v18, v18, v19
	v_cvt_pk_bf16_f32 v19, v20, v21
	global_store_dwordx2 v[10:11], v[18:19], off offset:2560
	ds_read_b128 v[18:21], v35 offset:6144
	ds_read_b128 v[22:25], v35 offset:47104
	s_waitcnt lgkmcnt(0)
	v_pk_fma_f32 v[14:15], v[14:15], v[20:21], v[24:25]
	v_pk_fma_f32 v[4:5], v[4:5], v[18:19], v[22:23]
	v_pk_mul_f32 v[20:21], v[16:17], v[34:35] op_sel_hi:[1,0]
	v_cvt_pk_bf16_f32 v4, v4, v5
	v_cvt_pk_bf16_f32 v5, v14, v15
	global_store_dwordx2 v[10:11], v[4:5], off offset:3072
	v_pk_mul_f32 v[4:5], v[12:13], v[34:35] op_sel_hi:[1,0]
	ds_read_b128 v[12:15], v35 offset:7168
	ds_read_b128 v[16:19], v35 offset:48128
	s_waitcnt lgkmcnt(0)
	v_pk_fma_f32 v[14:15], v[20:21], v[14:15], v[18:19]
	v_pk_fma_f32 v[4:5], v[4:5], v[12:13], v[16:17]
	s_nop 0
	v_cvt_pk_bf16_f32 v4, v4, v5
	v_cvt_pk_bf16_f32 v5, v14, v15
	global_store_dwordx2 v[10:11], v[4:5], off offset:3584
	s_cbranch_scc0 .LBB0_223
	s_addk_i32 s4, 0x4000
	s_ashr_i32 s5, s4, 31
	s_lshl_b64 s[6:7], s[4:5], 12
	v_lshl_add_u64 v[4:5], v[8:9], 0, s[6:7]
	v_lshl_add_u64 v[18:19], v[4:5], 0, v[6:7]
	global_load_dwordx2 v[22:23], v[18:19], off
	global_load_dwordx2 v[20:21], v[18:19], off offset:512
	global_load_dwordx2 v[16:17], v[18:19], off offset:1024
	global_load_dwordx2 v[12:13], v[18:19], off offset:1536
	global_load_dwordx2 v[14:15], v[18:19], off offset:2048
	global_load_dwordx2 v[10:11], v[18:19], off offset:2560
	global_load_dwordx2 v[8:9], v[18:19], off offset:3072
	global_load_dwordx2 v[4:5], v[18:19], off offset:3584
	v_lshlrev_b32_e32 v40, 2, v143
	s_cmp_eq_u32 s76, 0
	s_cbranch_scc1 .LBB0_222
	v_mov_b32_e32 v24, s72
	v_mov_b32_e32 v25, s73
	v_lshl_add_u64 v[24:25], s[8:9], 2, v[24:25]
	v_lshl_add_u64 v[24:25], v[24:25], 0, v[0:1]
	v_lshlrev_b32_e32 v0, 2, v40
	v_lshl_add_u64 v[26:27], s[86:87], 0, v[0:1]
	v_add_co_u32_e32 v28, vcc, 0x58400000, v24
	s_nop 1
	v_addc_co_u32_e32 v29, vcc, 0, v25, vcc
	v_add_co_u32_e32 v30, vcc, 0x58c00000, v24
	s_nop 1
	v_addc_co_u32_e32 v31, vcc, 0, v25, vcc
	v_add_co_u32_e32 v32, vcc, 0x59400000, v24
	s_nop 1
	v_addc_co_u32_e32 v33, vcc, 0, v25, vcc
	v_add_co_u32_e32 v34, vcc, 0x59c00000, v24
	s_nop 1
	v_addc_co_u32_e32 v35, vcc, 0, v25, vcc
	v_add_co_u32_e32 v36, vcc, 0x58401000, v24
	s_nop 1
	v_addc_co_u32_e32 v37, vcc, 0, v25, vcc
	v_add_co_u32_e32 v38, vcc, 0x58c01000, v24
	s_nop 1
	v_addc_co_u32_e32 v39, vcc, 0, v25, vcc
	v_add_co_u32_e32 v42, vcc, 0x59401000, v24
	s_nop 1
	v_addc_co_u32_e32 v43, vcc, 0, v25, vcc
	v_add_co_u32_e32 v44, vcc, 0x59c01000, v24
	s_nop 1
	v_addc_co_u32_e32 v45, vcc, 0, v25, vcc
	v_add_co_u32_e32 v48, vcc, 0xffffe000, v26
	s_nop 1
	v_addc_co_u32_e32 v49, vcc, -1, v27, vcc
	v_add_co_u32_e32 v50, vcc, 0xfffff000, v26
	s_nop 1
	v_addc_co_u32_e32 v51, vcc, -1, v27, vcc
	global_load_dwordx4 v[94:97], v[28:29], off
	global_load_dwordx4 v[98:101], v[30:31], off
	global_load_dwordx4 v[102:105], v[32:33], off
	global_load_dwordx4 v[106:109], v[34:35], off
	global_load_dwordx4 v[110:113], v[48:49], off
	global_load_dwordx4 v[114:117], v[28:29], off offset:1024
	global_load_dwordx4 v[118:121], v[30:31], off offset:1024
	global_load_dwordx4 v[122:125], v[32:33], off offset:1024
	global_load_dwordx4 v[126:129], v[34:35], off offset:1024
	global_load_dwordx4 v[130:133], v[48:49], off offset:1024
	global_load_dwordx4 v[134:137], v[28:29], off offset:2048
	global_load_dwordx4 v[138:141], v[30:31], off offset:2048
	global_load_dwordx4 v[142:145], v[32:33], off offset:2048
	global_load_dwordx4 v[146:149], v[34:35], off offset:2048
	global_load_dwordx4 v[150:153], v[48:49], off offset:2048
	global_load_dwordx4 v[154:157], v[28:29], off offset:3072
	global_load_dwordx4 v[158:161], v[30:31], off offset:3072
	global_load_dwordx4 v[162:165], v[32:33], off offset:3072
	global_load_dwordx4 v[170:173], v[34:35], off offset:3072
	global_load_dwordx4 v[174:177], v[48:49], off offset:3072
	s_waitcnt vmcnt(15)
; #define GAS __attribute__((address_space(1)))
; __device__ __forceinline__ unsigned xpk2(float lo, float hi) { if (XRES_F16) { const f32x2_t v = {lo, hi}; const f16x2_t h = __builtin_convertvector(v, f16x2_t); return __builtin_bit_cast(unsigned, h); } return pk2(lo, hi); }
; __device__ __forceinline__ float xlo(unsigned w) { if (XRES_F16) { const f16x2_t h = __builtin_bit_cast(f16x2_t, w); return (float)h[0]; } return __builtin_bit_cast(float, w << 16); }
; __device__ __forceinline__ float xhi(unsigned w) { if (XRES_F16) { const f16x2_t h = __builtin_bit_cast(f16x2_t, w); return (float)h[1]; } return __builtin_bit_cast(float, w & 0xffff0000u); }
; __device__ __forceinline__ void norm_mod_phase2(const Args& a, Frame& F, const float* gain, const float* modl, int sh_off, int sc_off, int nrows, const float* slab_gate) {
;     ...
;         if (slab_gate != nullptr) { const GAS f32x4* sl = (const GAS f32x4*)((const float*)(a.ws + WS_SLAB) + (size_t)rc * D) + F.lane;
; #pragma unroll
;             for (int j = 0; j < 8; ++j) { const f32x4 p = (sl[64 * j] + sl[64 * j + (size_t)MC * D / 4]) + (sl[64 * j + 2 * ((size_t)MC * D / 4)] + sl[64 * j + 3 * ((size_t)MC * D / 4)]);
;                 const f32x4 x = (f32x4){xlo(r0[j].x), xhi(r0[j].x), xlo(r0[j].y), xhi(r0[j].y)} + *(const GAS f32x4*)(slab_gate + 256 * j + 4 * F.lane) * p;
;                 v2u w; w.x = xpk2(x[0], x[1]); w.y = xpk2(x[2], x[3]); ((GAS v2u*)(X + (size_t)r * D) + F.lane)[64 * j] = w; r0[j] = w; } }
	v_pk_add_f32 v[220:221], v[94:95], v[98:99]
	v_pk_add_f32 v[222:223], v[96:97], v[100:101]
	v_pk_add_f32 v[224:225], v[102:103], v[106:107]
	v_pk_add_f32 v[226:227], v[104:105], v[108:109]
	v_cvt_f32_f16_e32 v232, v22
	v_cvt_f32_f16_sdwa v233, v22 dst_sel:DWORD dst_unused:UNUSED_PAD src0_sel:WORD_1
	v_cvt_f32_f16_e32 v234, v23
	v_cvt_f32_f16_sdwa v235, v23 dst_sel:DWORD dst_unused:UNUSED_PAD src0_sel:WORD_1
	v_pk_add_f32 v[228:229], v[220:221], v[224:225]
	v_pk_add_f32 v[230:231], v[222:223], v[226:227]
	s_nop 1
	v_pk_fma_f32 v[236:237], v[110:111], v[228:229], v[232:233]
	v_pk_fma_f32 v[238:239], v[112:113], v[230:231], v[234:235]
	s_nop 1
	v_cvt_pk_f16_f32 v22, v236, v237
	v_cvt_pk_f16_f32 v23, v238, v239
	global_store_dwordx2 v[18:19], v[22:23], off
	global_load_dwordx4 v[94:97], v[36:37], off
	global_load_dwordx4 v[98:101], v[38:39], off
	global_load_dwordx4 v[102:105], v[42:43], off
	global_load_dwordx4 v[106:109], v[44:45], off
	global_load_dwordx4 v[110:113], v[50:51], off
	s_waitcnt vmcnt(16)
	v_pk_add_f32 v[220:221], v[114:115], v[118:119]
	v_pk_add_f32 v[222:223], v[116:117], v[120:121]
	v_pk_add_f32 v[224:225], v[122:123], v[126:127]
	v_pk_add_f32 v[226:227], v[124:125], v[128:129]
	v_cvt_f32_f16_e32 v232, v20
	v_cvt_f32_f16_sdwa v233, v20 dst_sel:DWORD dst_unused:UNUSED_PAD src0_sel:WORD_1
	v_cvt_f32_f16_e32 v234, v21
	v_cvt_f32_f16_sdwa v235, v21 dst_sel:DWORD dst_unused:UNUSED_PAD src0_sel:WORD_1
	v_pk_add_f32 v[228:229], v[220:221], v[224:225]
	v_pk_add_f32 v[230:231], v[222:223], v[226:227]
	s_nop 1
	v_pk_fma_f32 v[236:237], v[130:131], v[228:229], v[232:233]
	v_pk_fma_f32 v[238:239], v[132:133], v[230:231], v[234:235]
	s_nop 1
	v_cvt_pk_f16_f32 v20, v236, v237
	v_cvt_pk_f16_f32 v21, v238, v239
	global_store_dwordx2 v[18:19], v[20:21], off offset:512
	global_load_dwordx4 v[114:117], v[36:37], off offset:1024
	global_load_dwordx4 v[118:121], v[38:39], off offset:1024
	global_load_dwordx4 v[122:125], v[42:43], off offset:1024
	global_load_dwordx4 v[126:129], v[44:45], off offset:1024
	global_load_dwordx4 v[130:133], v[50:51], off offset:1024
	s_waitcnt vmcnt(17)
	v_pk_add_f32 v[220:221], v[134:135], v[138:139]
	v_pk_add_f32 v[222:223], v[136:137], v[140:141]
	v_pk_add_f32 v[224:225], v[142:143], v[146:147]
	v_pk_add_f32 v[226:227], v[144:145], v[148:149]
	v_cvt_f32_f16_e32 v232, v16
	v_cvt_f32_f16_sdwa v233, v16 dst_sel:DWORD dst_unused:UNUSED_PAD src0_sel:WORD_1
	v_cvt_f32_f16_e32 v234, v17
	v_cvt_f32_f16_sdwa v235, v17 dst_sel:DWORD dst_unused:UNUSED_PAD src0_sel:WORD_1
	v_pk_add_f32 v[228:229], v[220:221], v[224:225]
	v_pk_add_f32 v[230:231], v[222:223], v[226:227]
	s_nop 1
	v_pk_fma_f32 v[236:237], v[150:151], v[228:229], v[232:233]
	v_pk_fma_f32 v[238:239], v[152:153], v[230:231], v[234:235]
	s_nop 1
	v_cvt_pk_f16_f32 v16, v236, v237
	v_cvt_pk_f16_f32 v17, v238, v239
	global_store_dwordx2 v[18:19], v[16:17], off offset:1024
	global_load_dwordx4 v[134:137], v[36:37], off offset:2048
	global_load_dwordx4 v[138:141], v[38:39], off offset:2048
	global_load_dwordx4 v[142:145], v[42:43], off offset:2048
	global_load_dwordx4 v[146:149], v[44:45], off offset:2048
	global_load_dwordx4 v[150:153], v[50:51], off offset:2048
	s_waitcnt vmcnt(18)
; #define GAS __attribute__((address_space(1)))
; __device__ __forceinline__ unsigned xpk2(float lo, float hi) { if (XRES_F16) { const f32x2_t v = {lo, hi}; const f16x2_t h = __builtin_convertvector(v, f16x2_t); return __builtin_bit_cast(unsigned, h); } return pk2(lo, hi); }
; __device__ __forceinline__ float xlo(unsigned w) { if (XRES_F16) { const f16x2_t h = __builtin_bit_cast(f16x2_t, w); return (float)h[0]; } return __builtin_bit_cast(float, w << 16); }
; __device__ __forceinline__ float xhi(unsigned w) { if (XRES_F16) { const f16x2_t h = __builtin_bit_cast(f16x2_t, w); return (float)h[1]; } return __builtin_bit_cast(float, w & 0xffff0000u); }
; __device__ __forceinline__ void norm_mod_phase2(const Args& a, Frame& F, const float* gain, const float* modl, int sh_off, int sc_off, int nrows, const float* slab_gate) {
;     ...
;         if (slab_gate != nullptr) { const GAS f32x4* sl = (const GAS f32x4*)((const float*)(a.ws + WS_SLAB) + (size_t)rc * D) + F.lane;
; #pragma unroll
;             for (int j = 0; j < 8; ++j) { const f32x4 p = (sl[64 * j] + sl[64 * j + (size_t)MC * D / 4]) + (sl[64 * j + 2 * ((size_t)MC * D / 4)] + sl[64 * j + 3 * ((size_t)MC * D / 4)]);
;                 const f32x4 x = (f32x4){xlo(r0[j].x), xhi(r0[j].x), xlo(r0[j].y), xhi(r0[j].y)} + *(const GAS f32x4*)(slab_gate + 256 * j + 4 * F.lane) * p;
;                 v2u w; w.x = xpk2(x[0], x[1]); w.y = xpk2(x[2], x[3]); ((GAS v2u*)(X + (size_t)r * D) + F.lane)[64 * j] = w; r0[j] = w; } }
	v_pk_add_f32 v[220:221], v[154:155], v[158:159]
	v_pk_add_f32 v[222:223], v[156:157], v[160:161]
	v_pk_add_f32 v[224:225], v[162:163], v[170:171]
	v_pk_add_f32 v[226:227], v[164:165], v[172:173]
	v_cvt_f32_f16_e32 v232, v12
	v_cvt_f32_f16_sdwa v233, v12 dst_sel:DWORD dst_unused:UNUSED_PAD src0_sel:WORD_1
	v_cvt_f32_f16_e32 v234, v13
	v_cvt_f32_f16_sdwa v235, v13 dst_sel:DWORD dst_unused:UNUSED_PAD src0_sel:WORD_1
	v_pk_add_f32 v[228:229], v[220:221], v[224:225]
	v_pk_add_f32 v[230:231], v[222:223], v[226:227]
	s_nop 1
	v_pk_fma_f32 v[236:237], v[174:175], v[228:229], v[232:233]
	v_pk_fma_f32 v[238:239], v[176:177], v[230:231], v[234:235]
	s_nop 1
	v_cvt_pk_f16_f32 v12, v236, v237
	v_cvt_pk_f16_f32 v13, v238, v239
	global_store_dwordx2 v[18:19], v[12:13], off offset:1536
	global_load_dwordx4 v[154:157], v[36:37], off offset:3072
	global_load_dwordx4 v[158:161], v[38:39], off offset:3072
	global_load_dwordx4 v[162:165], v[42:43], off offset:3072
	global_load_dwordx4 v[170:173], v[44:45], off offset:3072
	global_load_dwordx4 v[174:177], v[50:51], off offset:3072
	s_waitcnt vmcnt(18)
	v_pk_add_f32 v[220:221], v[94:95], v[98:99]
	v_pk_add_f32 v[222:223], v[96:97], v[100:101]
	v_pk_add_f32 v[224:225], v[102:103], v[106:107]
	v_pk_add_f32 v[226:227], v[104:105], v[108:109]
	v_cvt_f32_f16_e32 v232, v14
	v_cvt_f32_f16_sdwa v233, v14 dst_sel:DWORD dst_unused:UNUSED_PAD src0_sel:WORD_1
	v_cvt_f32_f16_e32 v234, v15
	v_cvt_f32_f16_sdwa v235, v15 dst_sel:DWORD dst_unused:UNUSED_PAD src0_sel:WORD_1
	v_pk_add_f32 v[228:229], v[220:221], v[224:225]
	v_pk_add_f32 v[230:231], v[222:223], v[226:227]
	s_nop 1
	v_pk_fma_f32 v[236:237], v[110:111], v[228:229], v[232:233]
	v_pk_fma_f32 v[238:239], v[112:113], v[230:231], v[234:235]
	s_nop 1
	v_cvt_pk_f16_f32 v14, v236, v237
	v_cvt_pk_f16_f32 v15, v238, v239
	global_store_dwordx2 v[18:19], v[14:15], off offset:2048
	s_waitcnt vmcnt(13)
	v_pk_add_f32 v[220:221], v[114:115], v[118:119]
	v_pk_add_f32 v[222:223], v[116:117], v[120:121]
	v_pk_add_f32 v[224:225], v[122:123], v[126:127]
	v_pk_add_f32 v[226:227], v[124:125], v[128:129]
	v_cvt_f32_f16_e32 v232, v10
	v_cvt_f32_f16_sdwa v233, v10 dst_sel:DWORD dst_unused:UNUSED_PAD src0_sel:WORD_1
	v_cvt_f32_f16_e32 v234, v11
	v_cvt_f32_f16_sdwa v235, v11 dst_sel:DWORD dst_unused:UNUSED_PAD src0_sel:WORD_1
	v_pk_add_f32 v[228:229], v[220:221], v[224:225]
	v_pk_add_f32 v[230:231], v[222:223], v[226:227]
	s_nop 1
	v_pk_fma_f32 v[236:237], v[130:131], v[228:229], v[232:233]
	v_pk_fma_f32 v[238:239], v[132:133], v[230:231], v[234:235]
	s_nop 1
	v_cvt_pk_f16_f32 v10, v236, v237
	v_cvt_pk_f16_f32 v11, v238, v239
	global_store_dwordx2 v[18:19], v[10:11], off offset:2560
	s_waitcnt vmcnt(8)
	v_pk_add_f32 v[220:221], v[134:135], v[138:139]
	v_pk_add_f32 v[222:223], v[136:137], v[140:141]
	v_pk_add_f32 v[224:225], v[142:143], v[146:147]
	v_pk_add_f32 v[226:227], v[144:145], v[148:149]
	v_cvt_f32_f16_e32 v232, v8
	v_cvt_f32_f16_sdwa v233, v8 dst_sel:DWORD dst_unused:UNUSED_PAD src0_sel:WORD_1
	v_cvt_f32_f16_e32 v234, v9
	v_cvt_f32_f16_sdwa v235, v9 dst_sel:DWORD dst_unused:UNUSED_PAD src0_sel:WORD_1
	v_pk_add_f32 v[228:229], v[220:221], v[224:225]
	v_pk_add_f32 v[230:231], v[222:223], v[226:227]
	s_nop 1
	v_pk_fma_f32 v[236:237], v[150:151], v[228:229], v[232:233]
	v_pk_fma_f32 v[238:239], v[152:153], v[230:231], v[234:235]
	s_nop 1
	v_cvt_pk_f16_f32 v8, v236, v237
	v_cvt_pk_f16_f32 v9, v238, v239
	global_store_dwordx2 v[18:19], v[8:9], off offset:3072
	s_waitcnt vmcnt(3)
	v_pk_add_f32 v[220:221], v[154:155], v[158:159]
	v_pk_add_f32 v[222:223], v[156:157], v[160:161]
	v_pk_add_f32 v[224:225], v[162:163], v[170:171]
	v_pk_add_f32 v[226:227], v[164:165], v[172:173]
	v_cvt_f32_f16_e32 v232, v4
	v_cvt_f32_f16_sdwa v233, v4 dst_sel:DWORD dst_unused:UNUSED_PAD src0_sel:WORD_1
	v_cvt_f32_f16_e32 v234, v5
	v_cvt_f32_f16_sdwa v235, v5 dst_sel:DWORD dst_unused:UNUSED_PAD src0_sel:WORD_1
	v_pk_add_f32 v[228:229], v[220:221], v[224:225]
	v_pk_add_f32 v[230:231], v[222:223], v[226:227]
	s_nop 1
	v_pk_fma_f32 v[236:237], v[174:175], v[228:229], v[232:233]
	v_pk_fma_f32 v[238:239], v[176:177], v[230:231], v[234:235]
	s_nop 1
	v_cvt_pk_f16_f32 v4, v236, v237
	v_cvt_pk_f16_f32 v5, v238, v239
	global_store_dwordx2 v[18:19], v[4:5], off offset:3584

; #define GAS __attribute__((address_space(1)))
; #define LAS __attribute__((address_space(3)))
; #define NR_LOAD(dst, k_) do { const GAS v2u* xr_ = (const GAS v2u*)(X + (size_t)(nw + 2048 * (k_)) * D) + F.lane; \
;         _Pragma("unroll") for (int j = 0; j < 8; ++j) dst[j] = __builtin_nontemporal_load(xr_ + 64 * j); } while (0)
; __device__ __forceinline__ void norm_mod_phase2(const Args& a, Frame& F, const float* gain, const float* modl, int sh_off, int sc_off, int nrows, const float* slab_gate) {
;     ...
;     const int nw = F.vcu * NWAVES + F.wave;
;     bf16* X = (bf16*)(a.ws + WS_X); bf16* HN = (bf16*)(a.ws + WS_HN);
;     LAS float* CA = (LAS float*)F.lds; LAS float* CB = CA + 5 * D;
;     v2u r0[8], r1[8], r2[8], r3[8], r4[8], r5[8], r6[8], r7[8];
;     ...
;     NR_LOAD(r0, 0); NR_LOAD(r1, 1); NR_LOAD(r2, 2); NR_LOAD(r3, 3); NR_LOAD(r4, 4); NR_LOAD(r5, 5); NR_LOAD(r6, 6); NR_LOAD(r7, 7);
;     { const GAS f32x4* g4 = (const GAS f32x4*)gain;
;       for (int q = F.tid; q < 5 * D / 4; q += NWAVES * 64) { const int bq = q >> 9, cq = q & 511; const GAS f32x4* mb4 = (const GAS f32x4*)(modl + (size_t)bq * MOD_LD);
;           ((LAS f32x4*)CA)[q] = g4[cq] * (mb4[sc_off / 4 + cq] + 1.0f); ((LAS f32x4*)CB)[q] = mb4[sh_off / 4 + cq]; } }
.LBB0_1042:
	s_andn2_b64 vcc, exec, s[8:9]
	s_cbranch_vccnz .LBB0_1051
	s_getreg_b32 s6, hwreg(HW_REG_HW_ID, 0, 6)
	s_lshl_b32 s6, s6, 2
	s_add_i32 s6, s6, 0
	s_add_i32 s6, s6, 0x20540
	v_mov_b32_e32 v0, s6
	ds_read_b32 v0, v0
	v_mov_b64_e32 v[2:3], s[0:1]
	v_mov_b32_e32 v7, v1
	s_waitcnt lgkmcnt(0)
	v_readfirstlane_b32 s6, v0
	v_mbcnt_lo_u32_b32 v0, -1, 0
	v_mbcnt_hi_u32_b32 v0, -1, v0
	s_nop 1
	v_lshl_add_u32 v142, s6, 6, v0
	v_mov_b32_e32 v136, s72
	v_mov_b32_e32 v137, s73
	v_readfirstlane_b32 s6, v142
	s_ashr_i32 s6, s6, 6
	s_add_i32 s10, s6, s91
	s_mov_b64 s[6:7], 0x400000
	s_ashr_i32 s11, s10, 31
	v_and_b32_e32 v147, 63, v142
	s_add_i32 s78, s10, 0x800
	v_lshlrev_b32_e32 v6, 3, v147
	s_ashr_i32 s79, s78, 31
	s_add_i32 s36, s10, 0x1000
	s_ashr_i32 s37, s36, 31
	s_add_i32 s30, s10, 0x1800
	s_ashr_i32 s31, s30, 31
	s_add_i32 s26, s10, 0x2000
	s_ashr_i32 s27, s26, 31
	s_add_i32 s22, s10, 0x2800
	s_ashr_i32 s23, s22, 31
	s_add_i32 s18, s10, 0x3000
	s_ashr_i32 s19, s18, 31
	s_add_i32 s14, s10, 0x3800
	s_ashr_i32 s15, s14, 31
	s_waitcnt vmcnt(0) lgkmcnt(0)
	v_lshl_add_u64 v[8:9], v[136:137], 0, s[6:7]
	s_lshl_b64 s[6:7], s[10:11], 12
	v_lshl_add_u64 v[2:3], v[8:9], 0, s[6:7]
	v_lshl_add_u64 v[2:3], v[2:3], 0, v[6:7]
	s_lshl_b64 s[6:7], s[78:79], 12
	v_and_b32_e32 v184, 0x1ff, v142
	v_lshlrev_b32_e32 v184, 4, v184
	v_mov_b32_e32 v185, 0
	v_mov_b32_e32 v186, s76
	v_lshlrev_b32_e32 v186, 13, v186
	v_mov_b32_e32 v187, 0
	v_lshl_add_u64 v[188:189], v[74:75], 0, v[186:187]
	v_lshl_add_u64 v[188:189], v[188:189], 0, v[184:185]
	global_load_dwordx4 v[192:195], v[188:189], off
	v_add_u32_e32 v196, 0x8000, v184
	v_add_u32_e32 v201, 0x6000, v184
	v_add_u32_e32 v197, 0x14000, v184
	v_add_u32_e32 v202, 0x12000, v184
	v_add_u32_e32 v198, 0x20000, v184
	v_add_u32_e32 v203, 0x1e000, v184
	v_add_u32_e32 v199, 0x2c000, v184
	v_add_u32_e32 v204, 0x2a000, v184
	v_add_u32_e32 v200, 0x38000, v184
	v_add_u32_e32 v205, 0x36000, v184
	global_load_dwordx4 v[208:211], v196, s[86:87]
	global_load_dwordx4 v[228:231], v201, s[86:87]
	global_load_dwordx4 v[212:215], v197, s[86:87]
	global_load_dwordx4 v[232:235], v202, s[86:87]
	global_load_dwordx4 v[216:219], v198, s[86:87]
	global_load_dwordx4 v[236:239], v203, s[86:87]
	global_load_dwordx4 v[220:223], v199, s[86:87]
	global_load_dwordx4 v[240:243], v204, s[86:87]
	global_load_dwordx4 v[224:227], v200, s[86:87]
	global_load_dwordx4 v[244:247], v205, s[86:87]
	global_load_dwordx2 v[140:141], v[2:3], off nt
	global_load_dwordx2 v[138:139], v[2:3], off offset:512 nt
	global_load_dwordx2 v[134:135], v[2:3], off offset:1024 nt
	global_load_dwordx2 v[132:133], v[2:3], off offset:1536 nt
	global_load_dwordx2 v[130:131], v[2:3], off offset:2048 nt
	global_load_dwordx2 v[128:129], v[2:3], off offset:2560 nt
	global_load_dwordx2 v[126:127], v[2:3], off offset:3072 nt
	global_load_dwordx2 v[124:125], v[2:3], off offset:3584 nt
	v_lshl_add_u64 v[2:3], v[8:9], 0, s[6:7]
	v_lshl_add_u64 v[2:3], v[2:3], 0, v[6:7]
	s_lshl_b64 s[6:7], s[36:37], 12
	global_load_dwordx2 v[122:123], v[2:3], off nt
	global_load_dwordx2 v[120:121], v[2:3], off offset:512 nt
	global_load_dwordx2 v[118:119], v[2:3], off offset:1024 nt
	global_load_dwordx2 v[116:117], v[2:3], off offset:1536 nt
	global_load_dwordx2 v[114:115], v[2:3], off offset:2048 nt
	global_load_dwordx2 v[112:113], v[2:3], off offset:2560 nt
	global_load_dwordx2 v[110:111], v[2:3], off offset:3072 nt
	global_load_dwordx2 v[108:109], v[2:3], off offset:3584 nt
	v_lshl_add_u64 v[2:3], v[8:9], 0, s[6:7]
	v_lshl_add_u64 v[2:3], v[2:3], 0, v[6:7]
	s_lshl_b64 s[6:7], s[30:31], 12
	global_load_dwordx2 v[106:107], v[2:3], off nt
	global_load_dwordx2 v[104:105], v[2:3], off offset:512 nt
	global_load_dwordx2 v[102:103], v[2:3], off offset:1024 nt
	global_load_dwordx2 v[100:101], v[2:3], off offset:1536 nt
	global_load_dwordx2 v[98:99], v[2:3], off offset:2048 nt
	global_load_dwordx2 v[96:97], v[2:3], off offset:2560 nt
	global_load_dwordx2 v[94:95], v[2:3], off offset:3072 nt
	global_load_dwordx2 v[92:93], v[2:3], off offset:3584 nt
	v_lshl_add_u64 v[2:3], v[8:9], 0, s[6:7]
	v_lshl_add_u64 v[2:3], v[2:3], 0, v[6:7]
	s_lshl_b64 s[6:7], s[26:27], 12
	global_load_dwordx2 v[90:91], v[2:3], off nt
	global_load_dwordx2 v[88:89], v[2:3], off offset:512 nt
	global_load_dwordx2 v[86:87], v[2:3], off offset:1024 nt
	global_load_dwordx2 v[84:85], v[2:3], off offset:1536 nt
	global_load_dwordx2 v[82:83], v[2:3], off offset:2048 nt
	global_load_dwordx2 v[80:81], v[2:3], off offset:2560 nt
	global_load_dwordx2 v[78:79], v[2:3], off offset:3072 nt
	global_load_dwordx2 v[76:77], v[2:3], off offset:3584 nt
	v_lshl_add_u64 v[2:3], v[8:9], 0, s[6:7]
	v_lshl_add_u64 v[2:3], v[2:3], 0, v[6:7]
	s_lshl_b64 s[6:7], s[22:23], 12
	global_load_dwordx2 v[72:73], v[2:3], off nt
	global_load_dwordx2 v[70:71], v[2:3], off offset:512 nt
	global_load_dwordx2 v[68:69], v[2:3], off offset:1024 nt
	global_load_dwordx2 v[66:67], v[2:3], off offset:1536 nt
	global_load_dwordx2 v[64:65], v[2:3], off offset:2048 nt
	global_load_dwordx2 v[62:63], v[2:3], off offset:2560 nt
	global_load_dwordx2 v[60:61], v[2:3], off offset:3072 nt
	global_load_dwordx2 v[58:59], v[2:3], off offset:3584 nt
	v_lshl_add_u64 v[2:3], v[8:9], 0, s[6:7]
	v_lshl_add_u64 v[2:3], v[2:3], 0, v[6:7]
	s_lshl_b64 s[6:7], s[18:19], 12
	global_load_dwordx2 v[56:57], v[2:3], off nt
	global_load_dwordx2 v[54:55], v[2:3], off offset:512 nt
	global_load_dwordx2 v[52:53], v[2:3], off offset:1024 nt
	global_load_dwordx2 v[50:51], v[2:3], off offset:1536 nt
	global_load_dwordx2 v[48:49], v[2:3], off offset:2048 nt
	global_load_dwordx2 v[46:47], v[2:3], off offset:2560 nt
	global_load_dwordx2 v[44:45], v[2:3], off offset:3072 nt
	global_load_dwordx2 v[42:43], v[2:3], off offset:3584 nt
	v_lshl_add_u64 v[2:3], v[8:9], 0, s[6:7]
	v_lshl_add_u64 v[2:3], v[2:3], 0, v[6:7]
	s_lshl_b64 s[6:7], s[14:15], 12
	global_load_dwordx2 v[40:41], v[2:3], off nt
	global_load_dwordx2 v[38:39], v[2:3], off offset:512 nt
	global_load_dwordx2 v[36:37], v[2:3], off offset:1024 nt
	global_load_dwordx2 v[34:35], v[2:3], off offset:1536 nt
	global_load_dwordx2 v[32:33], v[2:3], off offset:2048 nt
	global_load_dwordx2 v[30:31], v[2:3], off offset:2560 nt
	global_load_dwordx2 v[28:29], v[2:3], off offset:3072 nt
	global_load_dwordx2 v[26:27], v[2:3], off offset:3584 nt
	v_lshl_add_u64 v[2:3], v[8:9], 0, s[6:7]
	v_lshl_add_u64 v[2:3], v[2:3], 0, v[6:7]
	global_load_dwordx2 v[24:25], v[2:3], off nt
	global_load_dwordx2 v[22:23], v[2:3], off offset:512 nt
	global_load_dwordx2 v[20:21], v[2:3], off offset:1024 nt
	global_load_dwordx2 v[18:19], v[2:3], off offset:1536 nt
	global_load_dwordx2 v[16:17], v[2:3], off offset:2048 nt
	global_load_dwordx2 v[14:15], v[2:3], off offset:2560 nt
	global_load_dwordx2 v[12:13], v[2:3], off offset:3072 nt
	global_load_dwordx2 v[10:11], v[2:3], off offset:3584 nt
	s_waitcnt vmcnt(62)
; #define GAS __attribute__((address_space(1)))
; #define LAS __attribute__((address_space(3)))
; __device__ __forceinline__ void norm_mod_phase2(const Args& a, Frame& F, const float* gain, const float* modl, int sh_off, int sc_off, int nrows, const float* slab_gate) {
;     ...
;     { const GAS f32x4* g4 = (const GAS f32x4*)gain;
;       for (int q = F.tid; q < 5 * D / 4; q += NWAVES * 64) { const int bq = q >> 9, cq = q & 511; const GAS f32x4* mb4 = (const GAS f32x4*)(modl + (size_t)bq * MOD_LD);
;           ((LAS f32x4*)CA)[q] = g4[cq] * (mb4[sc_off / 4 + cq] + 1.0f); ((LAS f32x4*)CB)[q] = mb4[sh_off / 4 + cq]; } }
;     asm volatile("s_waitcnt lgkmcnt(0)" ::: "memory"); __builtin_amdgcn_s_barrier(); asm volatile("" ::: "memory");
	v_lshl_add_u32 v184, v142, 4, 0
	v_add_u32_e32 v185, 0xa000, v184
	v_pk_add_f32 v[210:211], v[210:211], 1.0 op_sel_hi:[1,0]
	v_pk_add_f32 v[208:209], v[208:209], 1.0 op_sel_hi:[1,0]
	v_pk_mul_f32 v[210:211], v[194:195], v[210:211]
	v_pk_mul_f32 v[208:209], v[192:193], v[208:209]
	ds_write_b128 v184, v[208:211]
	ds_write_b128 v185, v[228:231]
	v_pk_add_f32 v[214:215], v[214:215], 1.0 op_sel_hi:[1,0]
	v_pk_add_f32 v[212:213], v[212:213], 1.0 op_sel_hi:[1,0]
	v_pk_mul_f32 v[214:215], v[194:195], v[214:215]
	v_pk_mul_f32 v[212:213], v[192:193], v[212:213]
	ds_write_b128 v184, v[212:215] offset:8192
	ds_write_b128 v185, v[232:235] offset:8192
	v_pk_add_f32 v[218:219], v[218:219], 1.0 op_sel_hi:[1,0]
	v_pk_add_f32 v[216:217], v[216:217], 1.0 op_sel_hi:[1,0]
	v_pk_mul_f32 v[218:219], v[194:195], v[218:219]
	v_pk_mul_f32 v[216:217], v[192:193], v[216:217]
	ds_write_b128 v184, v[216:219] offset:16384
	ds_write_b128 v185, v[236:239] offset:16384
	v_pk_add_f32 v[222:223], v[222:223], 1.0 op_sel_hi:[1,0]
	v_pk_add_f32 v[220:221], v[220:221], 1.0 op_sel_hi:[1,0]
	v_pk_mul_f32 v[222:223], v[194:195], v[222:223]
	v_pk_mul_f32 v[220:221], v[192:193], v[220:221]
	ds_write_b128 v184, v[220:223] offset:24576
	ds_write_b128 v185, v[240:243] offset:24576
	v_pk_add_f32 v[226:227], v[226:227], 1.0 op_sel_hi:[1,0]
	v_pk_add_f32 v[224:225], v[224:225], 1.0 op_sel_hi:[1,0]
	v_pk_mul_f32 v[226:227], v[194:195], v[226:227]
	v_pk_mul_f32 v[224:225], v[192:193], v[224:225]
	ds_write_b128 v184, v[224:227] offset:32768
	ds_write_b128 v185, v[244:247] offset:32768
	s_waitcnt vmcnt(62)
	v_cvt_f32_f16_sdwa v153, v140 dst_sel:DWORD dst_unused:UNUSED_PAD src0_sel:WORD_1
	v_cvt_f32_f16_sdwa v149, v138 dst_sel:DWORD dst_unused:UNUSED_PAD src0_sel:WORD_1
	v_cvt_f32_f16_e32 v152, v140
	v_cvt_f32_f16_sdwa v155, v141 dst_sel:DWORD dst_unused:UNUSED_PAD src0_sel:WORD_1
	v_cvt_f32_f16_e32 v148, v138
	v_cvt_f32_f16_sdwa v151, v139 dst_sel:DWORD dst_unused:UNUSED_PAD src0_sel:WORD_1
	v_cvt_f32_f16_e32 v154, v141
	v_cvt_f32_f16_e32 v150, v139
	s_waitcnt vmcnt(61)
	v_cvt_f32_f16_sdwa v139, v134 dst_sel:DWORD dst_unused:UNUSED_PAD src0_sel:WORD_1
	v_cvt_f32_f16_sdwa v141, v135 dst_sel:DWORD dst_unused:UNUSED_PAD src0_sel:WORD_1
	s_mov_b64 s[6:7], 0x8c00000
	v_mov_b32_e32 v74, v153
	v_mov_b32_e32 v75, v149
	v_cvt_f32_f16_e32 v138, v134
	v_cvt_f32_f16_e32 v140, v135
	v_lshl_add_u64 v[2:3], v[136:137], 0, s[6:7]
	v_mov_b32_e32 v4, v152
	v_mov_b32_e32 v5, v148
	v_pk_mul_f32 v[74:75], v[74:75], v[74:75]
	v_mov_b32_e32 v136, v155
	v_mov_b32_e32 v137, v151
	v_pk_fma_f32 v[4:5], v[4:5], v[4:5], v[74:75]
	v_mov_b32_e32 v74, v154
	v_mov_b32_e32 v75, v150
	v_pk_mul_f32 v[136:137], v[136:137], v[136:137]
	v_mov_b32_e32 v134, v139
	v_pk_fma_f32 v[74:75], v[74:75], v[74:75], v[136:137]
	v_mov_b32_e32 v135, v141
	s_waitcnt vmcnt(60)
	v_cvt_f32_f16_sdwa v143, v132 dst_sel:DWORD dst_unused:UNUSED_PAD src0_sel:WORD_1
	v_pk_add_f32 v[4:5], v[4:5], v[74:75]
	v_mov_b32_e32 v74, v138
	v_mov_b32_e32 v75, v140
	v_pk_mul_f32 v[134:135], v[134:135], v[134:135]
	v_cvt_f32_f16_e32 v142, v132
	v_cvt_f32_f16_sdwa v145, v133 dst_sel:DWORD dst_unused:UNUSED_PAD src0_sel:WORD_1
	v_pk_fma_f32 v[74:75], v[74:75], v[74:75], v[134:135]
	v_cvt_f32_f16_e32 v144, v133
	s_waitcnt vmcnt(59)
	v_cvt_f32_f16_sdwa v133, v130 dst_sel:DWORD dst_unused:UNUSED_PAD src0_sel:WORD_1
	v_cvt_f32_f16_e32 v132, v130
	v_cvt_f32_f16_sdwa v135, v131 dst_sel:DWORD dst_unused:UNUSED_PAD src0_sel:WORD_1
	v_cvt_f32_f16_e32 v134, v131
	v_mul_f32_e32 v0, v143, v143
	v_pk_fma_f32 v[136:137], v[142:143], v[142:143], v[0:1] op_sel_hi:[1,1,0]
	v_mul_f32_e32 v0, v145, v145
	v_pk_add_f32 v[4:5], v[4:5], v[4:5] op_sel:[0,1] op_sel_hi:[1,0]
	v_pk_add_f32 v[74:75], v[74:75], v[74:75] op_sel:[0,1] op_sel_hi:[1,0]
	v_pk_fma_f32 v[156:157], v[144:145], v[144:145], v[0:1] op_sel_hi:[1,1,0]
	v_pk_mul_f32 v[130:131], v[132:133], v[132:133]
	v_pk_mul_f32 v[158:159], v[134:135], v[134:135]
	v_mov_b32_e32 v5, v130
	v_mov_b32_e32 v75, v131
	v_mov_b32_e32 v137, v158
	v_mov_b32_e32 v157, v159
	v_pk_add_f32 v[4:5], v[4:5], v[74:75]
	v_pk_add_f32 v[74:75], v[136:137], v[156:157]
	s_waitcnt vmcnt(58)
	v_cvt_f32_f16_sdwa v131, v128 dst_sel:DWORD dst_unused:UNUSED_PAD src0_sel:WORD_1
	v_cvt_f32_f16_sdwa v137, v129 dst_sel:DWORD dst_unused:UNUSED_PAD src0_sel:WORD_1
	v_cvt_f32_f16_e32 v130, v128
	v_cvt_f32_f16_e32 v136, v129
	v_pk_add_f32 v[4:5], v[4:5], v[74:75]
	v_mov_b32_e32 v74, v131
	v_mov_b32_e32 v75, v137
	v_pk_add_f32 v[156:157], v[4:5], v[4:5] op_sel:[0,1] op_sel_hi:[1,0]
	v_mov_b32_e32 v4, v130
	v_mov_b32_e32 v5, v136
	v_pk_mul_f32 v[74:75], v[74:75], v[74:75]
	s_waitcnt vmcnt(57)
	v_cvt_f32_f16_sdwa v129, v127 dst_sel:DWORD dst_unused:UNUSED_PAD src0_sel:WORD_1
	v_pk_fma_f32 v[4:5], v[4:5], v[4:5], v[74:75]
	v_cvt_f32_f16_e32 v128, v127
	v_pk_add_f32 v[158:159], v[4:5], v[4:5] op_sel:[0,1] op_sel_hi:[1,0]
	v_cvt_f32_f16_sdwa v5, v126 dst_sel:DWORD dst_unused:UNUSED_PAD src0_sel:WORD_1
	v_cvt_f32_f16_e32 v4, v126
	s_waitcnt vmcnt(56)
	v_cvt_f32_f16_sdwa v75, v124 dst_sel:DWORD dst_unused:UNUSED_PAD src0_sel:WORD_1
	v_cvt_f32_f16_e32 v74, v124
	v_cvt_f32_f16_sdwa v127, v125 dst_sel:DWORD dst_unused:UNUSED_PAD src0_sel:WORD_1
	v_cvt_f32_f16_e32 v126, v125
	v_mul_f32_e32 v0, v5, v5
	v_pk_fma_f32 v[160:161], v[4:5], v[4:5], v[0:1] op_sel_hi:[1,1,0]
	v_mul_f32_e32 v0, v129, v129
	v_pk_fma_f32 v[162:163], v[128:129], v[128:129], v[0:1] op_sel_hi:[1,1,0]
	v_pk_mul_f32 v[124:125], v[74:75], v[74:75]
	v_pk_mul_f32 v[164:165], v[126:127], v[126:127]
	v_mov_b32_e32 v157, v124
	v_mov_b32_e32 v159, v125
	v_mov_b32_e32 v161, v164
	v_mov_b32_e32 v163, v165
	v_pk_add_f32 v[124:125], v[156:157], v[158:159]
	v_pk_add_f32 v[156:157], v[160:161], v[162:163]
	s_waitcnt lgkmcnt(0)
	s_barrier
	v_pk_add_f32 v[124:125], v[124:125], v[156:157]
	s_lshl_b64 s[12:13], s[10:11], 11
	v_add_f32_e32 v0, v124, v125
	s_lshl_b64 s[48:49], s[78:79], 11
	s_lshl_b64 s[40:41], s[36:37], 11
	v_add_f32_dpp v0, v0, v0 quad_perm:[1,0,3,2] row_mask:0xf bank_mask:0xf bound_ctrl:1
	s_lshl_b64 s[34:35], s[30:31], 11
	s_lshl_b64 s[28:29], s[26:27], 11
	v_add_f32_dpp v0, v0, v0 quad_perm:[2,3,0,1] row_mask:0xf bank_mask:0xf bound_ctrl:1
	s_lshl_b64 s[24:25], s[22:23], 11
	s_lshl_b64 s[20:21], s[18:19], 11
	v_add_f32_dpp v0, v0, v0 row_half_mirror row_mask:0xf bank_mask:0xf bound_ctrl:1
	s_lshl_b64 s[16:17], s[14:15], 11
	s_nop 0
	v_add_f32_dpp v0, v0, v0 row_mirror row_mask:0xf bank_mask:0xf bound_ctrl:1
	s_nop 0
	v_readlane_b32 s8, v0, 16
	v_readlane_b32 s9, v0, 48
	v_readlane_b32 s6, v0, 0
	v_readlane_b32 s7, v0, 32
	v_mov_b32_e32 v124, s8
	v_mov_b32_e32 v125, s9
	v_pk_add_f32 v[124:125], s[6:7], v[124:125]
	s_nop 0
	v_add_f32_e32 v0, v124, v125
	v_fmamk_f32 v0, v0, 0x3a000000, v252
	v_cmp_gt_f32_e32 vcc, s55, v0
	v_mul_f32_e32 v7, 0x4f800000, v0
	s_nop 0
	v_cndmask_b32_e32 v0, v0, v7, vcc
	v_sqrt_f32_e32 v7, v0
	s_nop 0
	v_add_u32_e32 v124, -1, v7
	v_fma_f32 v125, -v124, v7, v0
	v_cmp_ge_f32_e64 s[8:9], 0, v125
	v_add_u32_e32 v125, 1, v7
	s_nop 0
	v_cndmask_b32_e64 v124, v7, v124, s[8:9]
	v_fma_f32 v7, -v125, v7, v0
	v_cmp_lt_f32_e64 s[8:9], 0, v7
	s_nop 1
	v_cndmask_b32_e64 v7, v124, v125, s[8:9]
	v_mul_f32_e32 v124, 0x37800000, v7
	v_cndmask_b32_e32 v7, v7, v124, vcc
	v_cmp_class_f32_e32 vcc, v0, v253
	s_nop 1
	v_cndmask_b32_e32 v0, v7, v0, vcc
	v_div_scale_f32 v7, s[6:7], v0, v0, 1.0
	v_rcp_f32_e32 v124, v7
	s_lshl_b32 s6, s10, 1
	s_and_b32 s6, s6, 0xffffe000
	s_add_i32 s6, s6, 0
	v_fma_f32 v125, -v7, v124, 1.0
	v_fmac_f32_e32 v124, v125, v124
	v_div_scale_f32 v125, vcc, 1.0, v0, 1.0
	v_mul_f32_e32 v146, v125, v124
	v_fma_f32 v156, -v7, v146, v125
	v_fmac_f32_e32 v146, v156, v124
	v_fma_f32 v7, -v7, v146, v125
	v_div_fmas_f32 v7, v7, v124, v146
	v_div_fixup_f32 v146, v7, v0, 1.0
	v_lshlrev_b32_e32 v0, 4, v147
	v_add_u32_e32 v164, s6, v0
	v_pk_mul_f32 v[160:161], v[152:153], v[146:147] op_sel_hi:[1,0]
	v_pk_mul_f32 v[162:163], v[154:155], v[146:147] op_sel_hi:[1,0]
	ds_read_b128 v[152:155], v164
	ds_read_b128 v[156:159], v164 offset:40960
	v_lshl_add_u64 v[124:125], s[12:13], 1, v[2:3]
	v_mov_b32_e32 v7, v1
	v_lshl_add_u64 v[124:125], v[124:125], 0, v[6:7]
	v_pk_mul_f32 v[4:5], v[4:5], v[146:147] op_sel_hi:[1,0]
	s_waitcnt lgkmcnt(0)
	v_pk_fma_f32 v[154:155], v[154:155], v[162:163], v[158:159]
	v_pk_fma_f32 v[152:153], v[152:153], v[160:161], v[156:157]
	v_pk_mul_f32 v[156:157], v[148:149], v[146:147] op_sel_hi:[1,0]
	v_cvt_pk_bf16_f32 v152, v152, v153
	v_cvt_pk_bf16_f32 v153, v154, v155
	global_store_dwordx2 v[124:125], v[152:153], off
	v_pk_mul_f32 v[158:159], v[150:151], v[146:147] op_sel_hi:[1,0]
	ds_read_b128 v[148:151], v164 offset:1024
	ds_read_b128 v[152:155], v164 offset:41984
	s_waitcnt lgkmcnt(0)
	v_pk_fma_f32 v[150:151], v[150:151], v[158:159], v[154:155]
	v_pk_fma_f32 v[148:149], v[148:149], v[156:157], v[152:153]
	v_pk_mul_f32 v[152:153], v[138:139], v[146:147] op_sel_hi:[1,0]
	v_cvt_pk_bf16_f32 v148, v148, v149
	v_cvt_pk_bf16_f32 v149, v150, v151
	global_store_dwordx2 v[124:125], v[148:149], off offset:512
	v_pk_mul_f32 v[154:155], v[140:141], v[146:147] op_sel_hi:[1,0]
	ds_read_b128 v[138:141], v164 offset:2048
	ds_read_b128 v[148:151], v164 offset:43008
	s_waitcnt lgkmcnt(0)
	v_pk_fma_f32 v[140:141], v[140:141], v[154:155], v[150:151]
	v_pk_fma_f32 v[138:139], v[138:139], v[152:153], v[148:149]
	v_pk_mul_f32 v[148:149], v[142:143], v[146:147] op_sel_hi:[1,0]
	v_cvt_pk_bf16_f32 v138, v138, v139
	v_cvt_pk_bf16_f32 v139, v140, v141
	global_store_dwordx2 v[124:125], v[138:139], off offset:1024
	v_pk_mul_f32 v[150:151], v[144:145], v[146:147] op_sel_hi:[1,0]
	ds_read_b128 v[138:141], v164 offset:3072
	ds_read_b128 v[142:145], v164 offset:44032
	s_waitcnt lgkmcnt(0)
	v_pk_fma_f32 v[140:141], v[150:151], v[140:141], v[144:145]
	v_pk_fma_f32 v[138:139], v[148:149], v[138:139], v[142:143]
	v_pk_mul_f32 v[142:143], v[132:133], v[146:147] op_sel_hi:[1,0]
	v_cvt_pk_bf16_f32 v138, v138, v139
	v_cvt_pk_bf16_f32 v139, v140, v141
	global_store_dwordx2 v[124:125], v[138:139], off offset:1536
	v_pk_mul_f32 v[144:145], v[134:135], v[146:147] op_sel_hi:[1,0]
	ds_read_b128 v[132:135], v164 offset:4096
	ds_read_b128 v[138:141], v164 offset:45056
	s_waitcnt lgkmcnt(0)
	v_pk_fma_f32 v[134:135], v[144:145], v[134:135], v[140:141]
	v_pk_fma_f32 v[132:133], v[142:143], v[132:133], v[138:139]
	v_pk_mul_f32 v[138:139], v[130:131], v[146:147] op_sel_hi:[1,0]
	v_cvt_pk_bf16_f32 v132, v132, v133
	v_cvt_pk_bf16_f32 v133, v134, v135
	global_store_dwordx2 v[124:125], v[132:133], off offset:2048
	v_pk_mul_f32 v[140:141], v[136:137], v[146:147] op_sel_hi:[1,0]
	ds_read_b128 v[130:133], v164 offset:5120
	ds_read_b128 v[134:137], v164 offset:46080
	s_waitcnt lgkmcnt(0)
	v_pk_fma_f32 v[132:133], v[140:141], v[132:133], v[136:137]
	v_pk_fma_f32 v[130:131], v[138:139], v[130:131], v[134:135]
	v_pk_mul_f32 v[136:137], v[128:129], v[146:147] op_sel_hi:[1,0]
	v_cvt_pk_bf16_f32 v130, v130, v131
	v_cvt_pk_bf16_f32 v131, v132, v133
	global_store_dwordx2 v[124:125], v[130:131], off offset:2560
	ds_read_b128 v[128:131], v164 offset:6144
	ds_read_b128 v[132:135], v164 offset:47104
	s_waitcnt vmcnt(61)
	v_cvt_f32_f16_sdwa v139, v123 dst_sel:DWORD dst_unused:UNUSED_PAD src0_sel:WORD_1
	v_cvt_f32_f16_e32 v138, v123
	s_waitcnt vmcnt(59)
	v_cvt_f32_f16_sdwa v123, v118 dst_sel:DWORD dst_unused:UNUSED_PAD src0_sel:WORD_1
	s_waitcnt lgkmcnt(0)
	v_pk_fma_f32 v[130:131], v[136:137], v[130:131], v[134:135]
	v_pk_fma_f32 v[4:5], v[4:5], v[128:129], v[132:133]
	v_cvt_f32_f16_sdwa v137, v122 dst_sel:DWORD dst_unused:UNUSED_PAD src0_sel:WORD_1
	v_cvt_pk_bf16_f32 v4, v4, v5
	v_cvt_pk_bf16_f32 v5, v130, v131
	global_store_dwordx2 v[124:125], v[4:5], off offset:3072
	v_pk_mul_f32 v[4:5], v[74:75], v[146:147] op_sel_hi:[1,0]
	v_pk_mul_f32 v[74:75], v[126:127], v[146:147] op_sel_hi:[1,0]
	ds_read_b128 v[126:129], v164 offset:7168
	ds_read_b128 v[130:133], v164 offset:48128
	v_cvt_f32_f16_e32 v136, v122
	v_cvt_f32_f16_sdwa v135, v121 dst_sel:DWORD dst_unused:UNUSED_PAD src0_sel:WORD_1
	v_cvt_f32_f16_e32 v134, v121
	v_cvt_f32_f16_e32 v122, v118
	s_waitcnt lgkmcnt(0)
	v_pk_fma_f32 v[74:75], v[74:75], v[128:129], v[132:133]
	v_cvt_f32_f16_sdwa v133, v120 dst_sel:DWORD dst_unused:UNUSED_PAD src0_sel:WORD_1
	v_pk_fma_f32 v[4:5], v[4:5], v[126:127], v[130:131]
	v_cvt_f32_f16_e32 v132, v120
	v_cvt_pk_bf16_f32 v4, v4, v5
	v_cvt_pk_bf16_f32 v5, v74, v75
	global_store_dwordx2 v[124:125], v[4:5], off offset:3584
	v_cvt_f32_f16_sdwa v125, v119 dst_sel:DWORD dst_unused:UNUSED_PAD src0_sel:WORD_1
	s_waitcnt vmcnt(60)
	v_cvt_f32_f16_sdwa v127, v116 dst_sel:DWORD dst_unused:UNUSED_PAD src0_sel:WORD_1
	v_mov_b32_e32 v74, v137
	v_mov_b32_e32 v75, v133
	v_cvt_f32_f16_e32 v124, v119
	v_cvt_f32_f16_e32 v126, v116
	v_cvt_f32_f16_sdwa v129, v117 dst_sel:DWORD dst_unused:UNUSED_PAD src0_sel:WORD_1
	v_mov_b32_e32 v4, v136
	v_mov_b32_e32 v5, v132
	v_pk_mul_f32 v[74:75], v[74:75], v[74:75]
	v_mov_b32_e32 v120, v139
	v_mov_b32_e32 v121, v135
	v_cvt_f32_f16_e32 v128, v117
	v_pk_fma_f32 v[4:5], v[4:5], v[4:5], v[74:75]
	v_mov_b32_e32 v74, v138
	v_mov_b32_e32 v75, v134
	v_pk_mul_f32 v[120:121], v[120:121], v[120:121]
	v_mov_b32_e32 v118, v123
	v_pk_fma_f32 v[74:75], v[74:75], v[74:75], v[120:121]
	v_mov_b32_e32 v119, v125
	v_mul_f32_e32 v116, v127, v127
	v_pk_add_f32 v[4:5], v[4:5], v[74:75]
	v_mov_b32_e32 v74, v122
	v_mov_b32_e32 v75, v124
	v_pk_mul_f32 v[118:119], v[118:119], v[118:119]
	v_pk_fma_f32 v[120:121], v[126:127], v[126:127], v[116:117] op_sel_hi:[1,1,0]
	v_mul_f32_e32 v116, v129, v129
	v_pk_fma_f32 v[74:75], v[74:75], v[74:75], v[118:119]
	v_pk_fma_f32 v[130:131], v[128:129], v[128:129], v[116:117] op_sel_hi:[1,1,0]
	s_waitcnt vmcnt(59)
	v_cvt_f32_f16_sdwa v117, v114 dst_sel:DWORD dst_unused:UNUSED_PAD src0_sel:WORD_1
	v_cvt_f32_f16_e32 v116, v114
	v_cvt_f32_f16_sdwa v119, v115 dst_sel:DWORD dst_unused:UNUSED_PAD src0_sel:WORD_1
	v_cvt_f32_f16_e32 v118, v115
	v_pk_add_f32 v[4:5], v[4:5], v[4:5] op_sel:[0,1] op_sel_hi:[1,0]
	v_pk_add_f32 v[74:75], v[74:75], v[74:75] op_sel:[0,1] op_sel_hi:[1,0]
	v_pk_mul_f32 v[114:115], v[116:117], v[116:117]
	v_pk_mul_f32 v[140:141], v[118:119], v[118:119]
	v_mov_b32_e32 v5, v114
	v_mov_b32_e32 v75, v115
	v_mov_b32_e32 v121, v140
	v_mov_b32_e32 v131, v141
	v_pk_add_f32 v[4:5], v[4:5], v[74:75]
	v_pk_add_f32 v[74:75], v[120:121], v[130:131]
	s_waitcnt vmcnt(58)
	v_cvt_f32_f16_sdwa v115, v112 dst_sel:DWORD dst_unused:UNUSED_PAD src0_sel:WORD_1
	v_cvt_f32_f16_sdwa v121, v113 dst_sel:DWORD dst_unused:UNUSED_PAD src0_sel:WORD_1
	v_cvt_f32_f16_e32 v114, v112
	v_cvt_f32_f16_e32 v120, v113
	v_pk_add_f32 v[4:5], v[4:5], v[74:75]
	v_mov_b32_e32 v74, v115
	v_mov_b32_e32 v75, v121
	v_pk_add_f32 v[130:131], v[4:5], v[4:5] op_sel:[0,1] op_sel_hi:[1,0]
	v_mov_b32_e32 v4, v114
	v_mov_b32_e32 v5, v120
	v_pk_mul_f32 v[74:75], v[74:75], v[74:75]
	s_waitcnt vmcnt(57)
	v_cvt_f32_f16_sdwa v113, v111 dst_sel:DWORD dst_unused:UNUSED_PAD src0_sel:WORD_1
	v_pk_fma_f32 v[4:5], v[4:5], v[4:5], v[74:75]
	v_cvt_f32_f16_e32 v112, v111
	v_pk_add_f32 v[140:141], v[4:5], v[4:5] op_sel:[0,1] op_sel_hi:[1,0]
	v_cvt_f32_f16_sdwa v5, v110 dst_sel:DWORD dst_unused:UNUSED_PAD src0_sel:WORD_1
	v_cvt_f32_f16_e32 v4, v110
	s_waitcnt vmcnt(56)
	v_cvt_f32_f16_sdwa v111, v109 dst_sel:DWORD dst_unused:UNUSED_PAD src0_sel:WORD_1
	v_cvt_f32_f16_e32 v110, v109
	v_mul_f32_e32 v74, v5, v5
	v_pk_fma_f32 v[142:143], v[4:5], v[4:5], v[74:75] op_sel_hi:[1,1,0]
	v_mul_f32_e32 v74, v113, v113
	v_pk_fma_f32 v[144:145], v[112:113], v[112:113], v[74:75] op_sel_hi:[1,1,0]
	v_cvt_f32_f16_sdwa v75, v108 dst_sel:DWORD dst_unused:UNUSED_PAD src0_sel:WORD_1
	v_cvt_f32_f16_e32 v74, v108
	v_pk_mul_f32 v[148:149], v[110:111], v[110:111]
	v_pk_mul_f32 v[108:109], v[74:75], v[74:75]
	s_nop 0
	v_mov_b32_e32 v131, v108
	v_mov_b32_e32 v141, v109
	v_mov_b32_e32 v143, v148
	v_mov_b32_e32 v145, v149
	v_pk_add_f32 v[108:109], v[130:131], v[140:141]
	v_pk_add_f32 v[130:131], v[142:143], v[144:145]
	s_nop 0
	v_pk_add_f32 v[108:109], v[108:109], v[130:131]
	s_nop 0
	v_add_f32_e32 v108, v108, v109
	s_nop 1
	v_add_f32_dpp v108, v108, v108 quad_perm:[1,0,3,2] row_mask:0xf bank_mask:0xf bound_ctrl:1
	s_nop 1
	v_add_f32_dpp v108, v108, v108 quad_perm:[2,3,0,1] row_mask:0xf bank_mask:0xf bound_ctrl:1
	s_nop 1
	v_add_f32_dpp v108, v108, v108 row_half_mirror row_mask:0xf bank_mask:0xf bound_ctrl:1
	s_nop 1
	v_add_f32_dpp v108, v108, v108 row_mirror row_mask:0xf bank_mask:0xf bound_ctrl:1
	s_nop 0
	v_readlane_b32 s8, v108, 16
	v_readlane_b32 s9, v108, 48
	v_readlane_b32 s6, v108, 0
	v_readlane_b32 s7, v108, 32
	v_mov_b32_e32 v108, s8
	v_mov_b32_e32 v109, s9
	v_pk_add_f32 v[108:109], s[6:7], v[108:109]
	s_nop 0
	v_add_f32_e32 v108, v108, v109
	v_fmamk_f32 v108, v108, 0x3a000000, v252
	v_cmp_gt_f32_e32 vcc, s55, v108
	v_mul_f32_e32 v109, 0x4f800000, v108
	s_nop 0
	v_cndmask_b32_e32 v108, v108, v109, vcc
	v_sqrt_f32_e32 v109, v108
	s_nop 0
	v_add_u32_e32 v130, -1, v109
	v_fma_f32 v131, -v130, v109, v108
	v_cmp_ge_f32_e64 s[8:9], 0, v131
	v_add_u32_e32 v131, 1, v109
	s_nop 0
	v_cndmask_b32_e64 v130, v109, v130, s[8:9]
	v_fma_f32 v109, -v131, v109, v108
	v_cmp_lt_f32_e64 s[8:9], 0, v109
	s_nop 1
	v_cndmask_b32_e64 v109, v130, v131, s[8:9]
	v_mul_f32_e32 v130, 0x37800000, v109
	v_cndmask_b32_e32 v109, v109, v130, vcc
	v_cmp_class_f32_e32 vcc, v108, v253
	s_nop 1
	v_cndmask_b32_e32 v108, v109, v108, vcc
	v_div_scale_f32 v109, s[6:7], v108, v108, 1.0
	v_rcp_f32_e32 v130, v109
	s_lshl_b32 s6, s78, 1
	s_and_b32 s6, s6, 0xffffe000
	s_add_i32 s6, s6, 0
	v_fma_f32 v131, -v109, v130, 1.0
	v_fmac_f32_e32 v130, v131, v130
	v_div_scale_f32 v131, vcc, 1.0, v108, 1.0
	v_mul_f32_e32 v140, v131, v130
	v_fma_f32 v141, -v109, v140, v131
	v_fmac_f32_e32 v140, v141, v130
	v_fma_f32 v109, -v109, v140, v131
	v_div_fmas_f32 v109, v109, v130, v140
	v_div_fixup_f32 v130, v109, v108, 1.0
	v_pk_mul_f32 v[144:145], v[136:137], v[130:131] op_sel_hi:[1,0]
	v_pk_mul_f32 v[148:149], v[138:139], v[130:131] op_sel_hi:[1,0]
	v_add_u32_e32 v131, s6, v0
	ds_read_b128 v[136:139], v131
	ds_read_b128 v[140:143], v131 offset:40960
	v_lshl_add_u64 v[108:109], s[48:49], 1, v[2:3]
	v_lshl_add_u64 v[108:109], v[108:109], 0, v[6:7]
	v_pk_mul_f32 v[4:5], v[4:5], v[130:131] op_sel_hi:[1,0]
	s_waitcnt lgkmcnt(0)
	v_pk_fma_f32 v[138:139], v[138:139], v[148:149], v[142:143]
	v_pk_fma_f32 v[136:137], v[136:137], v[144:145], v[140:141]
	v_pk_mul_f32 v[140:141], v[132:133], v[130:131] op_sel_hi:[1,0]
	v_cvt_pk_bf16_f32 v136, v136, v137
	v_cvt_pk_bf16_f32 v137, v138, v139
	global_store_dwordx2 v[108:109], v[136:137], off
	v_pk_mul_f32 v[142:143], v[134:135], v[130:131] op_sel_hi:[1,0]
	ds_read_b128 v[132:135], v131 offset:1024
	ds_read_b128 v[136:139], v131 offset:41984
	s_waitcnt lgkmcnt(0)
	v_pk_fma_f32 v[134:135], v[134:135], v[142:143], v[138:139]
	v_pk_fma_f32 v[132:133], v[132:133], v[140:141], v[136:137]
	v_pk_mul_f32 v[136:137], v[122:123], v[130:131] op_sel_hi:[1,0]
	v_cvt_pk_bf16_f32 v132, v132, v133
	v_cvt_pk_bf16_f32 v133, v134, v135
	global_store_dwordx2 v[108:109], v[132:133], off offset:512
	v_pk_mul_f32 v[138:139], v[124:125], v[130:131] op_sel_hi:[1,0]
	ds_read_b128 v[122:125], v131 offset:2048
	ds_read_b128 v[132:135], v131 offset:43008
	s_waitcnt lgkmcnt(0)
	v_pk_fma_f32 v[124:125], v[124:125], v[138:139], v[134:135]
	v_pk_fma_f32 v[122:123], v[122:123], v[136:137], v[132:133]
	v_pk_mul_f32 v[132:133], v[126:127], v[130:131] op_sel_hi:[1,0]
	v_cvt_pk_bf16_f32 v122, v122, v123
	v_cvt_pk_bf16_f32 v123, v124, v125
	global_store_dwordx2 v[108:109], v[122:123], off offset:1024
	v_pk_mul_f32 v[134:135], v[128:129], v[130:131] op_sel_hi:[1,0]
	ds_read_b128 v[122:125], v131 offset:3072
	ds_read_b128 v[126:129], v131 offset:44032
	s_waitcnt lgkmcnt(0)
	v_pk_fma_f32 v[124:125], v[134:135], v[124:125], v[128:129]
	v_pk_fma_f32 v[122:123], v[132:133], v[122:123], v[126:127]
	v_pk_mul_f32 v[126:127], v[116:117], v[130:131] op_sel_hi:[1,0]
	v_cvt_pk_bf16_f32 v122, v122, v123
	v_cvt_pk_bf16_f32 v123, v124, v125
	global_store_dwordx2 v[108:109], v[122:123], off offset:1536
	v_pk_mul_f32 v[128:129], v[118:119], v[130:131] op_sel_hi:[1,0]
	ds_read_b128 v[116:119], v131 offset:4096
	ds_read_b128 v[122:125], v131 offset:45056
	s_waitcnt lgkmcnt(0)
	v_pk_fma_f32 v[118:119], v[128:129], v[118:119], v[124:125]
	v_pk_fma_f32 v[116:117], v[126:127], v[116:117], v[122:123]
	v_pk_mul_f32 v[122:123], v[114:115], v[130:131] op_sel_hi:[1,0]
	v_cvt_pk_bf16_f32 v116, v116, v117
	v_cvt_pk_bf16_f32 v117, v118, v119
	global_store_dwordx2 v[108:109], v[116:117], off offset:2048
	v_pk_mul_f32 v[124:125], v[120:121], v[130:131] op_sel_hi:[1,0]
	ds_read_b128 v[114:117], v131 offset:5120
	ds_read_b128 v[118:121], v131 offset:46080
	s_waitcnt lgkmcnt(0)
	v_pk_fma_f32 v[116:117], v[124:125], v[116:117], v[120:121]
	v_pk_fma_f32 v[114:115], v[122:123], v[114:115], v[118:119]
	v_pk_mul_f32 v[120:121], v[112:113], v[130:131] op_sel_hi:[1,0]
	v_cvt_pk_bf16_f32 v114, v114, v115
	v_cvt_pk_bf16_f32 v115, v116, v117
	global_store_dwordx2 v[108:109], v[114:115], off offset:2560
	ds_read_b128 v[112:115], v131 offset:6144
	ds_read_b128 v[116:119], v131 offset:47104
	s_waitcnt vmcnt(61)
	v_cvt_f32_f16_sdwa v123, v107 dst_sel:DWORD dst_unused:UNUSED_PAD src0_sel:WORD_1
	v_cvt_f32_f16_e32 v122, v107
	s_waitcnt vmcnt(59)
	v_cvt_f32_f16_sdwa v107, v102 dst_sel:DWORD dst_unused:UNUSED_PAD src0_sel:WORD_1
	s_waitcnt lgkmcnt(0)
	v_pk_fma_f32 v[114:115], v[120:121], v[114:115], v[118:119]
	v_pk_fma_f32 v[4:5], v[4:5], v[112:113], v[116:117]
	v_cvt_f32_f16_sdwa v121, v106 dst_sel:DWORD dst_unused:UNUSED_PAD src0_sel:WORD_1
	v_cvt_pk_bf16_f32 v4, v4, v5
	v_cvt_pk_bf16_f32 v5, v114, v115
	global_store_dwordx2 v[108:109], v[4:5], off offset:3072
	v_pk_mul_f32 v[4:5], v[74:75], v[130:131] op_sel_hi:[1,0]
	v_pk_mul_f32 v[74:75], v[110:111], v[130:131] op_sel_hi:[1,0]
	ds_read_b128 v[110:113], v131 offset:7168
	ds_read_b128 v[114:117], v131 offset:48128
	v_cvt_f32_f16_e32 v120, v106
	v_cvt_f32_f16_sdwa v119, v105 dst_sel:DWORD dst_unused:UNUSED_PAD src0_sel:WORD_1
	v_cvt_f32_f16_e32 v118, v105
	v_cvt_f32_f16_e32 v106, v102
	s_waitcnt lgkmcnt(0)
	v_pk_fma_f32 v[74:75], v[74:75], v[112:113], v[116:117]
	v_cvt_f32_f16_sdwa v117, v104 dst_sel:DWORD dst_unused:UNUSED_PAD src0_sel:WORD_1
	v_pk_fma_f32 v[4:5], v[4:5], v[110:111], v[114:115]
	v_cvt_f32_f16_e32 v116, v104
	v_cvt_pk_bf16_f32 v4, v4, v5
	v_cvt_pk_bf16_f32 v5, v74, v75
	global_store_dwordx2 v[108:109], v[4:5], off offset:3584
	v_cvt_f32_f16_sdwa v109, v103 dst_sel:DWORD dst_unused:UNUSED_PAD src0_sel:WORD_1
	s_waitcnt vmcnt(60)
	v_cvt_f32_f16_sdwa v111, v100 dst_sel:DWORD dst_unused:UNUSED_PAD src0_sel:WORD_1
	v_mov_b32_e32 v74, v121
	v_mov_b32_e32 v75, v117
	v_cvt_f32_f16_e32 v108, v103
	v_cvt_f32_f16_e32 v110, v100
	v_cvt_f32_f16_sdwa v113, v101 dst_sel:DWORD dst_unused:UNUSED_PAD src0_sel:WORD_1
	v_mov_b32_e32 v4, v120
	v_mov_b32_e32 v5, v116
	v_pk_mul_f32 v[74:75], v[74:75], v[74:75]
	v_mov_b32_e32 v104, v123
	v_mov_b32_e32 v105, v119
	v_cvt_f32_f16_e32 v112, v101
	v_pk_fma_f32 v[4:5], v[4:5], v[4:5], v[74:75]
	v_mov_b32_e32 v74, v122
	v_mov_b32_e32 v75, v118
	v_pk_mul_f32 v[104:105], v[104:105], v[104:105]
	v_mov_b32_e32 v102, v107
	v_pk_fma_f32 v[74:75], v[74:75], v[74:75], v[104:105]
	v_mov_b32_e32 v103, v109
	v_mul_f32_e32 v100, v111, v111
	v_pk_add_f32 v[4:5], v[4:5], v[74:75]
	v_mov_b32_e32 v74, v106
	v_mov_b32_e32 v75, v108
	v_pk_mul_f32 v[102:103], v[102:103], v[102:103]
	v_pk_fma_f32 v[104:105], v[110:111], v[110:111], v[100:101] op_sel_hi:[1,1,0]
	v_mul_f32_e32 v100, v113, v113
	v_pk_fma_f32 v[74:75], v[74:75], v[74:75], v[102:103]
	v_pk_fma_f32 v[114:115], v[112:113], v[112:113], v[100:101] op_sel_hi:[1,1,0]
	s_waitcnt vmcnt(59)
	v_cvt_f32_f16_sdwa v101, v98 dst_sel:DWORD dst_unused:UNUSED_PAD src0_sel:WORD_1
	v_cvt_f32_f16_e32 v100, v98
	v_cvt_f32_f16_sdwa v103, v99 dst_sel:DWORD dst_unused:UNUSED_PAD src0_sel:WORD_1
	v_cvt_f32_f16_e32 v102, v99
	v_pk_add_f32 v[4:5], v[4:5], v[4:5] op_sel:[0,1] op_sel_hi:[1,0]
	v_pk_add_f32 v[74:75], v[74:75], v[74:75] op_sel:[0,1] op_sel_hi:[1,0]
	v_pk_mul_f32 v[98:99], v[100:101], v[100:101]
	v_pk_mul_f32 v[124:125], v[102:103], v[102:103]
	v_mov_b32_e32 v5, v98
	v_mov_b32_e32 v75, v99
	v_mov_b32_e32 v105, v124
	v_mov_b32_e32 v115, v125
	v_pk_add_f32 v[4:5], v[4:5], v[74:75]
	v_pk_add_f32 v[74:75], v[104:105], v[114:115]
	s_waitcnt vmcnt(58)
	v_cvt_f32_f16_sdwa v99, v96 dst_sel:DWORD dst_unused:UNUSED_PAD src0_sel:WORD_1
	v_cvt_f32_f16_sdwa v105, v97 dst_sel:DWORD dst_unused:UNUSED_PAD src0_sel:WORD_1
	v_cvt_f32_f16_e32 v98, v96
	v_cvt_f32_f16_e32 v104, v97
	v_pk_add_f32 v[4:5], v[4:5], v[74:75]
	v_mov_b32_e32 v74, v99
	v_mov_b32_e32 v75, v105
	v_pk_add_f32 v[114:115], v[4:5], v[4:5] op_sel:[0,1] op_sel_hi:[1,0]
	v_mov_b32_e32 v4, v98
	v_mov_b32_e32 v5, v104
	v_pk_mul_f32 v[74:75], v[74:75], v[74:75]
	s_waitcnt vmcnt(57)
	v_cvt_f32_f16_sdwa v97, v95 dst_sel:DWORD dst_unused:UNUSED_PAD src0_sel:WORD_1
	v_pk_fma_f32 v[4:5], v[4:5], v[4:5], v[74:75]
	v_cvt_f32_f16_e32 v96, v95
	v_pk_add_f32 v[124:125], v[4:5], v[4:5] op_sel:[0,1] op_sel_hi:[1,0]
	v_cvt_f32_f16_sdwa v5, v94 dst_sel:DWORD dst_unused:UNUSED_PAD src0_sel:WORD_1
	v_cvt_f32_f16_e32 v4, v94
	s_waitcnt vmcnt(56)
	v_cvt_f32_f16_sdwa v95, v93 dst_sel:DWORD dst_unused:UNUSED_PAD src0_sel:WORD_1
	v_cvt_f32_f16_e32 v94, v93
	v_mul_f32_e32 v74, v5, v5
	v_pk_fma_f32 v[126:127], v[4:5], v[4:5], v[74:75] op_sel_hi:[1,1,0]
	v_mul_f32_e32 v74, v97, v97
	v_pk_fma_f32 v[128:129], v[96:97], v[96:97], v[74:75] op_sel_hi:[1,1,0]
	v_cvt_f32_f16_sdwa v75, v92 dst_sel:DWORD dst_unused:UNUSED_PAD src0_sel:WORD_1
	v_cvt_f32_f16_e32 v74, v92
	v_pk_mul_f32 v[130:131], v[94:95], v[94:95]
	v_pk_mul_f32 v[92:93], v[74:75], v[74:75]
	s_nop 0
	v_mov_b32_e32 v115, v92
	v_mov_b32_e32 v125, v93
	v_mov_b32_e32 v127, v130
	v_mov_b32_e32 v129, v131
	v_pk_add_f32 v[92:93], v[114:115], v[124:125]
	v_pk_add_f32 v[114:115], v[126:127], v[128:129]
	s_nop 0
	v_pk_add_f32 v[92:93], v[92:93], v[114:115]
	s_nop 0
	v_add_f32_e32 v92, v92, v93
	s_nop 1
	v_add_f32_dpp v92, v92, v92 quad_perm:[1,0,3,2] row_mask:0xf bank_mask:0xf bound_ctrl:1
	s_nop 1
	v_add_f32_dpp v92, v92, v92 quad_perm:[2,3,0,1] row_mask:0xf bank_mask:0xf bound_ctrl:1
	s_nop 1
	v_add_f32_dpp v92, v92, v92 row_half_mirror row_mask:0xf bank_mask:0xf bound_ctrl:1
	s_nop 1
	v_add_f32_dpp v92, v92, v92 row_mirror row_mask:0xf bank_mask:0xf bound_ctrl:1
	s_nop 0
	v_readlane_b32 s8, v92, 16
	v_readlane_b32 s9, v92, 48
	v_readlane_b32 s6, v92, 0
	v_readlane_b32 s7, v92, 32
	v_mov_b32_e32 v92, s8
	v_mov_b32_e32 v93, s9
	v_pk_add_f32 v[92:93], s[6:7], v[92:93]
	s_nop 0
	v_add_f32_e32 v92, v92, v93
	v_fmamk_f32 v92, v92, 0x3a000000, v252
	v_cmp_gt_f32_e32 vcc, s55, v92
	v_mul_f32_e32 v93, 0x4f800000, v92
	s_nop 0
	v_cndmask_b32_e32 v92, v92, v93, vcc
	v_sqrt_f32_e32 v93, v92
	s_nop 0
	v_add_u32_e32 v114, -1, v93
	v_fma_f32 v115, -v114, v93, v92
	v_cmp_ge_f32_e64 s[8:9], 0, v115
	v_add_u32_e32 v115, 1, v93
	s_nop 0
	v_cndmask_b32_e64 v114, v93, v114, s[8:9]
	v_fma_f32 v93, -v115, v93, v92
	v_cmp_lt_f32_e64 s[8:9], 0, v93
	s_nop 1
	v_cndmask_b32_e64 v93, v114, v115, s[8:9]
	v_mul_f32_e32 v114, 0x37800000, v93
	v_cndmask_b32_e32 v93, v93, v114, vcc
	v_cmp_class_f32_e32 vcc, v92, v253
	s_nop 1
	v_cndmask_b32_e32 v92, v93, v92, vcc
	v_div_scale_f32 v93, s[6:7], v92, v92, 1.0
	v_rcp_f32_e32 v114, v93
	s_lshl_b32 s6, s36, 1
	s_and_b32 s6, s6, 0xffffe000
	s_add_i32 s6, s6, 0
	v_fma_f32 v115, -v93, v114, 1.0
	v_fmac_f32_e32 v114, v115, v114
	v_div_scale_f32 v115, vcc, 1.0, v92, 1.0
	v_mul_f32_e32 v124, v115, v114
	v_fma_f32 v125, -v93, v124, v115
	v_fmac_f32_e32 v124, v125, v114
	v_fma_f32 v93, -v93, v124, v115
	v_div_fmas_f32 v93, v93, v114, v124
	v_div_fixup_f32 v114, v93, v92, 1.0
	v_pk_mul_f32 v[128:129], v[120:121], v[114:115] op_sel_hi:[1,0]
	v_pk_mul_f32 v[130:131], v[122:123], v[114:115] op_sel_hi:[1,0]
	v_add_u32_e32 v115, s6, v0
	ds_read_b128 v[120:123], v115
	ds_read_b128 v[124:127], v115 offset:40960
	v_lshl_add_u64 v[92:93], s[40:41], 1, v[2:3]
	v_lshl_add_u64 v[92:93], v[92:93], 0, v[6:7]
	v_pk_mul_f32 v[4:5], v[4:5], v[114:115] op_sel_hi:[1,0]
	s_waitcnt lgkmcnt(0)
	v_pk_fma_f32 v[122:123], v[122:123], v[130:131], v[126:127]
	v_pk_fma_f32 v[120:121], v[120:121], v[128:129], v[124:125]
	v_pk_mul_f32 v[124:125], v[116:117], v[114:115] op_sel_hi:[1,0]
	v_cvt_pk_bf16_f32 v120, v120, v121
	v_cvt_pk_bf16_f32 v121, v122, v123
	global_store_dwordx2 v[92:93], v[120:121], off
	v_pk_mul_f32 v[126:127], v[118:119], v[114:115] op_sel_hi:[1,0]
	ds_read_b128 v[116:119], v115 offset:1024
	ds_read_b128 v[120:123], v115 offset:41984
	s_waitcnt lgkmcnt(0)
	v_pk_fma_f32 v[118:119], v[118:119], v[126:127], v[122:123]
	v_pk_fma_f32 v[116:117], v[116:117], v[124:125], v[120:121]
	v_pk_mul_f32 v[120:121], v[106:107], v[114:115] op_sel_hi:[1,0]
	v_cvt_pk_bf16_f32 v116, v116, v117
	v_cvt_pk_bf16_f32 v117, v118, v119
	global_store_dwordx2 v[92:93], v[116:117], off offset:512
	v_pk_mul_f32 v[122:123], v[108:109], v[114:115] op_sel_hi:[1,0]
	ds_read_b128 v[106:109], v115 offset:2048
	ds_read_b128 v[116:119], v115 offset:43008
	s_waitcnt lgkmcnt(0)
	v_pk_fma_f32 v[108:109], v[108:109], v[122:123], v[118:119]
	v_pk_fma_f32 v[106:107], v[106:107], v[120:121], v[116:117]
	v_pk_mul_f32 v[116:117], v[110:111], v[114:115] op_sel_hi:[1,0]
	v_cvt_pk_bf16_f32 v106, v106, v107
	v_cvt_pk_bf16_f32 v107, v108, v109
	global_store_dwordx2 v[92:93], v[106:107], off offset:1024
	v_pk_mul_f32 v[118:119], v[112:113], v[114:115] op_sel_hi:[1,0]
	ds_read_b128 v[106:109], v115 offset:3072
	ds_read_b128 v[110:113], v115 offset:44032
	s_waitcnt lgkmcnt(0)
	v_pk_fma_f32 v[108:109], v[118:119], v[108:109], v[112:113]
	v_pk_fma_f32 v[106:107], v[116:117], v[106:107], v[110:111]
	v_pk_mul_f32 v[110:111], v[100:101], v[114:115] op_sel_hi:[1,0]
	v_cvt_pk_bf16_f32 v106, v106, v107
	v_cvt_pk_bf16_f32 v107, v108, v109
	global_store_dwordx2 v[92:93], v[106:107], off offset:1536
	v_pk_mul_f32 v[112:113], v[102:103], v[114:115] op_sel_hi:[1,0]
	ds_read_b128 v[100:103], v115 offset:4096
	ds_read_b128 v[106:109], v115 offset:45056
	s_waitcnt lgkmcnt(0)
	v_pk_fma_f32 v[102:103], v[112:113], v[102:103], v[108:109]
	v_pk_fma_f32 v[100:101], v[110:111], v[100:101], v[106:107]
	v_pk_mul_f32 v[106:107], v[98:99], v[114:115] op_sel_hi:[1,0]
	v_cvt_pk_bf16_f32 v100, v100, v101
	v_cvt_pk_bf16_f32 v101, v102, v103
	global_store_dwordx2 v[92:93], v[100:101], off offset:2048
	v_pk_mul_f32 v[108:109], v[104:105], v[114:115] op_sel_hi:[1,0]
	ds_read_b128 v[98:101], v115 offset:5120
	ds_read_b128 v[102:105], v115 offset:46080
	s_waitcnt lgkmcnt(0)
	v_pk_fma_f32 v[100:101], v[108:109], v[100:101], v[104:105]
	v_pk_fma_f32 v[98:99], v[106:107], v[98:99], v[102:103]
	v_pk_mul_f32 v[104:105], v[96:97], v[114:115] op_sel_hi:[1,0]
	v_cvt_pk_bf16_f32 v98, v98, v99
	v_cvt_pk_bf16_f32 v99, v100, v101
	global_store_dwordx2 v[92:93], v[98:99], off offset:2560
	ds_read_b128 v[96:99], v115 offset:6144
	ds_read_b128 v[100:103], v115 offset:47104
	s_waitcnt vmcnt(61)
	v_cvt_f32_f16_sdwa v107, v91 dst_sel:DWORD dst_unused:UNUSED_PAD src0_sel:WORD_1
	v_cvt_f32_f16_e32 v106, v91
	s_waitcnt vmcnt(59)
	v_cvt_f32_f16_sdwa v91, v86 dst_sel:DWORD dst_unused:UNUSED_PAD src0_sel:WORD_1
	s_waitcnt lgkmcnt(0)
	v_pk_fma_f32 v[98:99], v[104:105], v[98:99], v[102:103]
	v_pk_fma_f32 v[4:5], v[4:5], v[96:97], v[100:101]
	v_cvt_f32_f16_sdwa v105, v90 dst_sel:DWORD dst_unused:UNUSED_PAD src0_sel:WORD_1
	v_cvt_pk_bf16_f32 v4, v4, v5
	v_cvt_pk_bf16_f32 v5, v98, v99
	global_store_dwordx2 v[92:93], v[4:5], off offset:3072
	v_pk_mul_f32 v[4:5], v[74:75], v[114:115] op_sel_hi:[1,0]
	v_pk_mul_f32 v[74:75], v[94:95], v[114:115] op_sel_hi:[1,0]
	ds_read_b128 v[94:97], v115 offset:7168
	ds_read_b128 v[98:101], v115 offset:48128
	v_cvt_f32_f16_e32 v104, v90
	v_cvt_f32_f16_sdwa v103, v89 dst_sel:DWORD dst_unused:UNUSED_PAD src0_sel:WORD_1
	v_cvt_f32_f16_e32 v102, v89
	v_cvt_f32_f16_e32 v90, v86
	s_waitcnt lgkmcnt(0)
	v_pk_fma_f32 v[74:75], v[74:75], v[96:97], v[100:101]
	v_cvt_f32_f16_sdwa v101, v88 dst_sel:DWORD dst_unused:UNUSED_PAD src0_sel:WORD_1
	v_pk_fma_f32 v[4:5], v[4:5], v[94:95], v[98:99]
	v_cvt_f32_f16_e32 v100, v88
	v_cvt_pk_bf16_f32 v4, v4, v5
	v_cvt_pk_bf16_f32 v5, v74, v75
	global_store_dwordx2 v[92:93], v[4:5], off offset:3584
	v_cvt_f32_f16_sdwa v93, v87 dst_sel:DWORD dst_unused:UNUSED_PAD src0_sel:WORD_1
	s_waitcnt vmcnt(60)
	v_cvt_f32_f16_sdwa v95, v84 dst_sel:DWORD dst_unused:UNUSED_PAD src0_sel:WORD_1
	v_mov_b32_e32 v74, v105
	v_mov_b32_e32 v75, v101
	v_cvt_f32_f16_e32 v92, v87
	v_cvt_f32_f16_e32 v94, v84
	v_cvt_f32_f16_sdwa v97, v85 dst_sel:DWORD dst_unused:UNUSED_PAD src0_sel:WORD_1
	v_mov_b32_e32 v4, v104
	v_mov_b32_e32 v5, v100
	v_pk_mul_f32 v[74:75], v[74:75], v[74:75]
	v_mov_b32_e32 v88, v107
	v_mov_b32_e32 v89, v103
	v_cvt_f32_f16_e32 v96, v85
	v_pk_fma_f32 v[4:5], v[4:5], v[4:5], v[74:75]
	v_mov_b32_e32 v74, v106
	v_mov_b32_e32 v75, v102
	v_pk_mul_f32 v[88:89], v[88:89], v[88:89]
	v_mov_b32_e32 v86, v91
	v_pk_fma_f32 v[74:75], v[74:75], v[74:75], v[88:89]
	v_mov_b32_e32 v87, v93
	v_mul_f32_e32 v84, v95, v95
	v_pk_add_f32 v[4:5], v[4:5], v[74:75]
	v_mov_b32_e32 v74, v90
	v_mov_b32_e32 v75, v92
	v_pk_mul_f32 v[86:87], v[86:87], v[86:87]
	v_pk_fma_f32 v[88:89], v[94:95], v[94:95], v[84:85] op_sel_hi:[1,1,0]
	v_mul_f32_e32 v84, v97, v97
	v_pk_fma_f32 v[74:75], v[74:75], v[74:75], v[86:87]
	v_pk_fma_f32 v[98:99], v[96:97], v[96:97], v[84:85] op_sel_hi:[1,1,0]
	s_waitcnt vmcnt(59)
	v_cvt_f32_f16_sdwa v85, v82 dst_sel:DWORD dst_unused:UNUSED_PAD src0_sel:WORD_1
	v_cvt_f32_f16_e32 v84, v82
	v_cvt_f32_f16_sdwa v87, v83 dst_sel:DWORD dst_unused:UNUSED_PAD src0_sel:WORD_1
	v_cvt_f32_f16_e32 v86, v83
	v_pk_add_f32 v[4:5], v[4:5], v[4:5] op_sel:[0,1] op_sel_hi:[1,0]
	v_pk_add_f32 v[74:75], v[74:75], v[74:75] op_sel:[0,1] op_sel_hi:[1,0]
	v_pk_mul_f32 v[82:83], v[84:85], v[84:85]
	v_pk_mul_f32 v[108:109], v[86:87], v[86:87]
	v_mov_b32_e32 v5, v82
	v_mov_b32_e32 v75, v83
	v_mov_b32_e32 v89, v108
	v_mov_b32_e32 v99, v109
	v_pk_add_f32 v[4:5], v[4:5], v[74:75]
	v_pk_add_f32 v[74:75], v[88:89], v[98:99]
	s_waitcnt vmcnt(58)
	v_cvt_f32_f16_sdwa v83, v80 dst_sel:DWORD dst_unused:UNUSED_PAD src0_sel:WORD_1
	v_cvt_f32_f16_sdwa v89, v81 dst_sel:DWORD dst_unused:UNUSED_PAD src0_sel:WORD_1
	v_cvt_f32_f16_e32 v82, v80
	v_cvt_f32_f16_e32 v88, v81
	v_pk_add_f32 v[4:5], v[4:5], v[74:75]
	v_mov_b32_e32 v74, v83
	v_mov_b32_e32 v75, v89
	v_pk_add_f32 v[98:99], v[4:5], v[4:5] op_sel:[0,1] op_sel_hi:[1,0]
	v_mov_b32_e32 v4, v82
	v_mov_b32_e32 v5, v88
	v_pk_mul_f32 v[74:75], v[74:75], v[74:75]
	s_waitcnt vmcnt(57)
	v_cvt_f32_f16_sdwa v81, v79 dst_sel:DWORD dst_unused:UNUSED_PAD src0_sel:WORD_1
	v_pk_fma_f32 v[4:5], v[4:5], v[4:5], v[74:75]
	v_cvt_f32_f16_e32 v80, v79
	v_pk_add_f32 v[108:109], v[4:5], v[4:5] op_sel:[0,1] op_sel_hi:[1,0]
	v_cvt_f32_f16_sdwa v5, v78 dst_sel:DWORD dst_unused:UNUSED_PAD src0_sel:WORD_1
	v_cvt_f32_f16_e32 v4, v78
	s_waitcnt vmcnt(56)
	v_cvt_f32_f16_sdwa v79, v77 dst_sel:DWORD dst_unused:UNUSED_PAD src0_sel:WORD_1
	v_cvt_f32_f16_e32 v78, v77
	v_mul_f32_e32 v74, v5, v5
	v_pk_fma_f32 v[110:111], v[4:5], v[4:5], v[74:75] op_sel_hi:[1,1,0]
	v_mul_f32_e32 v74, v81, v81
	v_pk_fma_f32 v[112:113], v[80:81], v[80:81], v[74:75] op_sel_hi:[1,1,0]
	v_cvt_f32_f16_sdwa v75, v76 dst_sel:DWORD dst_unused:UNUSED_PAD src0_sel:WORD_1
	v_cvt_f32_f16_e32 v74, v76
	v_pk_mul_f32 v[114:115], v[78:79], v[78:79]
	v_pk_mul_f32 v[76:77], v[74:75], v[74:75]
	s_nop 0
	v_mov_b32_e32 v99, v76
	v_mov_b32_e32 v109, v77
	v_mov_b32_e32 v111, v114
	v_mov_b32_e32 v113, v115
	v_pk_add_f32 v[76:77], v[98:99], v[108:109]
	v_pk_add_f32 v[98:99], v[110:111], v[112:113]
	s_nop 0
	v_pk_add_f32 v[76:77], v[76:77], v[98:99]
	s_nop 0
	v_add_f32_e32 v76, v76, v77
	s_nop 1
	v_add_f32_dpp v76, v76, v76 quad_perm:[1,0,3,2] row_mask:0xf bank_mask:0xf bound_ctrl:1
	s_nop 1
	v_add_f32_dpp v76, v76, v76 quad_perm:[2,3,0,1] row_mask:0xf bank_mask:0xf bound_ctrl:1
	s_nop 1
	v_add_f32_dpp v76, v76, v76 row_half_mirror row_mask:0xf bank_mask:0xf bound_ctrl:1
	s_nop 1
	v_add_f32_dpp v76, v76, v76 row_mirror row_mask:0xf bank_mask:0xf bound_ctrl:1
	s_nop 0
	v_readlane_b32 s8, v76, 16
	v_readlane_b32 s9, v76, 48
	v_readlane_b32 s6, v76, 0
	v_readlane_b32 s7, v76, 32
	v_mov_b32_e32 v76, s8
	v_mov_b32_e32 v77, s9
	v_pk_add_f32 v[76:77], s[6:7], v[76:77]
	s_nop 0
	v_add_f32_e32 v76, v76, v77
	v_fmamk_f32 v76, v76, 0x3a000000, v252
	v_cmp_gt_f32_e32 vcc, s55, v76
	v_mul_f32_e32 v77, 0x4f800000, v76
	s_nop 0
	v_cndmask_b32_e32 v76, v76, v77, vcc
	v_sqrt_f32_e32 v77, v76
	s_nop 0
	v_add_u32_e32 v98, -1, v77
	v_fma_f32 v99, -v98, v77, v76
	v_cmp_ge_f32_e64 s[8:9], 0, v99
	v_add_u32_e32 v99, 1, v77
	s_nop 0
	v_cndmask_b32_e64 v98, v77, v98, s[8:9]
	v_fma_f32 v77, -v99, v77, v76
	v_cmp_lt_f32_e64 s[8:9], 0, v77
	s_nop 1
	v_cndmask_b32_e64 v77, v98, v99, s[8:9]
	v_mul_f32_e32 v98, 0x37800000, v77
	v_cndmask_b32_e32 v77, v77, v98, vcc
	v_cmp_class_f32_e32 vcc, v76, v253
	s_nop 1
	v_cndmask_b32_e32 v76, v77, v76, vcc
	v_div_scale_f32 v77, s[6:7], v76, v76, 1.0
	v_rcp_f32_e32 v98, v77
	s_lshl_b32 s6, s30, 1
	s_and_b32 s6, s6, 0xffffe000
	s_add_i32 s6, s6, 0
	v_fma_f32 v99, -v77, v98, 1.0
	v_fmac_f32_e32 v98, v99, v98
	v_div_scale_f32 v99, vcc, 1.0, v76, 1.0
	v_mul_f32_e32 v108, v99, v98
	v_fma_f32 v109, -v77, v108, v99
	v_fmac_f32_e32 v108, v109, v98
	v_fma_f32 v77, -v77, v108, v99
	v_div_fmas_f32 v77, v77, v98, v108
	v_div_fixup_f32 v98, v77, v76, 1.0
	v_pk_mul_f32 v[112:113], v[104:105], v[98:99] op_sel_hi:[1,0]
	v_pk_mul_f32 v[114:115], v[106:107], v[98:99] op_sel_hi:[1,0]
	v_add_u32_e32 v99, s6, v0
	ds_read_b128 v[104:107], v99
	ds_read_b128 v[108:111], v99 offset:40960
	v_lshl_add_u64 v[76:77], s[34:35], 1, v[2:3]
	v_lshl_add_u64 v[76:77], v[76:77], 0, v[6:7]
	v_pk_mul_f32 v[4:5], v[4:5], v[98:99] op_sel_hi:[1,0]
	s_waitcnt lgkmcnt(0)
	v_pk_fma_f32 v[106:107], v[106:107], v[114:115], v[110:111]
	v_pk_fma_f32 v[104:105], v[104:105], v[112:113], v[108:109]
	v_pk_mul_f32 v[108:109], v[100:101], v[98:99] op_sel_hi:[1,0]
	v_cvt_pk_bf16_f32 v104, v104, v105
	v_cvt_pk_bf16_f32 v105, v106, v107
	global_store_dwordx2 v[76:77], v[104:105], off
	v_pk_mul_f32 v[110:111], v[102:103], v[98:99] op_sel_hi:[1,0]
	ds_read_b128 v[100:103], v99 offset:1024
	ds_read_b128 v[104:107], v99 offset:41984
	s_waitcnt lgkmcnt(0)
	v_pk_fma_f32 v[102:103], v[102:103], v[110:111], v[106:107]
	v_pk_fma_f32 v[100:101], v[100:101], v[108:109], v[104:105]
	v_pk_mul_f32 v[104:105], v[90:91], v[98:99] op_sel_hi:[1,0]
	v_cvt_pk_bf16_f32 v100, v100, v101
	v_cvt_pk_bf16_f32 v101, v102, v103
	global_store_dwordx2 v[76:77], v[100:101], off offset:512
	v_pk_mul_f32 v[106:107], v[92:93], v[98:99] op_sel_hi:[1,0]
	ds_read_b128 v[90:93], v99 offset:2048
	ds_read_b128 v[100:103], v99 offset:43008
	s_waitcnt lgkmcnt(0)
	v_pk_fma_f32 v[92:93], v[92:93], v[106:107], v[102:103]
	v_pk_fma_f32 v[90:91], v[90:91], v[104:105], v[100:101]
	v_pk_mul_f32 v[100:101], v[94:95], v[98:99] op_sel_hi:[1,0]
	v_cvt_pk_bf16_f32 v90, v90, v91
	v_cvt_pk_bf16_f32 v91, v92, v93
	global_store_dwordx2 v[76:77], v[90:91], off offset:1024
	v_pk_mul_f32 v[102:103], v[96:97], v[98:99] op_sel_hi:[1,0]
	ds_read_b128 v[90:93], v99 offset:3072
	ds_read_b128 v[94:97], v99 offset:44032
	s_waitcnt lgkmcnt(0)
	v_pk_fma_f32 v[92:93], v[102:103], v[92:93], v[96:97]
	v_pk_fma_f32 v[90:91], v[100:101], v[90:91], v[94:95]
	v_pk_mul_f32 v[94:95], v[84:85], v[98:99] op_sel_hi:[1,0]
	v_cvt_pk_bf16_f32 v90, v90, v91
	v_cvt_pk_bf16_f32 v91, v92, v93
	global_store_dwordx2 v[76:77], v[90:91], off offset:1536
	v_pk_mul_f32 v[96:97], v[86:87], v[98:99] op_sel_hi:[1,0]
	ds_read_b128 v[84:87], v99 offset:4096
	ds_read_b128 v[90:93], v99 offset:45056
	s_waitcnt lgkmcnt(0)
	v_pk_fma_f32 v[86:87], v[96:97], v[86:87], v[92:93]
	v_pk_fma_f32 v[84:85], v[94:95], v[84:85], v[90:91]
	v_pk_mul_f32 v[90:91], v[82:83], v[98:99] op_sel_hi:[1,0]
	v_cvt_pk_bf16_f32 v84, v84, v85
	v_cvt_pk_bf16_f32 v85, v86, v87
	global_store_dwordx2 v[76:77], v[84:85], off offset:2048
	v_pk_mul_f32 v[92:93], v[88:89], v[98:99] op_sel_hi:[1,0]
	ds_read_b128 v[82:85], v99 offset:5120
	ds_read_b128 v[86:89], v99 offset:46080
	s_waitcnt lgkmcnt(0)
	v_pk_fma_f32 v[84:85], v[92:93], v[84:85], v[88:89]
	v_pk_fma_f32 v[82:83], v[90:91], v[82:83], v[86:87]
	v_pk_mul_f32 v[88:89], v[80:81], v[98:99] op_sel_hi:[1,0]
	v_cvt_pk_bf16_f32 v82, v82, v83
	v_cvt_pk_bf16_f32 v83, v84, v85
	global_store_dwordx2 v[76:77], v[82:83], off offset:2560
	ds_read_b128 v[80:83], v99 offset:6144
	ds_read_b128 v[84:87], v99 offset:47104
	s_waitcnt vmcnt(61)
	v_cvt_f32_f16_sdwa v91, v73 dst_sel:DWORD dst_unused:UNUSED_PAD src0_sel:WORD_1
	v_cvt_f32_f16_e32 v90, v73
	s_waitcnt lgkmcnt(0)
	v_pk_fma_f32 v[82:83], v[88:89], v[82:83], v[86:87]
	v_pk_fma_f32 v[4:5], v[4:5], v[80:81], v[84:85]
	v_cvt_f32_f16_sdwa v89, v72 dst_sel:DWORD dst_unused:UNUSED_PAD src0_sel:WORD_1
	v_cvt_pk_bf16_f32 v4, v4, v5
	v_cvt_pk_bf16_f32 v5, v82, v83
	global_store_dwordx2 v[76:77], v[4:5], off offset:3072
	v_pk_mul_f32 v[4:5], v[74:75], v[98:99] op_sel_hi:[1,0]
	v_pk_mul_f32 v[74:75], v[78:79], v[98:99] op_sel_hi:[1,0]
	ds_read_b128 v[78:81], v99 offset:7168
	ds_read_b128 v[82:85], v99 offset:48128
	v_cvt_f32_f16_e32 v88, v72
	s_waitcnt vmcnt(61)
	v_cvt_f32_f16_sdwa v87, v71 dst_sel:DWORD dst_unused:UNUSED_PAD src0_sel:WORD_1
	v_cvt_f32_f16_e32 v86, v71
	v_mov_b32_e32 v72, v91
	s_waitcnt lgkmcnt(0)
	v_pk_fma_f32 v[74:75], v[74:75], v[80:81], v[84:85]
	v_cvt_f32_f16_sdwa v85, v70 dst_sel:DWORD dst_unused:UNUSED_PAD src0_sel:WORD_1
	v_cvt_f32_f16_e32 v84, v70
	v_pk_fma_f32 v[4:5], v[4:5], v[78:79], v[82:83]
	v_mov_b32_e32 v70, v89
	v_cvt_pk_bf16_f32 v4, v4, v5
	v_cvt_pk_bf16_f32 v5, v74, v75
	global_store_dwordx2 v[76:77], v[4:5], off offset:3584
	v_mov_b32_e32 v71, v85
	s_waitcnt vmcnt(61)
	v_cvt_f32_f16_sdwa v75, v68 dst_sel:DWORD dst_unused:UNUSED_PAD src0_sel:WORD_1
	v_cvt_f32_f16_sdwa v77, v69 dst_sel:DWORD dst_unused:UNUSED_PAD src0_sel:WORD_1
	v_mov_b32_e32 v4, v88
	v_mov_b32_e32 v5, v84
	v_pk_mul_f32 v[70:71], v[70:71], v[70:71]
	v_mov_b32_e32 v73, v87
	v_cvt_f32_f16_e32 v74, v68
	v_cvt_f32_f16_e32 v76, v69
	s_waitcnt vmcnt(60)
	v_cvt_f32_f16_sdwa v79, v66 dst_sel:DWORD dst_unused:UNUSED_PAD src0_sel:WORD_1
	v_pk_fma_f32 v[4:5], v[4:5], v[4:5], v[70:71]
	v_mov_b32_e32 v70, v90
	v_mov_b32_e32 v71, v86
	v_pk_mul_f32 v[72:73], v[72:73], v[72:73]
	v_cvt_f32_f16_e32 v78, v66
	v_cvt_f32_f16_sdwa v81, v67 dst_sel:DWORD dst_unused:UNUSED_PAD src0_sel:WORD_1
	v_pk_fma_f32 v[70:71], v[70:71], v[70:71], v[72:73]
	v_cvt_f32_f16_e32 v80, v67
	v_pk_add_f32 v[4:5], v[4:5], v[70:71]
	v_mov_b32_e32 v70, v75
	v_mov_b32_e32 v71, v77
	v_mov_b32_e32 v68, v74
	v_mov_b32_e32 v69, v76
	v_pk_mul_f32 v[70:71], v[70:71], v[70:71]
	v_mul_f32_e32 v66, v79, v79
	v_pk_fma_f32 v[68:69], v[68:69], v[68:69], v[70:71]
	v_pk_fma_f32 v[72:73], v[78:79], v[78:79], v[66:67] op_sel_hi:[1,1,0]
	v_mul_f32_e32 v66, v81, v81
	v_pk_add_f32 v[70:71], v[68:69], v[68:69] op_sel:[0,1] op_sel_hi:[1,0]
	v_pk_fma_f32 v[82:83], v[80:81], v[80:81], v[66:67] op_sel_hi:[1,1,0]
	s_waitcnt vmcnt(59)
	v_cvt_f32_f16_sdwa v67, v64 dst_sel:DWORD dst_unused:UNUSED_PAD src0_sel:WORD_1
	v_cvt_f32_f16_e32 v66, v64
	v_cvt_f32_f16_sdwa v69, v65 dst_sel:DWORD dst_unused:UNUSED_PAD src0_sel:WORD_1
	v_cvt_f32_f16_e32 v68, v65
	v_pk_add_f32 v[4:5], v[4:5], v[4:5] op_sel:[0,1] op_sel_hi:[1,0]
	v_pk_mul_f32 v[64:65], v[66:67], v[66:67]
	v_pk_mul_f32 v[92:93], v[68:69], v[68:69]
	v_mov_b32_e32 v5, v64
	v_mov_b32_e32 v71, v65
	v_mov_b32_e32 v73, v92
	v_mov_b32_e32 v83, v93
	v_pk_add_f32 v[4:5], v[4:5], v[70:71]
	v_pk_add_f32 v[64:65], v[72:73], v[82:83]
	s_waitcnt vmcnt(58)
	v_cvt_f32_f16_sdwa v71, v62 dst_sel:DWORD dst_unused:UNUSED_PAD src0_sel:WORD_1
	v_cvt_f32_f16_sdwa v73, v63 dst_sel:DWORD dst_unused:UNUSED_PAD src0_sel:WORD_1
	v_cvt_f32_f16_e32 v70, v62
	v_cvt_f32_f16_e32 v72, v63
	v_pk_add_f32 v[4:5], v[4:5], v[64:65]
	v_mov_b32_e32 v62, v71
	v_mov_b32_e32 v63, v73
	v_pk_add_f32 v[82:83], v[4:5], v[4:5] op_sel:[0,1] op_sel_hi:[1,0]
	v_mov_b32_e32 v4, v70
	v_mov_b32_e32 v5, v72
	v_pk_mul_f32 v[62:63], v[62:63], v[62:63]
	s_waitcnt vmcnt(56)
	v_cvt_f32_f16_sdwa v65, v59 dst_sel:DWORD dst_unused:UNUSED_PAD src0_sel:WORD_1
	v_pk_fma_f32 v[4:5], v[4:5], v[4:5], v[62:63]
	v_cvt_f32_f16_sdwa v63, v61 dst_sel:DWORD dst_unused:UNUSED_PAD src0_sel:WORD_1
	v_pk_add_f32 v[92:93], v[4:5], v[4:5] op_sel:[0,1] op_sel_hi:[1,0]
	v_cvt_f32_f16_sdwa v5, v60 dst_sel:DWORD dst_unused:UNUSED_PAD src0_sel:WORD_1
	v_cvt_f32_f16_e32 v4, v60
	v_cvt_f32_f16_e32 v62, v61
	v_cvt_f32_f16_e32 v64, v59
	v_mul_f32_e32 v60, v5, v5
	v_pk_fma_f32 v[94:95], v[4:5], v[4:5], v[60:61] op_sel_hi:[1,1,0]
	v_mul_f32_e32 v60, v63, v63
	v_pk_fma_f32 v[96:97], v[62:63], v[62:63], v[60:61] op_sel_hi:[1,1,0]
	v_cvt_f32_f16_sdwa v61, v58 dst_sel:DWORD dst_unused:UNUSED_PAD src0_sel:WORD_1
	v_cvt_f32_f16_e32 v60, v58
	v_pk_mul_f32 v[98:99], v[64:65], v[64:65]
	v_pk_mul_f32 v[58:59], v[60:61], v[60:61]
	s_nop 0
	v_mov_b32_e32 v83, v58
	v_mov_b32_e32 v93, v59
	v_mov_b32_e32 v95, v98
	v_mov_b32_e32 v97, v99
	v_pk_add_f32 v[58:59], v[82:83], v[92:93]
	v_pk_add_f32 v[82:83], v[94:95], v[96:97]
	s_nop 0
	v_pk_add_f32 v[58:59], v[58:59], v[82:83]
	s_nop 0
	v_add_f32_e32 v58, v58, v59
	s_nop 1
	v_add_f32_dpp v58, v58, v58 quad_perm:[1,0,3,2] row_mask:0xf bank_mask:0xf bound_ctrl:1
	s_nop 1
	v_add_f32_dpp v58, v58, v58 quad_perm:[2,3,0,1] row_mask:0xf bank_mask:0xf bound_ctrl:1
	s_nop 1
	v_add_f32_dpp v58, v58, v58 row_half_mirror row_mask:0xf bank_mask:0xf bound_ctrl:1
	s_nop 1
	v_add_f32_dpp v58, v58, v58 row_mirror row_mask:0xf bank_mask:0xf bound_ctrl:1
	s_nop 0
	v_readlane_b32 s8, v58, 16
	v_readlane_b32 s9, v58, 48
	v_readlane_b32 s6, v58, 0
	v_readlane_b32 s7, v58, 32
	v_mov_b32_e32 v58, s8
	v_mov_b32_e32 v59, s9
	v_pk_add_f32 v[58:59], s[6:7], v[58:59]
	s_nop 0
	v_add_f32_e32 v58, v58, v59
	v_fmamk_f32 v58, v58, 0x3a000000, v252
	v_cmp_gt_f32_e32 vcc, s55, v58
	v_mul_f32_e32 v59, 0x4f800000, v58
	s_nop 0
	v_cndmask_b32_e32 v58, v58, v59, vcc
	v_sqrt_f32_e32 v59, v58
	s_nop 0
	v_add_u32_e32 v82, -1, v59
	v_fma_f32 v83, -v82, v59, v58
	v_cmp_ge_f32_e64 s[8:9], 0, v83
	v_add_u32_e32 v83, 1, v59
	s_nop 0
	v_cndmask_b32_e64 v82, v59, v82, s[8:9]
	v_fma_f32 v59, -v83, v59, v58
	v_cmp_lt_f32_e64 s[8:9], 0, v59
	s_nop 1
	v_cndmask_b32_e64 v59, v82, v83, s[8:9]
	v_mul_f32_e32 v82, 0x37800000, v59
	v_cndmask_b32_e32 v59, v59, v82, vcc
	v_cmp_class_f32_e32 vcc, v58, v253
	s_nop 1
	v_cndmask_b32_e32 v58, v59, v58, vcc
	v_div_scale_f32 v59, s[6:7], v58, v58, 1.0
	v_rcp_f32_e32 v82, v59
	s_lshl_b32 s6, s26, 1
	s_and_b32 s6, s6, 0xffffe000
	s_add_i32 s6, s6, 0
	v_fma_f32 v83, -v59, v82, 1.0
	v_fmac_f32_e32 v82, v83, v82
	v_div_scale_f32 v83, vcc, 1.0, v58, 1.0
	v_mul_f32_e32 v92, v83, v82
	v_fma_f32 v93, -v59, v92, v83
	v_fmac_f32_e32 v92, v93, v82
	v_fma_f32 v59, -v59, v92, v83
	v_div_fmas_f32 v59, v59, v82, v92
	v_div_fixup_f32 v82, v59, v58, 1.0
	v_pk_mul_f32 v[96:97], v[88:89], v[82:83] op_sel_hi:[1,0]
	v_pk_mul_f32 v[98:99], v[90:91], v[82:83] op_sel_hi:[1,0]
	v_add_u32_e32 v83, s6, v0
	ds_read_b128 v[88:91], v83
	ds_read_b128 v[92:95], v83 offset:40960
	v_lshl_add_u64 v[58:59], s[28:29], 1, v[2:3]
	v_lshl_add_u64 v[58:59], v[58:59], 0, v[6:7]
	v_pk_mul_f32 v[4:5], v[4:5], v[82:83] op_sel_hi:[1,0]
	v_pk_mul_f32 v[62:63], v[62:63], v[82:83] op_sel_hi:[1,0]
	s_waitcnt lgkmcnt(0)
	v_pk_fma_f32 v[90:91], v[90:91], v[98:99], v[94:95]
	v_pk_fma_f32 v[88:89], v[88:89], v[96:97], v[92:93]
	v_pk_mul_f32 v[92:93], v[84:85], v[82:83] op_sel_hi:[1,0]
	v_cvt_pk_bf16_f32 v88, v88, v89
	v_cvt_pk_bf16_f32 v89, v90, v91
	global_store_dwordx2 v[58:59], v[88:89], off
	v_pk_mul_f32 v[94:95], v[86:87], v[82:83] op_sel_hi:[1,0]
	ds_read_b128 v[84:87], v83 offset:1024
	ds_read_b128 v[88:91], v83 offset:41984
	s_waitcnt lgkmcnt(0)
	v_pk_fma_f32 v[86:87], v[86:87], v[94:95], v[90:91]
	v_pk_fma_f32 v[84:85], v[84:85], v[92:93], v[88:89]
	v_pk_mul_f32 v[88:89], v[74:75], v[82:83] op_sel_hi:[1,0]
	v_cvt_pk_bf16_f32 v84, v84, v85
	v_cvt_pk_bf16_f32 v85, v86, v87
	global_store_dwordx2 v[58:59], v[84:85], off offset:512
	v_pk_mul_f32 v[90:91], v[76:77], v[82:83] op_sel_hi:[1,0]
	ds_read_b128 v[74:77], v83 offset:2048
	ds_read_b128 v[84:87], v83 offset:43008
	s_waitcnt lgkmcnt(0)
	v_pk_fma_f32 v[76:77], v[76:77], v[90:91], v[86:87]
	v_pk_fma_f32 v[74:75], v[74:75], v[88:89], v[84:85]
	v_pk_mul_f32 v[84:85], v[78:79], v[82:83] op_sel_hi:[1,0]
	v_cvt_pk_bf16_f32 v74, v74, v75
	v_cvt_pk_bf16_f32 v75, v76, v77
	global_store_dwordx2 v[58:59], v[74:75], off offset:1024
	v_pk_mul_f32 v[86:87], v[80:81], v[82:83] op_sel_hi:[1,0]
	ds_read_b128 v[74:77], v83 offset:3072
	ds_read_b128 v[78:81], v83 offset:44032
	s_waitcnt lgkmcnt(0)
	v_pk_fma_f32 v[76:77], v[86:87], v[76:77], v[80:81]
	v_pk_fma_f32 v[74:75], v[84:85], v[74:75], v[78:79]
	v_pk_mul_f32 v[78:79], v[66:67], v[82:83] op_sel_hi:[1,0]
	v_cvt_pk_bf16_f32 v74, v74, v75
	v_cvt_pk_bf16_f32 v75, v76, v77
	global_store_dwordx2 v[58:59], v[74:75], off offset:1536
	v_pk_mul_f32 v[80:81], v[68:69], v[82:83] op_sel_hi:[1,0]
	ds_read_b128 v[66:69], v83 offset:4096
	ds_read_b128 v[74:77], v83 offset:45056
	s_waitcnt lgkmcnt(0)
	v_pk_fma_f32 v[68:69], v[80:81], v[68:69], v[76:77]
	v_pk_fma_f32 v[66:67], v[78:79], v[66:67], v[74:75]
	v_pk_mul_f32 v[74:75], v[70:71], v[82:83] op_sel_hi:[1,0]
	v_cvt_pk_bf16_f32 v66, v66, v67
	v_cvt_pk_bf16_f32 v67, v68, v69
	global_store_dwordx2 v[58:59], v[66:67], off offset:2048
	v_pk_mul_f32 v[76:77], v[72:73], v[82:83] op_sel_hi:[1,0]
	ds_read_b128 v[66:69], v83 offset:5120
	ds_read_b128 v[70:73], v83 offset:46080
	s_waitcnt lgkmcnt(0)
	v_pk_fma_f32 v[68:69], v[76:77], v[68:69], v[72:73]
	v_pk_fma_f32 v[66:67], v[74:75], v[66:67], v[70:71]
	s_waitcnt vmcnt(60)
	v_cvt_f32_f16_sdwa v75, v57 dst_sel:DWORD dst_unused:UNUSED_PAD src0_sel:WORD_1
	v_cvt_pk_bf16_f32 v66, v66, v67
	v_cvt_pk_bf16_f32 v67, v68, v69
	global_store_dwordx2 v[58:59], v[66:67], off offset:2560
	ds_read_b128 v[66:69], v83 offset:6144
	ds_read_b128 v[70:73], v83 offset:47104
	v_cvt_f32_f16_e32 v74, v57
	s_waitcnt lgkmcnt(0)
	v_pk_fma_f32 v[62:63], v[62:63], v[68:69], v[72:73]
	v_pk_fma_f32 v[4:5], v[4:5], v[66:67], v[70:71]
	v_pk_mul_f32 v[68:69], v[64:65], v[82:83] op_sel_hi:[1,0]
	v_cvt_pk_bf16_f32 v4, v4, v5
	v_cvt_pk_bf16_f32 v5, v62, v63
	global_store_dwordx2 v[58:59], v[4:5], off offset:3072
	v_pk_mul_f32 v[4:5], v[60:61], v[82:83] op_sel_hi:[1,0]
	ds_read_b128 v[60:63], v83 offset:7168
	ds_read_b128 v[64:67], v83 offset:48128
	v_cvt_f32_f16_sdwa v73, v56 dst_sel:DWORD dst_unused:UNUSED_PAD src0_sel:WORD_1
	v_cvt_f32_f16_e32 v72, v56
	s_waitcnt vmcnt(61)
	v_cvt_f32_f16_sdwa v71, v55 dst_sel:DWORD dst_unused:UNUSED_PAD src0_sel:WORD_1
	v_cvt_f32_f16_e32 v70, v55
	s_waitcnt lgkmcnt(0)
	v_pk_fma_f32 v[62:63], v[68:69], v[62:63], v[66:67]
	v_cvt_f32_f16_sdwa v69, v54 dst_sel:DWORD dst_unused:UNUSED_PAD src0_sel:WORD_1
	v_cvt_f32_f16_e32 v68, v54
	v_pk_fma_f32 v[4:5], v[4:5], v[60:61], v[64:65]
	v_mov_b32_e32 v54, v73
	v_cvt_pk_bf16_f32 v4, v4, v5
	v_cvt_pk_bf16_f32 v5, v62, v63
	global_store_dwordx2 v[58:59], v[4:5], off offset:3584
	v_mov_b32_e32 v55, v69
	s_waitcnt vmcnt(61)
	v_cvt_f32_f16_sdwa v59, v52 dst_sel:DWORD dst_unused:UNUSED_PAD src0_sel:WORD_1
	v_cvt_f32_f16_sdwa v61, v53 dst_sel:DWORD dst_unused:UNUSED_PAD src0_sel:WORD_1
	v_mov_b32_e32 v4, v72
	v_mov_b32_e32 v5, v68
	v_pk_mul_f32 v[54:55], v[54:55], v[54:55]
	v_mov_b32_e32 v56, v75
	v_mov_b32_e32 v57, v71
	v_cvt_f32_f16_e32 v58, v52
	v_cvt_f32_f16_e32 v60, v53
	s_waitcnt vmcnt(60)
	v_cvt_f32_f16_sdwa v63, v50 dst_sel:DWORD dst_unused:UNUSED_PAD src0_sel:WORD_1
	v_pk_fma_f32 v[4:5], v[4:5], v[4:5], v[54:55]
	v_mov_b32_e32 v54, v74
	v_mov_b32_e32 v55, v70
	v_pk_mul_f32 v[56:57], v[56:57], v[56:57]
	v_cvt_f32_f16_e32 v62, v50
	v_cvt_f32_f16_sdwa v65, v51 dst_sel:DWORD dst_unused:UNUSED_PAD src0_sel:WORD_1
	v_pk_fma_f32 v[54:55], v[54:55], v[54:55], v[56:57]
	v_cvt_f32_f16_e32 v64, v51
	v_pk_add_f32 v[4:5], v[4:5], v[54:55]
	v_mov_b32_e32 v54, v59
	v_mov_b32_e32 v55, v61
	v_mov_b32_e32 v52, v58
	v_mov_b32_e32 v53, v60
	v_pk_mul_f32 v[54:55], v[54:55], v[54:55]
	v_mul_f32_e32 v50, v63, v63
	v_pk_fma_f32 v[52:53], v[52:53], v[52:53], v[54:55]
	v_pk_fma_f32 v[56:57], v[62:63], v[62:63], v[50:51] op_sel_hi:[1,1,0]
	v_mul_f32_e32 v50, v65, v65
	v_pk_add_f32 v[54:55], v[52:53], v[52:53] op_sel:[0,1] op_sel_hi:[1,0]
	v_pk_fma_f32 v[66:67], v[64:65], v[64:65], v[50:51] op_sel_hi:[1,1,0]
	s_waitcnt vmcnt(59)
	v_cvt_f32_f16_sdwa v51, v48 dst_sel:DWORD dst_unused:UNUSED_PAD src0_sel:WORD_1
	v_cvt_f32_f16_e32 v50, v48
	v_cvt_f32_f16_sdwa v53, v49 dst_sel:DWORD dst_unused:UNUSED_PAD src0_sel:WORD_1
	v_cvt_f32_f16_e32 v52, v49
	v_pk_add_f32 v[4:5], v[4:5], v[4:5] op_sel:[0,1] op_sel_hi:[1,0]
	v_pk_mul_f32 v[48:49], v[50:51], v[50:51]
	v_pk_mul_f32 v[76:77], v[52:53], v[52:53]
	v_mov_b32_e32 v5, v48
	v_mov_b32_e32 v55, v49
	v_mov_b32_e32 v57, v76
	v_mov_b32_e32 v67, v77
	v_pk_add_f32 v[4:5], v[4:5], v[54:55]
	v_pk_add_f32 v[48:49], v[56:57], v[66:67]
	s_waitcnt vmcnt(58)
	v_cvt_f32_f16_sdwa v55, v46 dst_sel:DWORD dst_unused:UNUSED_PAD src0_sel:WORD_1
	v_cvt_f32_f16_sdwa v57, v47 dst_sel:DWORD dst_unused:UNUSED_PAD src0_sel:WORD_1
	v_cvt_f32_f16_e32 v54, v46
	v_cvt_f32_f16_e32 v56, v47
	v_pk_add_f32 v[4:5], v[4:5], v[48:49]
	v_mov_b32_e32 v46, v55
	v_mov_b32_e32 v47, v57
	v_pk_add_f32 v[66:67], v[4:5], v[4:5] op_sel:[0,1] op_sel_hi:[1,0]
	v_mov_b32_e32 v4, v54
	v_mov_b32_e32 v5, v56
	v_pk_mul_f32 v[46:47], v[46:47], v[46:47]
	s_waitcnt vmcnt(56)
	v_cvt_f32_f16_sdwa v49, v43 dst_sel:DWORD dst_unused:UNUSED_PAD src0_sel:WORD_1
	v_pk_fma_f32 v[4:5], v[4:5], v[4:5], v[46:47]
	v_cvt_f32_f16_sdwa v47, v45 dst_sel:DWORD dst_unused:UNUSED_PAD src0_sel:WORD_1
	v_pk_add_f32 v[76:77], v[4:5], v[4:5] op_sel:[0,1] op_sel_hi:[1,0]
	v_cvt_f32_f16_sdwa v5, v44 dst_sel:DWORD dst_unused:UNUSED_PAD src0_sel:WORD_1
	v_cvt_f32_f16_e32 v4, v44
	v_cvt_f32_f16_e32 v46, v45
	v_cvt_f32_f16_e32 v48, v43
	v_mul_f32_e32 v44, v5, v5
	v_pk_fma_f32 v[78:79], v[4:5], v[4:5], v[44:45] op_sel_hi:[1,1,0]
	v_mul_f32_e32 v44, v47, v47
	v_pk_fma_f32 v[80:81], v[46:47], v[46:47], v[44:45] op_sel_hi:[1,1,0]
	v_cvt_f32_f16_sdwa v45, v42 dst_sel:DWORD dst_unused:UNUSED_PAD src0_sel:WORD_1
	v_cvt_f32_f16_e32 v44, v42
	v_pk_mul_f32 v[82:83], v[48:49], v[48:49]
	v_pk_mul_f32 v[42:43], v[44:45], v[44:45]
	s_nop 0
	v_mov_b32_e32 v67, v42
	v_mov_b32_e32 v77, v43
	v_mov_b32_e32 v79, v82
	v_mov_b32_e32 v81, v83
	v_pk_add_f32 v[42:43], v[66:67], v[76:77]
	v_pk_add_f32 v[66:67], v[78:79], v[80:81]
	s_nop 0
	v_pk_add_f32 v[42:43], v[42:43], v[66:67]
	s_nop 0
	v_add_f32_e32 v42, v42, v43
	s_nop 1
	v_add_f32_dpp v42, v42, v42 quad_perm:[1,0,3,2] row_mask:0xf bank_mask:0xf bound_ctrl:1
	s_nop 1
	v_add_f32_dpp v42, v42, v42 quad_perm:[2,3,0,1] row_mask:0xf bank_mask:0xf bound_ctrl:1
	s_nop 1
	v_add_f32_dpp v42, v42, v42 row_half_mirror row_mask:0xf bank_mask:0xf bound_ctrl:1
	s_nop 1
	v_add_f32_dpp v42, v42, v42 row_mirror row_mask:0xf bank_mask:0xf bound_ctrl:1
	s_nop 0
	v_readlane_b32 s8, v42, 16
	v_readlane_b32 s9, v42, 48
	v_readlane_b32 s6, v42, 0
	v_readlane_b32 s7, v42, 32
	v_mov_b32_e32 v42, s8
	v_mov_b32_e32 v43, s9
	v_pk_add_f32 v[42:43], s[6:7], v[42:43]
	s_nop 0
	v_add_f32_e32 v42, v42, v43
	v_fmamk_f32 v42, v42, 0x3a000000, v252
	v_cmp_gt_f32_e32 vcc, s55, v42
	v_mul_f32_e32 v43, 0x4f800000, v42
	s_nop 0
	v_cndmask_b32_e32 v42, v42, v43, vcc
	v_sqrt_f32_e32 v43, v42
	s_nop 0
	v_add_u32_e32 v66, -1, v43
	v_fma_f32 v67, -v66, v43, v42
	v_cmp_ge_f32_e64 s[8:9], 0, v67
	v_add_u32_e32 v67, 1, v43
	s_nop 0
	v_cndmask_b32_e64 v66, v43, v66, s[8:9]
	v_fma_f32 v43, -v67, v43, v42
	v_cmp_lt_f32_e64 s[8:9], 0, v43
	s_nop 1
	v_cndmask_b32_e64 v43, v66, v67, s[8:9]
	v_mul_f32_e32 v66, 0x37800000, v43
	v_cndmask_b32_e32 v43, v43, v66, vcc
	v_cmp_class_f32_e32 vcc, v42, v253
	s_nop 1
	v_cndmask_b32_e32 v42, v43, v42, vcc
	v_div_scale_f32 v43, s[6:7], v42, v42, 1.0
	v_rcp_f32_e32 v66, v43
	s_lshl_b32 s6, s22, 1
	s_and_b32 s6, s6, 0xffffe000
	s_add_i32 s6, s6, 0
	v_fma_f32 v67, -v43, v66, 1.0
	v_fmac_f32_e32 v66, v67, v66
	v_div_scale_f32 v67, vcc, 1.0, v42, 1.0
	v_mul_f32_e32 v76, v67, v66
	v_fma_f32 v77, -v43, v76, v67
	v_fmac_f32_e32 v76, v77, v66
	v_fma_f32 v43, -v43, v76, v67
	v_div_fmas_f32 v43, v43, v66, v76
	v_div_fixup_f32 v66, v43, v42, 1.0
	v_pk_mul_f32 v[80:81], v[72:73], v[66:67] op_sel_hi:[1,0]
	v_pk_mul_f32 v[82:83], v[74:75], v[66:67] op_sel_hi:[1,0]
	v_add_u32_e32 v67, s6, v0
	ds_read_b128 v[72:75], v67
	ds_read_b128 v[76:79], v67 offset:40960
	v_lshl_add_u64 v[42:43], s[24:25], 1, v[2:3]
	v_lshl_add_u64 v[42:43], v[42:43], 0, v[6:7]
	v_pk_mul_f32 v[4:5], v[4:5], v[66:67] op_sel_hi:[1,0]
	v_pk_mul_f32 v[46:47], v[46:47], v[66:67] op_sel_hi:[1,0]
	s_waitcnt lgkmcnt(0)
	v_pk_fma_f32 v[74:75], v[74:75], v[82:83], v[78:79]
	v_pk_fma_f32 v[72:73], v[72:73], v[80:81], v[76:77]
	v_pk_mul_f32 v[76:77], v[68:69], v[66:67] op_sel_hi:[1,0]
	v_cvt_pk_bf16_f32 v72, v72, v73
	v_cvt_pk_bf16_f32 v73, v74, v75
	global_store_dwordx2 v[42:43], v[72:73], off
	v_pk_mul_f32 v[78:79], v[70:71], v[66:67] op_sel_hi:[1,0]
	ds_read_b128 v[68:71], v67 offset:1024
	ds_read_b128 v[72:75], v67 offset:41984
	s_waitcnt lgkmcnt(0)
	v_pk_fma_f32 v[70:71], v[70:71], v[78:79], v[74:75]
	v_pk_fma_f32 v[68:69], v[68:69], v[76:77], v[72:73]
	v_pk_mul_f32 v[72:73], v[58:59], v[66:67] op_sel_hi:[1,0]
	v_cvt_pk_bf16_f32 v68, v68, v69
	v_cvt_pk_bf16_f32 v69, v70, v71
	global_store_dwordx2 v[42:43], v[68:69], off offset:512
	v_pk_mul_f32 v[74:75], v[60:61], v[66:67] op_sel_hi:[1,0]
	ds_read_b128 v[58:61], v67 offset:2048
	ds_read_b128 v[68:71], v67 offset:43008
	s_waitcnt lgkmcnt(0)
	v_pk_fma_f32 v[60:61], v[60:61], v[74:75], v[70:71]
	v_pk_fma_f32 v[58:59], v[58:59], v[72:73], v[68:69]
	v_pk_mul_f32 v[68:69], v[62:63], v[66:67] op_sel_hi:[1,0]
	v_cvt_pk_bf16_f32 v58, v58, v59
	v_cvt_pk_bf16_f32 v59, v60, v61
	global_store_dwordx2 v[42:43], v[58:59], off offset:1024
	v_pk_mul_f32 v[70:71], v[64:65], v[66:67] op_sel_hi:[1,0]
	ds_read_b128 v[58:61], v67 offset:3072
	ds_read_b128 v[62:65], v67 offset:44032
	s_waitcnt lgkmcnt(0)
	v_pk_fma_f32 v[60:61], v[70:71], v[60:61], v[64:65]
	v_pk_fma_f32 v[58:59], v[68:69], v[58:59], v[62:63]
	v_pk_mul_f32 v[62:63], v[50:51], v[66:67] op_sel_hi:[1,0]
	v_cvt_pk_bf16_f32 v58, v58, v59
	v_cvt_pk_bf16_f32 v59, v60, v61
	global_store_dwordx2 v[42:43], v[58:59], off offset:1536
	v_pk_mul_f32 v[64:65], v[52:53], v[66:67] op_sel_hi:[1,0]
	ds_read_b128 v[50:53], v67 offset:4096
	ds_read_b128 v[58:61], v67 offset:45056
	s_waitcnt lgkmcnt(0)
	v_pk_fma_f32 v[52:53], v[64:65], v[52:53], v[60:61]
	v_pk_fma_f32 v[50:51], v[62:63], v[50:51], v[58:59]
	v_pk_mul_f32 v[58:59], v[54:55], v[66:67] op_sel_hi:[1,0]
	v_cvt_pk_bf16_f32 v50, v50, v51
	v_cvt_pk_bf16_f32 v51, v52, v53
	global_store_dwordx2 v[42:43], v[50:51], off offset:2048
	v_pk_mul_f32 v[60:61], v[56:57], v[66:67] op_sel_hi:[1,0]
	ds_read_b128 v[50:53], v67 offset:5120
	ds_read_b128 v[54:57], v67 offset:46080
	s_waitcnt lgkmcnt(0)
	v_pk_fma_f32 v[52:53], v[60:61], v[52:53], v[56:57]
	v_pk_fma_f32 v[50:51], v[58:59], v[50:51], v[54:55]
	s_waitcnt vmcnt(60)
	v_cvt_f32_f16_sdwa v59, v41 dst_sel:DWORD dst_unused:UNUSED_PAD src0_sel:WORD_1
	v_cvt_pk_bf16_f32 v50, v50, v51
	v_cvt_pk_bf16_f32 v51, v52, v53
	global_store_dwordx2 v[42:43], v[50:51], off offset:2560
	ds_read_b128 v[50:53], v67 offset:6144
	ds_read_b128 v[54:57], v67 offset:47104
	v_cvt_f32_f16_e32 v58, v41
	s_waitcnt lgkmcnt(0)
	v_pk_fma_f32 v[46:47], v[46:47], v[52:53], v[56:57]
	v_pk_fma_f32 v[4:5], v[4:5], v[50:51], v[54:55]
	v_pk_mul_f32 v[52:53], v[48:49], v[66:67] op_sel_hi:[1,0]
	v_cvt_pk_bf16_f32 v4, v4, v5
	v_cvt_pk_bf16_f32 v5, v46, v47
	global_store_dwordx2 v[42:43], v[4:5], off offset:3072
	v_pk_mul_f32 v[4:5], v[44:45], v[66:67] op_sel_hi:[1,0]
	ds_read_b128 v[44:47], v67 offset:7168
	ds_read_b128 v[48:51], v67 offset:48128
	v_cvt_f32_f16_sdwa v57, v40 dst_sel:DWORD dst_unused:UNUSED_PAD src0_sel:WORD_1
	v_cvt_f32_f16_e32 v56, v40
	s_waitcnt vmcnt(61)
	v_cvt_f32_f16_sdwa v55, v39 dst_sel:DWORD dst_unused:UNUSED_PAD src0_sel:WORD_1
	v_cvt_f32_f16_e32 v54, v39
	s_waitcnt lgkmcnt(0)
	v_pk_fma_f32 v[46:47], v[52:53], v[46:47], v[50:51]
	v_cvt_f32_f16_sdwa v53, v38 dst_sel:DWORD dst_unused:UNUSED_PAD src0_sel:WORD_1
	v_cvt_f32_f16_e32 v52, v38
	v_pk_fma_f32 v[4:5], v[4:5], v[44:45], v[48:49]
	v_mov_b32_e32 v38, v57
	v_cvt_pk_bf16_f32 v4, v4, v5
	v_cvt_pk_bf16_f32 v5, v46, v47
	global_store_dwordx2 v[42:43], v[4:5], off offset:3584
	v_mov_b32_e32 v39, v53
	s_waitcnt vmcnt(61)
	v_cvt_f32_f16_sdwa v43, v36 dst_sel:DWORD dst_unused:UNUSED_PAD src0_sel:WORD_1
	v_cvt_f32_f16_sdwa v45, v37 dst_sel:DWORD dst_unused:UNUSED_PAD src0_sel:WORD_1
	v_mov_b32_e32 v4, v56
	v_mov_b32_e32 v5, v52
	v_pk_mul_f32 v[38:39], v[38:39], v[38:39]
	v_mov_b32_e32 v40, v59
	v_mov_b32_e32 v41, v55
	v_cvt_f32_f16_e32 v42, v36
	v_cvt_f32_f16_e32 v44, v37
	s_waitcnt vmcnt(60)
	v_cvt_f32_f16_sdwa v47, v34 dst_sel:DWORD dst_unused:UNUSED_PAD src0_sel:WORD_1
	v_pk_fma_f32 v[4:5], v[4:5], v[4:5], v[38:39]
	v_mov_b32_e32 v38, v58
	v_mov_b32_e32 v39, v54
	v_pk_mul_f32 v[40:41], v[40:41], v[40:41]
	v_cvt_f32_f16_e32 v46, v34
	v_cvt_f32_f16_sdwa v49, v35 dst_sel:DWORD dst_unused:UNUSED_PAD src0_sel:WORD_1
	v_pk_fma_f32 v[38:39], v[38:39], v[38:39], v[40:41]
	v_cvt_f32_f16_e32 v48, v35
	v_pk_add_f32 v[4:5], v[4:5], v[38:39]
	v_mov_b32_e32 v38, v43
	v_mov_b32_e32 v39, v45
	v_mov_b32_e32 v36, v42
	v_mov_b32_e32 v37, v44
	v_pk_mul_f32 v[38:39], v[38:39], v[38:39]
	v_mul_f32_e32 v34, v47, v47
	v_pk_fma_f32 v[36:37], v[36:37], v[36:37], v[38:39]
	v_pk_fma_f32 v[40:41], v[46:47], v[46:47], v[34:35] op_sel_hi:[1,1,0]
	v_mul_f32_e32 v34, v49, v49
	v_pk_add_f32 v[38:39], v[36:37], v[36:37] op_sel:[0,1] op_sel_hi:[1,0]
	v_pk_fma_f32 v[50:51], v[48:49], v[48:49], v[34:35] op_sel_hi:[1,1,0]
	s_waitcnt vmcnt(59)
	v_cvt_f32_f16_sdwa v35, v32 dst_sel:DWORD dst_unused:UNUSED_PAD src0_sel:WORD_1
	v_cvt_f32_f16_e32 v34, v32
	v_cvt_f32_f16_sdwa v37, v33 dst_sel:DWORD dst_unused:UNUSED_PAD src0_sel:WORD_1
	v_cvt_f32_f16_e32 v36, v33
	v_pk_add_f32 v[4:5], v[4:5], v[4:5] op_sel:[0,1] op_sel_hi:[1,0]
	v_pk_mul_f32 v[32:33], v[34:35], v[34:35]
	v_pk_mul_f32 v[60:61], v[36:37], v[36:37]
	v_mov_b32_e32 v5, v32
	v_mov_b32_e32 v39, v33
	v_mov_b32_e32 v41, v60
	v_mov_b32_e32 v51, v61
	v_pk_add_f32 v[4:5], v[4:5], v[38:39]
	v_pk_add_f32 v[32:33], v[40:41], v[50:51]
	s_waitcnt vmcnt(58)
	v_cvt_f32_f16_sdwa v39, v30 dst_sel:DWORD dst_unused:UNUSED_PAD src0_sel:WORD_1
	v_cvt_f32_f16_sdwa v41, v31 dst_sel:DWORD dst_unused:UNUSED_PAD src0_sel:WORD_1
	v_cvt_f32_f16_e32 v38, v30
	v_cvt_f32_f16_e32 v40, v31
	v_pk_add_f32 v[4:5], v[4:5], v[32:33]
	v_mov_b32_e32 v30, v39
	v_mov_b32_e32 v31, v41
	v_pk_add_f32 v[50:51], v[4:5], v[4:5] op_sel:[0,1] op_sel_hi:[1,0]
	v_mov_b32_e32 v4, v38
	v_mov_b32_e32 v5, v40
	v_pk_mul_f32 v[30:31], v[30:31], v[30:31]
	s_waitcnt vmcnt(56)
	v_cvt_f32_f16_sdwa v33, v27 dst_sel:DWORD dst_unused:UNUSED_PAD src0_sel:WORD_1
	v_pk_fma_f32 v[4:5], v[4:5], v[4:5], v[30:31]
	v_cvt_f32_f16_sdwa v31, v29 dst_sel:DWORD dst_unused:UNUSED_PAD src0_sel:WORD_1
	v_pk_add_f32 v[60:61], v[4:5], v[4:5] op_sel:[0,1] op_sel_hi:[1,0]
	v_cvt_f32_f16_sdwa v5, v28 dst_sel:DWORD dst_unused:UNUSED_PAD src0_sel:WORD_1
	v_cvt_f32_f16_e32 v4, v28
	v_cvt_f32_f16_e32 v30, v29
	v_cvt_f32_f16_e32 v32, v27
	v_mul_f32_e32 v28, v5, v5
	v_pk_fma_f32 v[62:63], v[4:5], v[4:5], v[28:29] op_sel_hi:[1,1,0]
	v_mul_f32_e32 v28, v31, v31
	v_pk_fma_f32 v[64:65], v[30:31], v[30:31], v[28:29] op_sel_hi:[1,1,0]
	v_cvt_f32_f16_sdwa v29, v26 dst_sel:DWORD dst_unused:UNUSED_PAD src0_sel:WORD_1
	v_cvt_f32_f16_e32 v28, v26
	v_pk_mul_f32 v[66:67], v[32:33], v[32:33]
	v_pk_mul_f32 v[26:27], v[28:29], v[28:29]
	s_nop 0
	v_mov_b32_e32 v51, v26
	v_mov_b32_e32 v61, v27
	v_mov_b32_e32 v63, v66
	v_mov_b32_e32 v65, v67
	v_pk_add_f32 v[26:27], v[50:51], v[60:61]
	v_pk_add_f32 v[50:51], v[62:63], v[64:65]
	s_nop 0
	v_pk_add_f32 v[26:27], v[26:27], v[50:51]
	s_nop 0
	v_add_f32_e32 v26, v26, v27
	s_nop 1
	v_add_f32_dpp v26, v26, v26 quad_perm:[1,0,3,2] row_mask:0xf bank_mask:0xf bound_ctrl:1
	s_nop 1
	v_add_f32_dpp v26, v26, v26 quad_perm:[2,3,0,1] row_mask:0xf bank_mask:0xf bound_ctrl:1
	s_nop 1
	v_add_f32_dpp v26, v26, v26 row_half_mirror row_mask:0xf bank_mask:0xf bound_ctrl:1
	s_nop 1
	v_add_f32_dpp v26, v26, v26 row_mirror row_mask:0xf bank_mask:0xf bound_ctrl:1
	s_nop 0
	v_readlane_b32 s8, v26, 16
	v_readlane_b32 s9, v26, 48
	v_readlane_b32 s6, v26, 0
	v_readlane_b32 s7, v26, 32
	v_mov_b32_e32 v26, s8
	v_mov_b32_e32 v27, s9
	v_pk_add_f32 v[26:27], s[6:7], v[26:27]
	s_nop 0
	v_add_f32_e32 v26, v26, v27
	v_fmamk_f32 v26, v26, 0x3a000000, v252
	v_cmp_gt_f32_e32 vcc, s55, v26
	v_mul_f32_e32 v27, 0x4f800000, v26
	s_nop 0
	v_cndmask_b32_e32 v26, v26, v27, vcc
	v_sqrt_f32_e32 v27, v26
	s_nop 0
	v_add_u32_e32 v50, -1, v27
	v_fma_f32 v51, -v50, v27, v26
	v_cmp_ge_f32_e64 s[8:9], 0, v51
	v_add_u32_e32 v51, 1, v27
	s_nop 0
	v_cndmask_b32_e64 v50, v27, v50, s[8:9]
	v_fma_f32 v27, -v51, v27, v26
	v_cmp_lt_f32_e64 s[8:9], 0, v27
	s_nop 1
	v_cndmask_b32_e64 v27, v50, v51, s[8:9]
	v_mul_f32_e32 v50, 0x37800000, v27
	v_cndmask_b32_e32 v27, v27, v50, vcc
	v_cmp_class_f32_e32 vcc, v26, v253
	s_nop 1
	v_cndmask_b32_e32 v26, v27, v26, vcc
	v_div_scale_f32 v27, s[6:7], v26, v26, 1.0
	v_rcp_f32_e32 v50, v27
	s_lshl_b32 s6, s18, 1
	s_and_b32 s6, s6, 0xffffe000
	s_add_i32 s6, s6, 0
	v_fma_f32 v51, -v27, v50, 1.0
	v_fmac_f32_e32 v50, v51, v50
	v_div_scale_f32 v51, vcc, 1.0, v26, 1.0
	v_mul_f32_e32 v60, v51, v50
	v_fma_f32 v61, -v27, v60, v51
	v_fmac_f32_e32 v60, v61, v50
	v_fma_f32 v27, -v27, v60, v51
	v_div_fmas_f32 v27, v27, v50, v60
	v_div_fixup_f32 v50, v27, v26, 1.0
	v_pk_mul_f32 v[64:65], v[56:57], v[50:51] op_sel_hi:[1,0]
	v_pk_mul_f32 v[66:67], v[58:59], v[50:51] op_sel_hi:[1,0]
	v_add_u32_e32 v51, s6, v0
	ds_read_b128 v[56:59], v51
	ds_read_b128 v[60:63], v51 offset:40960
	v_lshl_add_u64 v[26:27], s[20:21], 1, v[2:3]
	v_lshl_add_u64 v[26:27], v[26:27], 0, v[6:7]
	v_pk_mul_f32 v[4:5], v[4:5], v[50:51] op_sel_hi:[1,0]
	v_pk_mul_f32 v[30:31], v[30:31], v[50:51] op_sel_hi:[1,0]
	s_waitcnt lgkmcnt(0)
	v_pk_fma_f32 v[58:59], v[58:59], v[66:67], v[62:63]
	v_pk_fma_f32 v[56:57], v[56:57], v[64:65], v[60:61]
	v_pk_mul_f32 v[60:61], v[52:53], v[50:51] op_sel_hi:[1,0]
	v_cvt_pk_bf16_f32 v56, v56, v57
	v_cvt_pk_bf16_f32 v57, v58, v59
	global_store_dwordx2 v[26:27], v[56:57], off
	v_pk_mul_f32 v[62:63], v[54:55], v[50:51] op_sel_hi:[1,0]
	ds_read_b128 v[52:55], v51 offset:1024
	ds_read_b128 v[56:59], v51 offset:41984
	s_waitcnt lgkmcnt(0)
	v_pk_fma_f32 v[54:55], v[54:55], v[62:63], v[58:59]
	v_pk_fma_f32 v[52:53], v[52:53], v[60:61], v[56:57]
	v_pk_mul_f32 v[56:57], v[42:43], v[50:51] op_sel_hi:[1,0]
	v_cvt_pk_bf16_f32 v52, v52, v53
	v_cvt_pk_bf16_f32 v53, v54, v55
	global_store_dwordx2 v[26:27], v[52:53], off offset:512
	v_pk_mul_f32 v[58:59], v[44:45], v[50:51] op_sel_hi:[1,0]
	ds_read_b128 v[42:45], v51 offset:2048
	ds_read_b128 v[52:55], v51 offset:43008
	s_waitcnt lgkmcnt(0)
	v_pk_fma_f32 v[44:45], v[44:45], v[58:59], v[54:55]
	v_pk_fma_f32 v[42:43], v[42:43], v[56:57], v[52:53]
	v_pk_mul_f32 v[52:53], v[46:47], v[50:51] op_sel_hi:[1,0]
	v_cvt_pk_bf16_f32 v42, v42, v43
	v_cvt_pk_bf16_f32 v43, v44, v45
	global_store_dwordx2 v[26:27], v[42:43], off offset:1024
	v_pk_mul_f32 v[54:55], v[48:49], v[50:51] op_sel_hi:[1,0]
	ds_read_b128 v[42:45], v51 offset:3072
	ds_read_b128 v[46:49], v51 offset:44032
	s_waitcnt lgkmcnt(0)
	v_pk_fma_f32 v[44:45], v[54:55], v[44:45], v[48:49]
	v_pk_fma_f32 v[42:43], v[52:53], v[42:43], v[46:47]
	v_pk_mul_f32 v[46:47], v[34:35], v[50:51] op_sel_hi:[1,0]
	v_cvt_pk_bf16_f32 v42, v42, v43
	v_cvt_pk_bf16_f32 v43, v44, v45
	global_store_dwordx2 v[26:27], v[42:43], off offset:1536
	v_pk_mul_f32 v[48:49], v[36:37], v[50:51] op_sel_hi:[1,0]
	ds_read_b128 v[34:37], v51 offset:4096
	ds_read_b128 v[42:45], v51 offset:45056
	s_waitcnt lgkmcnt(0)
	v_pk_fma_f32 v[36:37], v[48:49], v[36:37], v[44:45]
	v_pk_fma_f32 v[34:35], v[46:47], v[34:35], v[42:43]
	v_pk_mul_f32 v[42:43], v[38:39], v[50:51] op_sel_hi:[1,0]
	v_cvt_pk_bf16_f32 v34, v34, v35
	v_cvt_pk_bf16_f32 v35, v36, v37
	global_store_dwordx2 v[26:27], v[34:35], off offset:2048
	v_pk_mul_f32 v[44:45], v[40:41], v[50:51] op_sel_hi:[1,0]
	ds_read_b128 v[34:37], v51 offset:5120
	ds_read_b128 v[38:41], v51 offset:46080
	s_waitcnt lgkmcnt(0)
	v_pk_fma_f32 v[36:37], v[44:45], v[36:37], v[40:41]
	v_pk_fma_f32 v[34:35], v[42:43], v[34:35], v[38:39]
	s_waitcnt vmcnt(60)
; __device__ __forceinline__ void norm_mod_phase2(const Args& a, Frame& F, const float* gain, const float* modl, int sh_off, int sc_off, int nrows, const float* slab_gate) {
;     ...
;     NR_FINISH(r0, nw,            (nw) >> 12);
;     NR_FINISH(r1, nw + 2048,     (nw + 2048) >> 12);
;     NR_FINISH(r2, nw + 2 * 2048, (nw + 2 * 2048) >> 12);
;     NR_FINISH(r3, nw + 3 * 2048, (nw + 3 * 2048) >> 12);
;     NR_FINISH(r4, nw + 4 * 2048, (nw + 4 * 2048) >> 12);
;     NR_FINISH(r5, nw + 5 * 2048, (nw + 5 * 2048) >> 12);
;     NR_FINISH(r6, nw + 6 * 2048, (nw + 6 * 2048) >> 12);
;     NR_FINISH(r7, nw + 7 * 2048, (nw + 7 * 2048) >> 12);
	v_cvt_f32_f16_sdwa v43, v25 dst_sel:DWORD dst_unused:UNUSED_PAD src0_sel:WORD_1
	v_cvt_pk_bf16_f32 v34, v34, v35
	v_cvt_pk_bf16_f32 v35, v36, v37
	global_store_dwordx2 v[26:27], v[34:35], off offset:2560
	ds_read_b128 v[34:37], v51 offset:6144
	ds_read_b128 v[38:41], v51 offset:47104
	v_cvt_f32_f16_e32 v42, v25
	s_waitcnt lgkmcnt(0)
	v_pk_fma_f32 v[30:31], v[30:31], v[36:37], v[40:41]
	v_pk_fma_f32 v[4:5], v[4:5], v[34:35], v[38:39]
	v_pk_mul_f32 v[36:37], v[32:33], v[50:51] op_sel_hi:[1,0]
	v_cvt_pk_bf16_f32 v4, v4, v5
	v_cvt_pk_bf16_f32 v5, v30, v31
	global_store_dwordx2 v[26:27], v[4:5], off offset:3072
	v_pk_mul_f32 v[4:5], v[28:29], v[50:51] op_sel_hi:[1,0]
	ds_read_b128 v[28:31], v51 offset:7168
	ds_read_b128 v[32:35], v51 offset:48128
	v_cvt_f32_f16_sdwa v41, v24 dst_sel:DWORD dst_unused:UNUSED_PAD src0_sel:WORD_1
	v_cvt_f32_f16_e32 v40, v24
	s_waitcnt vmcnt(61)
	v_cvt_f32_f16_sdwa v39, v23 dst_sel:DWORD dst_unused:UNUSED_PAD src0_sel:WORD_1
	v_cvt_f32_f16_e32 v38, v23
	s_waitcnt lgkmcnt(0)
	v_pk_fma_f32 v[30:31], v[36:37], v[30:31], v[34:35]
	v_cvt_f32_f16_sdwa v37, v22 dst_sel:DWORD dst_unused:UNUSED_PAD src0_sel:WORD_1
	v_cvt_f32_f16_e32 v36, v22
	v_pk_fma_f32 v[4:5], v[4:5], v[28:29], v[32:33]
	v_mov_b32_e32 v22, v41
	v_cvt_pk_bf16_f32 v4, v4, v5
	v_cvt_pk_bf16_f32 v5, v30, v31
	global_store_dwordx2 v[26:27], v[4:5], off offset:3584
	v_mov_b32_e32 v23, v37
	s_waitcnt vmcnt(61)
	v_cvt_f32_f16_sdwa v27, v20 dst_sel:DWORD dst_unused:UNUSED_PAD src0_sel:WORD_1
	v_cvt_f32_f16_sdwa v29, v21 dst_sel:DWORD dst_unused:UNUSED_PAD src0_sel:WORD_1
	v_mov_b32_e32 v4, v40
	v_mov_b32_e32 v5, v36
	v_pk_mul_f32 v[22:23], v[22:23], v[22:23]
	v_mov_b32_e32 v24, v43
	v_mov_b32_e32 v25, v39
	v_cvt_f32_f16_e32 v26, v20
	v_cvt_f32_f16_e32 v28, v21
	s_waitcnt vmcnt(60)
	v_cvt_f32_f16_sdwa v31, v18 dst_sel:DWORD dst_unused:UNUSED_PAD src0_sel:WORD_1
	v_pk_fma_f32 v[4:5], v[4:5], v[4:5], v[22:23]
	v_mov_b32_e32 v22, v42
	v_mov_b32_e32 v23, v38
	v_pk_mul_f32 v[24:25], v[24:25], v[24:25]
	v_cvt_f32_f16_e32 v30, v18
	v_cvt_f32_f16_sdwa v33, v19 dst_sel:DWORD dst_unused:UNUSED_PAD src0_sel:WORD_1
	v_pk_fma_f32 v[22:23], v[22:23], v[22:23], v[24:25]
	v_cvt_f32_f16_e32 v32, v19
	v_pk_add_f32 v[4:5], v[4:5], v[22:23]
	v_mov_b32_e32 v22, v27
	v_mov_b32_e32 v23, v29
	v_mov_b32_e32 v20, v26
	v_mov_b32_e32 v21, v28
	v_pk_mul_f32 v[22:23], v[22:23], v[22:23]
	v_mul_f32_e32 v18, v31, v31
	v_pk_fma_f32 v[20:21], v[20:21], v[20:21], v[22:23]
	v_pk_fma_f32 v[24:25], v[30:31], v[30:31], v[18:19] op_sel_hi:[1,1,0]
	v_mul_f32_e32 v18, v33, v33
	v_pk_add_f32 v[22:23], v[20:21], v[20:21] op_sel:[0,1] op_sel_hi:[1,0]
	v_pk_fma_f32 v[34:35], v[32:33], v[32:33], v[18:19] op_sel_hi:[1,1,0]
	s_waitcnt vmcnt(59)
	v_cvt_f32_f16_sdwa v19, v16 dst_sel:DWORD dst_unused:UNUSED_PAD src0_sel:WORD_1
	v_cvt_f32_f16_e32 v18, v16
	v_cvt_f32_f16_sdwa v21, v17 dst_sel:DWORD dst_unused:UNUSED_PAD src0_sel:WORD_1
	v_cvt_f32_f16_e32 v20, v17
	v_pk_add_f32 v[4:5], v[4:5], v[4:5] op_sel:[0,1] op_sel_hi:[1,0]
	v_pk_mul_f32 v[16:17], v[18:19], v[18:19]
	v_pk_mul_f32 v[44:45], v[20:21], v[20:21]
	v_mov_b32_e32 v5, v16
	v_mov_b32_e32 v23, v17
	v_mov_b32_e32 v25, v44
	v_mov_b32_e32 v35, v45
	v_pk_add_f32 v[4:5], v[4:5], v[22:23]
	v_pk_add_f32 v[16:17], v[24:25], v[34:35]
	s_waitcnt vmcnt(58)
	v_cvt_f32_f16_sdwa v23, v14 dst_sel:DWORD dst_unused:UNUSED_PAD src0_sel:WORD_1
	v_cvt_f32_f16_sdwa v25, v15 dst_sel:DWORD dst_unused:UNUSED_PAD src0_sel:WORD_1
	v_cvt_f32_f16_e32 v22, v14
	v_cvt_f32_f16_e32 v24, v15
	v_pk_add_f32 v[4:5], v[4:5], v[16:17]
	v_mov_b32_e32 v14, v23
	v_mov_b32_e32 v15, v25
	v_pk_add_f32 v[34:35], v[4:5], v[4:5] op_sel:[0,1] op_sel_hi:[1,0]
	v_mov_b32_e32 v4, v22
	v_mov_b32_e32 v5, v24
	v_pk_mul_f32 v[14:15], v[14:15], v[14:15]
	s_waitcnt vmcnt(56)
	v_cvt_f32_f16_sdwa v17, v11 dst_sel:DWORD dst_unused:UNUSED_PAD src0_sel:WORD_1
	v_pk_fma_f32 v[4:5], v[4:5], v[4:5], v[14:15]
	v_cvt_f32_f16_sdwa v15, v13 dst_sel:DWORD dst_unused:UNUSED_PAD src0_sel:WORD_1
	v_pk_add_f32 v[44:45], v[4:5], v[4:5] op_sel:[0,1] op_sel_hi:[1,0]
	v_cvt_f32_f16_sdwa v5, v12 dst_sel:DWORD dst_unused:UNUSED_PAD src0_sel:WORD_1
	v_cvt_f32_f16_e32 v4, v12
	v_cvt_f32_f16_e32 v14, v13
	v_cvt_f32_f16_e32 v16, v11
	v_mul_f32_e32 v12, v5, v5
	v_pk_fma_f32 v[46:47], v[4:5], v[4:5], v[12:13] op_sel_hi:[1,1,0]
	v_mul_f32_e32 v12, v15, v15
	v_pk_fma_f32 v[48:49], v[14:15], v[14:15], v[12:13] op_sel_hi:[1,1,0]
	v_cvt_f32_f16_sdwa v13, v10 dst_sel:DWORD dst_unused:UNUSED_PAD src0_sel:WORD_1
	v_cvt_f32_f16_e32 v12, v10
	v_pk_mul_f32 v[50:51], v[16:17], v[16:17]
	v_pk_mul_f32 v[10:11], v[12:13], v[12:13]
	s_nop 0
	v_mov_b32_e32 v35, v10
	v_mov_b32_e32 v45, v11
	v_mov_b32_e32 v47, v50
	v_mov_b32_e32 v49, v51
	v_pk_add_f32 v[10:11], v[34:35], v[44:45]
	v_pk_add_f32 v[34:35], v[46:47], v[48:49]
	s_nop 0
	v_pk_add_f32 v[10:11], v[10:11], v[34:35]
	s_nop 0
	v_add_f32_e32 v10, v10, v11
	s_nop 1
	v_add_f32_dpp v10, v10, v10 quad_perm:[1,0,3,2] row_mask:0xf bank_mask:0xf bound_ctrl:1
	s_nop 1
	v_add_f32_dpp v10, v10, v10 quad_perm:[2,3,0,1] row_mask:0xf bank_mask:0xf bound_ctrl:1
	s_nop 1
	v_add_f32_dpp v10, v10, v10 row_half_mirror row_mask:0xf bank_mask:0xf bound_ctrl:1
	s_nop 1
	v_add_f32_dpp v10, v10, v10 row_mirror row_mask:0xf bank_mask:0xf bound_ctrl:1
	s_nop 0
	v_readlane_b32 s8, v10, 16
	v_readlane_b32 s9, v10, 48
	v_readlane_b32 s6, v10, 0
	v_readlane_b32 s7, v10, 32
	v_mov_b32_e32 v10, s8
	v_mov_b32_e32 v11, s9
	v_pk_add_f32 v[10:11], s[6:7], v[10:11]
	s_nop 0
	v_add_f32_e32 v10, v10, v11
	v_fmamk_f32 v10, v10, 0x3a000000, v252
	v_cmp_gt_f32_e32 vcc, s55, v10
	v_mul_f32_e32 v11, 0x4f800000, v10
	s_nop 0
	v_cndmask_b32_e32 v10, v10, v11, vcc
	v_sqrt_f32_e32 v11, v10
	s_nop 0
	v_add_u32_e32 v34, -1, v11
	v_fma_f32 v35, -v34, v11, v10
	v_cmp_ge_f32_e64 s[8:9], 0, v35
	v_add_u32_e32 v35, 1, v11
	s_nop 0
	v_cndmask_b32_e64 v34, v11, v34, s[8:9]
	v_fma_f32 v11, -v35, v11, v10
	v_cmp_lt_f32_e64 s[8:9], 0, v11
	s_nop 1
	v_cndmask_b32_e64 v11, v34, v35, s[8:9]
	v_mul_f32_e32 v34, 0x37800000, v11
	v_cndmask_b32_e32 v11, v11, v34, vcc
	v_cmp_class_f32_e32 vcc, v10, v253
	s_add_i32 s8, s10, 0x4000
	s_nop 0
	v_cndmask_b32_e32 v10, v11, v10, vcc
	v_div_scale_f32 v11, s[6:7], v10, v10, 1.0
	v_rcp_f32_e32 v34, v11
	s_lshl_b32 s6, s14, 1
	s_and_b32 s6, s6, 0xffffe000
	s_add_i32 s6, s6, 0
	v_fma_f32 v35, -v11, v34, 1.0
	v_fmac_f32_e32 v34, v35, v34
	v_div_scale_f32 v35, vcc, 1.0, v10, 1.0
	v_mul_f32_e32 v44, v35, v34
	v_fma_f32 v45, -v11, v44, v35
	v_fmac_f32_e32 v44, v45, v34
	v_fma_f32 v11, -v11, v44, v35
	v_div_fmas_f32 v11, v11, v34, v44
	v_div_fixup_f32 v34, v11, v10, 1.0
	v_pk_mul_f32 v[48:49], v[40:41], v[34:35] op_sel_hi:[1,0]
	v_pk_mul_f32 v[50:51], v[42:43], v[34:35] op_sel_hi:[1,0]
	v_add_u32_e32 v35, s6, v0
	ds_read_b128 v[40:43], v35
	ds_read_b128 v[44:47], v35 offset:40960
	v_lshl_add_u64 v[10:11], s[16:17], 1, v[2:3]
	v_lshl_add_u64 v[10:11], v[10:11], 0, v[6:7]
	v_pk_mul_f32 v[4:5], v[4:5], v[34:35] op_sel_hi:[1,0]
	v_pk_mul_f32 v[14:15], v[14:15], v[34:35] op_sel_hi:[1,0]
	s_waitcnt lgkmcnt(0)
; #define GAS __attribute__((address_space(1)))
; __device__ __forceinline__ void norm_mod_phase2(const Args& a, Frame& F, const float* gain, const float* modl, int sh_off, int sc_off, int nrows, const float* slab_gate) {
;     ...
;     if (ML + nw < nrows) {
;         const int r = ML + nw, rc = nw;
;         const GAS v2u* xr = (const GAS v2u*)(X + (size_t)r * D) + F.lane;
; #pragma unroll
;         for (int j = 0; j < 8; ++j) r0[j] = xr[64 * j];
;         if (slab_gate != nullptr) { const GAS f32x4* sl = (const GAS f32x4*)((const float*)(a.ws + WS_SLAB) + (size_t)rc * D) + F.lane;
; #pragma unroll
;             for (int j = 0; j < 8; ++j) { const f32x4 p = (sl[64 * j] + sl[64 * j + (size_t)MC * D / 4]) + (sl[64 * j + 2 * ((size_t)MC * D / 4)] + sl[64 * j + 3 * ((size_t)MC * D / 4)]);
	v_pk_fma_f32 v[42:43], v[42:43], v[50:51], v[46:47]
	v_pk_fma_f32 v[40:41], v[40:41], v[48:49], v[44:45]
	v_pk_mul_f32 v[44:45], v[36:37], v[34:35] op_sel_hi:[1,0]
	v_cvt_pk_bf16_f32 v40, v40, v41
	v_cvt_pk_bf16_f32 v41, v42, v43
	global_store_dwordx2 v[10:11], v[40:41], off
	v_pk_mul_f32 v[46:47], v[38:39], v[34:35] op_sel_hi:[1,0]
	ds_read_b128 v[36:39], v35 offset:1024
	ds_read_b128 v[40:43], v35 offset:41984
	s_cmp_lt_i32 s8, s47
	s_waitcnt lgkmcnt(0)
	v_pk_fma_f32 v[38:39], v[38:39], v[46:47], v[42:43]
	v_pk_fma_f32 v[36:37], v[36:37], v[44:45], v[40:41]
	v_pk_mul_f32 v[40:41], v[26:27], v[34:35] op_sel_hi:[1,0]
	v_cvt_pk_bf16_f32 v36, v36, v37
	v_cvt_pk_bf16_f32 v37, v38, v39
	global_store_dwordx2 v[10:11], v[36:37], off offset:512
	v_pk_mul_f32 v[42:43], v[28:29], v[34:35] op_sel_hi:[1,0]
	ds_read_b128 v[26:29], v35 offset:2048
	ds_read_b128 v[36:39], v35 offset:43008
	s_waitcnt lgkmcnt(0)
	v_pk_fma_f32 v[28:29], v[28:29], v[42:43], v[38:39]
	v_pk_fma_f32 v[26:27], v[26:27], v[40:41], v[36:37]
	v_pk_mul_f32 v[36:37], v[30:31], v[34:35] op_sel_hi:[1,0]
	v_cvt_pk_bf16_f32 v26, v26, v27
	v_cvt_pk_bf16_f32 v27, v28, v29
	global_store_dwordx2 v[10:11], v[26:27], off offset:1024
	v_pk_mul_f32 v[38:39], v[32:33], v[34:35] op_sel_hi:[1,0]
	ds_read_b128 v[26:29], v35 offset:3072
	ds_read_b128 v[30:33], v35 offset:44032
	s_waitcnt lgkmcnt(0)
	v_pk_fma_f32 v[28:29], v[38:39], v[28:29], v[32:33]
	v_pk_fma_f32 v[26:27], v[36:37], v[26:27], v[30:31]
	v_pk_mul_f32 v[30:31], v[18:19], v[34:35] op_sel_hi:[1,0]
	v_cvt_pk_bf16_f32 v26, v26, v27
	v_cvt_pk_bf16_f32 v27, v28, v29
	global_store_dwordx2 v[10:11], v[26:27], off offset:1536
	v_pk_mul_f32 v[32:33], v[20:21], v[34:35] op_sel_hi:[1,0]
	ds_read_b128 v[18:21], v35 offset:4096
	ds_read_b128 v[26:29], v35 offset:45056
	s_waitcnt lgkmcnt(0)
	v_pk_fma_f32 v[20:21], v[32:33], v[20:21], v[28:29]
	v_pk_fma_f32 v[18:19], v[30:31], v[18:19], v[26:27]
	v_pk_mul_f32 v[26:27], v[22:23], v[34:35] op_sel_hi:[1,0]
	v_cvt_pk_bf16_f32 v18, v18, v19
	v_cvt_pk_bf16_f32 v19, v20, v21
	global_store_dwordx2 v[10:11], v[18:19], off offset:2048
	v_pk_mul_f32 v[28:29], v[24:25], v[34:35] op_sel_hi:[1,0]
	ds_read_b128 v[18:21], v35 offset:5120
	ds_read_b128 v[22:25], v35 offset:46080
	s_waitcnt lgkmcnt(0)
	v_pk_fma_f32 v[20:21], v[28:29], v[20:21], v[24:25]
	v_pk_fma_f32 v[18:19], v[26:27], v[18:19], v[22:23]
	s_nop 0
	v_cvt_pk_bf16_f32 v18, v18, v19
	v_cvt_pk_bf16_f32 v19, v20, v21
	global_store_dwordx2 v[10:11], v[18:19], off offset:2560
	ds_read_b128 v[18:21], v35 offset:6144
	ds_read_b128 v[22:25], v35 offset:47104
	s_waitcnt lgkmcnt(0)
	v_pk_fma_f32 v[14:15], v[14:15], v[20:21], v[24:25]
	v_pk_fma_f32 v[4:5], v[4:5], v[18:19], v[22:23]
	v_pk_mul_f32 v[20:21], v[16:17], v[34:35] op_sel_hi:[1,0]
	v_cvt_pk_bf16_f32 v4, v4, v5
	v_cvt_pk_bf16_f32 v5, v14, v15
	global_store_dwordx2 v[10:11], v[4:5], off offset:3072
	v_pk_mul_f32 v[4:5], v[12:13], v[34:35] op_sel_hi:[1,0]
	ds_read_b128 v[12:15], v35 offset:7168
	ds_read_b128 v[16:19], v35 offset:48128
	s_waitcnt lgkmcnt(0)
	v_pk_fma_f32 v[14:15], v[20:21], v[14:15], v[18:19]
	v_pk_fma_f32 v[4:5], v[4:5], v[12:13], v[16:17]
	s_nop 0
	v_cvt_pk_bf16_f32 v4, v4, v5
	v_cvt_pk_bf16_f32 v5, v14, v15
	global_store_dwordx2 v[10:11], v[4:5], off offset:3584
	s_cbranch_scc0 .LBB0_1050
	s_ashr_i32 s9, s8, 31
	s_lshl_b64 s[6:7], s[8:9], 12
	v_lshl_add_u64 v[4:5], v[8:9], 0, s[6:7]
	v_lshl_add_u64 v[18:19], v[4:5], 0, v[6:7]
	global_load_dwordx2 v[22:23], v[18:19], off
	global_load_dwordx2 v[20:21], v[18:19], off offset:512
	global_load_dwordx2 v[16:17], v[18:19], off offset:1024
	global_load_dwordx2 v[12:13], v[18:19], off offset:1536
	global_load_dwordx2 v[14:15], v[18:19], off offset:2048
	global_load_dwordx2 v[10:11], v[18:19], off offset:2560
	global_load_dwordx2 v[8:9], v[18:19], off offset:3072
	global_load_dwordx2 v[4:5], v[18:19], off offset:3584
	s_andn2_b64 vcc, exec, s[4:5]
	v_lshlrev_b32_e32 v46, 2, v147
	s_cbranch_vccnz .LBB0_1049
	v_mov_b32_e32 v24, s72
	v_mov_b32_e32 v25, s73
	v_lshl_add_u64 v[24:25], s[12:13], 2, v[24:25]
	v_lshl_add_u64 v[24:25], v[24:25], 0, v[0:1]
	v_lshlrev_b32_e32 v0, 2, v46
	v_lshl_add_u64 v[26:27], s[86:87], 0, v[0:1]
	v_add_co_u32_e32 v28, vcc, 0x58400000, v24
	s_nop 1
	v_addc_co_u32_e32 v29, vcc, 0, v25, vcc
	v_add_co_u32_e32 v30, vcc, 0x58c00000, v24
	s_nop 1
	v_addc_co_u32_e32 v31, vcc, 0, v25, vcc
	v_add_co_u32_e32 v32, vcc, 0x59400000, v24
	s_nop 1
	v_addc_co_u32_e32 v33, vcc, 0, v25, vcc
	v_add_co_u32_e32 v34, vcc, 0x59c00000, v24
	s_nop 1
	v_addc_co_u32_e32 v35, vcc, 0, v25, vcc
	v_add_co_u32_e32 v36, vcc, 0x58401000, v24
	s_nop 1
	v_addc_co_u32_e32 v37, vcc, 0, v25, vcc
	v_add_co_u32_e32 v38, vcc, 0x58c01000, v24
	s_nop 1
	v_addc_co_u32_e32 v39, vcc, 0, v25, vcc
	v_add_co_u32_e32 v42, vcc, 0x59401000, v24
	s_nop 1
	v_addc_co_u32_e32 v43, vcc, 0, v25, vcc
	v_add_co_u32_e32 v44, vcc, 0x59c01000, v24
	s_nop 1
	v_addc_co_u32_e32 v45, vcc, 0, v25, vcc
	v_add_co_u32_e32 v48, vcc, 0x34000, v26
	s_nop 1
	v_addc_co_u32_e32 v49, vcc, 0, v27, vcc
	v_add_co_u32_e32 v50, vcc, 0x35000, v26
	s_nop 1
	v_addc_co_u32_e32 v51, vcc, 0, v27, vcc
	global_load_dwordx4 v[94:97], v[28:29], off
	global_load_dwordx4 v[98:101], v[30:31], off
	global_load_dwordx4 v[102:105], v[32:33], off
	global_load_dwordx4 v[106:109], v[34:35], off
	global_load_dwordx4 v[110:113], v[48:49], off
	global_load_dwordx4 v[114:117], v[28:29], off offset:1024
	global_load_dwordx4 v[118:121], v[30:31], off offset:1024
	global_load_dwordx4 v[122:125], v[32:33], off offset:1024
	global_load_dwordx4 v[126:129], v[34:35], off offset:1024
	global_load_dwordx4 v[130:133], v[48:49], off offset:1024
	global_load_dwordx4 v[134:137], v[28:29], off offset:2048
	global_load_dwordx4 v[138:141], v[30:31], off offset:2048
	global_load_dwordx4 v[142:145], v[32:33], off offset:2048
	global_load_dwordx4 v[146:149], v[34:35], off offset:2048
	global_load_dwordx4 v[150:153], v[48:49], off offset:2048
	global_load_dwordx4 v[154:157], v[28:29], off offset:3072
	global_load_dwordx4 v[158:161], v[30:31], off offset:3072
	global_load_dwordx4 v[162:165], v[32:33], off offset:3072
	global_load_dwordx4 v[170:173], v[34:35], off offset:3072
	global_load_dwordx4 v[174:177], v[48:49], off offset:3072
	s_waitcnt vmcnt(15)
; #define GAS __attribute__((address_space(1)))
; __device__ __forceinline__ unsigned xpk2(float lo, float hi) { if (XRES_F16) { const f32x2_t v = {lo, hi}; const f16x2_t h = __builtin_convertvector(v, f16x2_t); return __builtin_bit_cast(unsigned, h); } return pk2(lo, hi); }
; __device__ __forceinline__ float xlo(unsigned w) { if (XRES_F16) { const f16x2_t h = __builtin_bit_cast(f16x2_t, w); return (float)h[0]; } return __builtin_bit_cast(float, w << 16); }
; __device__ __forceinline__ float xhi(unsigned w) { if (XRES_F16) { const f16x2_t h = __builtin_bit_cast(f16x2_t, w); return (float)h[1]; } return __builtin_bit_cast(float, w & 0xffff0000u); }
; __device__ __forceinline__ void norm_mod_phase2(const Args& a, Frame& F, const float* gain, const float* modl, int sh_off, int sc_off, int nrows, const float* slab_gate) {
;     ...
;         if (slab_gate != nullptr) { const GAS f32x4* sl = (const GAS f32x4*)((const float*)(a.ws + WS_SLAB) + (size_t)rc * D) + F.lane;
; #pragma unroll
;             for (int j = 0; j < 8; ++j) { const f32x4 p = (sl[64 * j] + sl[64 * j + (size_t)MC * D / 4]) + (sl[64 * j + 2 * ((size_t)MC * D / 4)] + sl[64 * j + 3 * ((size_t)MC * D / 4)]);
;                 const f32x4 x = (f32x4){xlo(r0[j].x), xhi(r0[j].x), xlo(r0[j].y), xhi(r0[j].y)} + *(const GAS f32x4*)(slab_gate + 256 * j + 4 * F.lane) * p;
;                 v2u w; w.x = xpk2(x[0], x[1]); w.y = xpk2(x[2], x[3]); ((GAS v2u*)(X + (size_t)r * D) + F.lane)[64 * j] = w; r0[j] = w; } }
	v_pk_add_f32 v[220:221], v[94:95], v[98:99]
	v_pk_add_f32 v[222:223], v[96:97], v[100:101]
	v_pk_add_f32 v[224:225], v[102:103], v[106:107]
	v_pk_add_f32 v[226:227], v[104:105], v[108:109]
	v_cvt_f32_f16_e32 v232, v22
	v_cvt_f32_f16_sdwa v233, v22 dst_sel:DWORD dst_unused:UNUSED_PAD src0_sel:WORD_1
	v_cvt_f32_f16_e32 v234, v23
	v_cvt_f32_f16_sdwa v235, v23 dst_sel:DWORD dst_unused:UNUSED_PAD src0_sel:WORD_1
	v_pk_add_f32 v[228:229], v[220:221], v[224:225]
	v_pk_add_f32 v[230:231], v[222:223], v[226:227]
	s_nop 1
	v_pk_fma_f32 v[236:237], v[110:111], v[228:229], v[232:233]
	v_pk_fma_f32 v[238:239], v[112:113], v[230:231], v[234:235]
	s_nop 1
	v_cvt_pk_f16_f32 v22, v236, v237
	v_cvt_pk_f16_f32 v23, v238, v239
	global_store_dwordx2 v[18:19], v[22:23], off
	global_load_dwordx4 v[94:97], v[36:37], off
	global_load_dwordx4 v[98:101], v[38:39], off
	global_load_dwordx4 v[102:105], v[42:43], off
	global_load_dwordx4 v[106:109], v[44:45], off
	global_load_dwordx4 v[110:113], v[50:51], off
	s_waitcnt vmcnt(16)
	v_pk_add_f32 v[220:221], v[114:115], v[118:119]
	v_pk_add_f32 v[222:223], v[116:117], v[120:121]
	v_pk_add_f32 v[224:225], v[122:123], v[126:127]
	v_pk_add_f32 v[226:227], v[124:125], v[128:129]
	v_cvt_f32_f16_e32 v232, v20
	v_cvt_f32_f16_sdwa v233, v20 dst_sel:DWORD dst_unused:UNUSED_PAD src0_sel:WORD_1
	v_cvt_f32_f16_e32 v234, v21
	v_cvt_f32_f16_sdwa v235, v21 dst_sel:DWORD dst_unused:UNUSED_PAD src0_sel:WORD_1
	v_pk_add_f32 v[228:229], v[220:221], v[224:225]
	v_pk_add_f32 v[230:231], v[222:223], v[226:227]
	s_nop 1
	v_pk_fma_f32 v[236:237], v[130:131], v[228:229], v[232:233]
	v_pk_fma_f32 v[238:239], v[132:133], v[230:231], v[234:235]
	s_nop 1
	v_cvt_pk_f16_f32 v20, v236, v237
	v_cvt_pk_f16_f32 v21, v238, v239
	global_store_dwordx2 v[18:19], v[20:21], off offset:512
	global_load_dwordx4 v[114:117], v[36:37], off offset:1024
	global_load_dwordx4 v[118:121], v[38:39], off offset:1024
	global_load_dwordx4 v[122:125], v[42:43], off offset:1024
	global_load_dwordx4 v[126:129], v[44:45], off offset:1024
	global_load_dwordx4 v[130:133], v[50:51], off offset:1024
	s_waitcnt vmcnt(17)
	v_pk_add_f32 v[220:221], v[134:135], v[138:139]
	v_pk_add_f32 v[222:223], v[136:137], v[140:141]
	v_pk_add_f32 v[224:225], v[142:143], v[146:147]
	v_pk_add_f32 v[226:227], v[144:145], v[148:149]
	v_cvt_f32_f16_e32 v232, v16
	v_cvt_f32_f16_sdwa v233, v16 dst_sel:DWORD dst_unused:UNUSED_PAD src0_sel:WORD_1
	v_cvt_f32_f16_e32 v234, v17
	v_cvt_f32_f16_sdwa v235, v17 dst_sel:DWORD dst_unused:UNUSED_PAD src0_sel:WORD_1
	v_pk_add_f32 v[228:229], v[220:221], v[224:225]
	v_pk_add_f32 v[230:231], v[222:223], v[226:227]
	s_nop 1
	v_pk_fma_f32 v[236:237], v[150:151], v[228:229], v[232:233]
	v_pk_fma_f32 v[238:239], v[152:153], v[230:231], v[234:235]
	s_nop 1
	v_cvt_pk_f16_f32 v16, v236, v237
	v_cvt_pk_f16_f32 v17, v238, v239
	global_store_dwordx2 v[18:19], v[16:17], off offset:1024
	global_load_dwordx4 v[134:137], v[36:37], off offset:2048
	global_load_dwordx4 v[138:141], v[38:39], off offset:2048
	global_load_dwordx4 v[142:145], v[42:43], off offset:2048
	global_load_dwordx4 v[146:149], v[44:45], off offset:2048
	global_load_dwordx4 v[150:153], v[50:51], off offset:2048
	s_waitcnt vmcnt(18)
; #define GAS __attribute__((address_space(1)))
; __device__ __forceinline__ unsigned xpk2(float lo, float hi) { if (XRES_F16) { const f32x2_t v = {lo, hi}; const f16x2_t h = __builtin_convertvector(v, f16x2_t); return __builtin_bit_cast(unsigned, h); } return pk2(lo, hi); }
; __device__ __forceinline__ float xlo(unsigned w) { if (XRES_F16) { const f16x2_t h = __builtin_bit_cast(f16x2_t, w); return (float)h[0]; } return __builtin_bit_cast(float, w << 16); }
; __device__ __forceinline__ float xhi(unsigned w) { if (XRES_F16) { const f16x2_t h = __builtin_bit_cast(f16x2_t, w); return (float)h[1]; } return __builtin_bit_cast(float, w & 0xffff0000u); }
; __device__ __forceinline__ void norm_mod_phase2(const Args& a, Frame& F, const float* gain, const float* modl, int sh_off, int sc_off, int nrows, const float* slab_gate) {
;     ...
;         if (slab_gate != nullptr) { const GAS f32x4* sl = (const GAS f32x4*)((const float*)(a.ws + WS_SLAB) + (size_t)rc * D) + F.lane;
; #pragma unroll
;             for (int j = 0; j < 8; ++j) { const f32x4 p = (sl[64 * j] + sl[64 * j + (size_t)MC * D / 4]) + (sl[64 * j + 2 * ((size_t)MC * D / 4)] + sl[64 * j + 3 * ((size_t)MC * D / 4)]);
;                 const f32x4 x = (f32x4){xlo(r0[j].x), xhi(r0[j].x), xlo(r0[j].y), xhi(r0[j].y)} + *(const GAS f32x4*)(slab_gate + 256 * j + 4 * F.lane) * p;
;                 v2u w; w.x = xpk2(x[0], x[1]); w.y = xpk2(x[2], x[3]); ((GAS v2u*)(X + (size_t)r * D) + F.lane)[64 * j] = w; r0[j] = w; } }
	v_pk_add_f32 v[220:221], v[154:155], v[158:159]
	v_pk_add_f32 v[222:223], v[156:157], v[160:161]
	v_pk_add_f32 v[224:225], v[162:163], v[170:171]
	v_pk_add_f32 v[226:227], v[164:165], v[172:173]
	v_cvt_f32_f16_e32 v232, v12
	v_cvt_f32_f16_sdwa v233, v12 dst_sel:DWORD dst_unused:UNUSED_PAD src0_sel:WORD_1
	v_cvt_f32_f16_e32 v234, v13
	v_cvt_f32_f16_sdwa v235, v13 dst_sel:DWORD dst_unused:UNUSED_PAD src0_sel:WORD_1
	v_pk_add_f32 v[228:229], v[220:221], v[224:225]
	v_pk_add_f32 v[230:231], v[222:223], v[226:227]
	s_nop 1
	v_pk_fma_f32 v[236:237], v[174:175], v[228:229], v[232:233]
	v_pk_fma_f32 v[238:239], v[176:177], v[230:231], v[234:235]
	s_nop 1
	v_cvt_pk_f16_f32 v12, v236, v237
	v_cvt_pk_f16_f32 v13, v238, v239
	global_store_dwordx2 v[18:19], v[12:13], off offset:1536
	global_load_dwordx4 v[154:157], v[36:37], off offset:3072
	global_load_dwordx4 v[158:161], v[38:39], off offset:3072
	global_load_dwordx4 v[162:165], v[42:43], off offset:3072
	global_load_dwordx4 v[170:173], v[44:45], off offset:3072
	global_load_dwordx4 v[174:177], v[50:51], off offset:3072
	s_waitcnt vmcnt(18)
	v_pk_add_f32 v[220:221], v[94:95], v[98:99]
	v_pk_add_f32 v[222:223], v[96:97], v[100:101]
	v_pk_add_f32 v[224:225], v[102:103], v[106:107]
	v_pk_add_f32 v[226:227], v[104:105], v[108:109]
	v_cvt_f32_f16_e32 v232, v14
	v_cvt_f32_f16_sdwa v233, v14 dst_sel:DWORD dst_unused:UNUSED_PAD src0_sel:WORD_1
	v_cvt_f32_f16_e32 v234, v15
	v_cvt_f32_f16_sdwa v235, v15 dst_sel:DWORD dst_unused:UNUSED_PAD src0_sel:WORD_1
	v_pk_add_f32 v[228:229], v[220:221], v[224:225]
	v_pk_add_f32 v[230:231], v[222:223], v[226:227]
	s_nop 1
	v_pk_fma_f32 v[236:237], v[110:111], v[228:229], v[232:233]
	v_pk_fma_f32 v[238:239], v[112:113], v[230:231], v[234:235]
	s_nop 1
	v_cvt_pk_f16_f32 v14, v236, v237
	v_cvt_pk_f16_f32 v15, v238, v239
	global_store_dwordx2 v[18:19], v[14:15], off offset:2048
	s_waitcnt vmcnt(13)
	v_pk_add_f32 v[220:221], v[114:115], v[118:119]
	v_pk_add_f32 v[222:223], v[116:117], v[120:121]
	v_pk_add_f32 v[224:225], v[122:123], v[126:127]
	v_pk_add_f32 v[226:227], v[124:125], v[128:129]
	v_cvt_f32_f16_e32 v232, v10
	v_cvt_f32_f16_sdwa v233, v10 dst_sel:DWORD dst_unused:UNUSED_PAD src0_sel:WORD_1
	v_cvt_f32_f16_e32 v234, v11
	v_cvt_f32_f16_sdwa v235, v11 dst_sel:DWORD dst_unused:UNUSED_PAD src0_sel:WORD_1
	v_pk_add_f32 v[228:229], v[220:221], v[224:225]
	v_pk_add_f32 v[230:231], v[222:223], v[226:227]
	s_nop 1
	v_pk_fma_f32 v[236:237], v[130:131], v[228:229], v[232:233]
	v_pk_fma_f32 v[238:239], v[132:133], v[230:231], v[234:235]
	s_nop 1
	v_cvt_pk_f16_f32 v10, v236, v237
	v_cvt_pk_f16_f32 v11, v238, v239
	global_store_dwordx2 v[18:19], v[10:11], off offset:2560
	s_waitcnt vmcnt(8)
	v_pk_add_f32 v[220:221], v[134:135], v[138:139]
	v_pk_add_f32 v[222:223], v[136:137], v[140:141]
	v_pk_add_f32 v[224:225], v[142:143], v[146:147]
	v_pk_add_f32 v[226:227], v[144:145], v[148:149]
	v_cvt_f32_f16_e32 v232, v8
	v_cvt_f32_f16_sdwa v233, v8 dst_sel:DWORD dst_unused:UNUSED_PAD src0_sel:WORD_1
	v_cvt_f32_f16_e32 v234, v9
	v_cvt_f32_f16_sdwa v235, v9 dst_sel:DWORD dst_unused:UNUSED_PAD src0_sel:WORD_1
	v_pk_add_f32 v[228:229], v[220:221], v[224:225]
	v_pk_add_f32 v[230:231], v[222:223], v[226:227]
	s_nop 1
	v_pk_fma_f32 v[236:237], v[150:151], v[228:229], v[232:233]
	v_pk_fma_f32 v[238:239], v[152:153], v[230:231], v[234:235]
	s_nop 1
	v_cvt_pk_f16_f32 v8, v236, v237
	v_cvt_pk_f16_f32 v9, v238, v239
	global_store_dwordx2 v[18:19], v[8:9], off offset:3072
	s_waitcnt vmcnt(3)
	v_pk_add_f32 v[220:221], v[154:155], v[158:159]
	v_pk_add_f32 v[222:223], v[156:157], v[160:161]
	v_pk_add_f32 v[224:225], v[162:163], v[170:171]
	v_pk_add_f32 v[226:227], v[164:165], v[172:173]
	v_cvt_f32_f16_e32 v232, v4
	v_cvt_f32_f16_sdwa v233, v4 dst_sel:DWORD dst_unused:UNUSED_PAD src0_sel:WORD_1
	v_cvt_f32_f16_e32 v234, v5
	v_cvt_f32_f16_sdwa v235, v5 dst_sel:DWORD dst_unused:UNUSED_PAD src0_sel:WORD_1
	v_pk_add_f32 v[228:229], v[220:221], v[224:225]
	v_pk_add_f32 v[230:231], v[222:223], v[226:227]
	s_nop 1
	v_pk_fma_f32 v[236:237], v[174:175], v[228:229], v[232:233]
	v_pk_fma_f32 v[238:239], v[176:177], v[230:231], v[234:235]
	s_nop 1
	v_cvt_pk_f16_f32 v4, v236, v237
	v_cvt_pk_f16_f32 v5, v238, v239
	global_store_dwordx2 v[18:19], v[4:5], off offset:3584
